# v45 + epilogue cross-row reductions via v_permlane16/32_swap instead of ds_bpermute (P2,P3,P6,P7,P8)
# speedup vs baseline: 1.0124x; 1.0021x over previous
; __global__ void __launch_bounds__(512, 2) mk_fwd(Args a) {
;     ...
;     const int tid = threadIdx.x, lane = tid & 63, wave = __builtin_amdgcn_readfirstlane(tid >> 6);
;     const int G = gridDim.x, bx = blockIdx.x;
;     const int vcu = (G % 8 == 0) ? (bx % 8) * (G / 8) + bx / 8 : bx;
_Z6mk_fwd4Args:
	s_load_dwordx8 s[68:75], s[0:1], 0x80
	s_add_u32 s40, s0, 0x98
	s_addc_u32 s41, s1, 0
	v_and_b32_e32 v196, 0x3ff, v0
	s_mov_b32 s67, s2
	s_waitcnt lgkmcnt(0)
	s_mov_b32 s98, 0xffff0000
	s_mov_b32 s99, 0xffff0000
	s_mov_b32 s100, 0
	s_mov_b32 s101, -1
	s_and_b32 s6, s74, 7
	s_cmp_eq_u32 s6, 0
	v_readfirstlane_b32 s10, v196
	s_cselect_b64 s[4:5], -1, 0
	s_cmp_lg_u32 s6, 0
	v_writelane_b32 v235, s2, 0
	s_cbranch_scc1 .LBB0_2
	v_readlane_b32 s2, v235, 0
	s_ashr_i32 s7, s2, 31
	s_lshr_b32 s7, s7, 29
	s_add_i32 s7, s2, s7
	s_and_b32 s8, s7, -8
	s_ashr_i32 s6, s74, 3
	s_sub_i32 s8, s2, s8
	s_mul_i32 s6, s6, s8
	s_ashr_i32 s7, s7, 3
	s_add_i32 s67, s6, s7

; __device__ __forceinline__ unsigned cvt_pk_bf16(float lo, float hi) { unsigned r; asm volatile("v_cvt_pk_bf16_f32 %0, %1, %2" : "=v"(r) : "v"(lo), "v"(hi)); return r; }
; __device__ __forceinline__ float bf_lo(unsigned w) { return __uint_as_float(w << 16); }
; __device__ __forceinline__ float bf_hi(unsigned w) { return __uint_as_float(w & 0xffff0000u); }
;     __device__ __forceinline__ void operator()(const f32x4 (&acc)[2][2][4][2], const Unit& u, int wr, int wc, int fr, int fq) const {
;     ...
;             for (int mm = 0; mm < RB; ++mm) { const size_t off = (size_t)(row0 + ai * HALF + (mh + mm) * 16) * D_MODEL + col0;
; #pragma unroll
;                 for (int bj = 0; bj < 2; ++bj) {
;                     if (BASE_F32) { bf[mm][bj][0] = *(const f32x4*)(basef + off + bj * HALF); bf[mm][bj][1] = *(const f32x4*)(basef + off + bj * HALF + 4); }
;                     else bb[mm][bj] = *(const u32x4*)(xb + off + bj * HALF);
;                 } }
;             asm volatile("" ::: "memory");
; #pragma unroll
;             for (int mm = 0; mm < RB; ++mm) {
;                 const int m = mh + mm;
;                 const int row = row0 + ai * HALF + m * 16; const size_t off = (size_t)row * D_MODEL + col0; float s = 0.f;
; #pragma unroll
;                 for (int bj = 0; bj < 2; ++bj) {
;                     f32x4 b0, b1;
;                     if (BASE_F32) { b0 = bf[mm][bj][0]; b1 = bf[mm][bj][1]; }
;                     else { const u32x4 w = bb[mm][bj]; b0 = (f32x4){bf_lo(w.x), bf_hi(w.x), bf_lo(w.y), bf_hi(w.y)}; b1 = (f32x4){bf_lo(w.z), bf_hi(w.z), bf_lo(w.w), bf_hi(w.w)}; }
;                     const f32x4 o0 = b0 + acc[ai][bj][m][0] * alpha, o1 = b1 + acc[ai][bj][m][1] * alpha;
;                     if (OUT_F32) { *(f32x4*)(out + off + bj * HALF) = o0; *(f32x4*)(out + off + bj * HALF + 4) = o1; }
;                     else { u32x4 w; w.x = cvt_pk_bf16(o0[0], o0[1]); w.y = cvt_pk_bf16(o0[2], o0[3]); w.z = cvt_pk_bf16(o1[0], o1[1]); w.w = cvt_pk_bf16(o1[2], o1[3]); *(u32x4*)(xb + off + bj * HALF) = w; }
;                     s += ((o0[0] * o0[0] + o0[1] * o0[1]) + (o0[2] * o0[2] + o0[3] * o0[3])) + ((o1[0] * o1[0] + o1[1] * o1[1]) + (o1[2] * o1[2] + o1[3] * o1[3]));
;                 }
;                 if (ssp) { s += __shfl_xor(s, 16); s += __shfl_xor(s, 32); if (fq == 0) ssp[(size_t)row * 16 + u.pn * 4 + wc] = s; }
.LBB0_260:
	v_lshl_or_b32 v166, s16, 8, v186
	v_lshl_add_u32 v168, s33, 8, v184
	v_ashrrev_i32_e32 v167, 31, v166
	v_readlane_b32 s2, v235, 38
	v_lshlrev_b64 v[202:203], 1, v[166:167]
	v_readlane_b32 s3, v235, 39
	v_ashrrev_i32_e32 v169, 31, v168
	v_or_b32_e32 v180, 16, v168
	v_or_b32_e32 v176, 32, v168
	v_lshl_add_u64 v[170:171], s[2:3], 0, v[202:203]
	v_lshlrev_b64 v[204:205], 11, v[168:169]
	v_or_b32_e32 v172, 48, v168
	v_ashrrev_i32_e32 v181, 31, v180
	v_ashrrev_i32_e32 v177, 31, v176
	v_lshl_add_u64 v[128:129], v[170:171], 0, v[204:205]
	v_ashrrev_i32_e32 v173, 31, v172
	v_lshlrev_b64 v[182:183], 11, v[180:181]
	v_lshlrev_b64 v[178:179], 11, v[176:177]
	global_load_dwordx4 v[192:195], v[128:129], off
	global_load_dwordx4 v[198:201], v[128:129], off offset:256
	v_lshlrev_b64 v[174:175], 11, v[172:173]
	v_lshl_add_u64 v[128:129], v[170:171], 0, v[182:183]
	v_lshl_add_u64 v[130:131], v[170:171], 0, v[178:179]
	v_lshl_add_u64 v[206:207], v[170:171], 0, v[174:175]
	global_load_dwordx4 v[148:151], v[128:129], off
	global_load_dwordx4 v[144:147], v[128:129], off offset:256
	global_load_dwordx4 v[140:143], v[130:131], off
	global_load_dwordx4 v[136:139], v[130:131], off offset:256
	global_load_dwordx4 v[132:135], v[206:207], off
	s_nop 0
	global_load_dwordx4 v[128:131], v[206:207], off offset:256
	v_readlane_b32 s30, v235, 42
	v_readlane_b32 s31, v235, 43
	v_lshl_add_u64 v[204:205], s[2:3], 0, v[204:205]
	s_lshl_b32 s26, s16, 2
	v_cndmask_b32_e64 v197, 0, 1, s[30:31]
	v_lshl_add_u64 v[202:203], v[204:205], 0, v[202:203]
	s_ashr_i32 s27, s26, 31
	v_cmp_ne_u32_e64 s[8:9], 1, v197
	s_andn2_b64 vcc, exec, s[30:31]
	s_waitcnt vmcnt(0)
	v_lshlrev_b32_e32 v204, 16, v192
	v_and_b32_e32 v205, 0xffff0000, v192
	v_lshlrev_b32_e32 v192, 16, v193
	v_and_b32_e32 v193, 0xffff0000, v193
	v_lshlrev_b32_e32 v206, 16, v194
	v_and_b32_e32 v207, 0xffff0000, v194
	v_lshlrev_b32_e32 v194, 16, v195
	v_and_b32_e32 v195, 0xffff0000, v195
	v_lshlrev_b32_e32 v208, 16, v198
	v_and_b32_e32 v209, 0xffff0000, v198
	v_lshlrev_b32_e32 v198, 16, v199
	v_and_b32_e32 v199, 0xffff0000, v199
	v_lshlrev_b32_e32 v210, 16, v200
	v_and_b32_e32 v211, 0xffff0000, v200
	v_lshlrev_b32_e32 v200, 16, v201
	v_and_b32_e32 v201, 0xffff0000, v201
	v_pk_fma_f32 v[126:127], v[126:127], 0.5, v[192:193] op_sel_hi:[1,0,1]
	v_pk_fma_f32 v[124:125], v[124:125], 0.5, v[204:205] op_sel_hi:[1,0,1]
	v_pk_fma_f32 v[122:123], v[122:123], 0.5, v[194:195] op_sel_hi:[1,0,1]
	v_pk_fma_f32 v[120:121], v[120:121], 0.5, v[206:207] op_sel_hi:[1,0,1]
	v_pk_fma_f32 v[118:119], v[118:119], 0.5, v[198:199] op_sel_hi:[1,0,1]
	v_pk_fma_f32 v[116:117], v[116:117], 0.5, v[208:209] op_sel_hi:[1,0,1]
	v_pk_fma_f32 v[114:115], v[114:115], 0.5, v[200:201] op_sel_hi:[1,0,1]
	v_pk_fma_f32 v[112:113], v[112:113], 0.5, v[210:211] op_sel_hi:[1,0,1]
	v_cvt_pk_bf16_f32 v192, v124, v125
	v_cvt_pk_bf16_f32 v193, v126, v127
	v_cvt_pk_bf16_f32 v194, v120, v121
	v_cvt_pk_bf16_f32 v195, v122, v123
	global_store_dwordx4 v[202:203], v[192:195], off
	s_nop 1
	v_cvt_pk_bf16_f32 v192, v116, v117
	v_cvt_pk_bf16_f32 v193, v118, v119
	v_cvt_pk_bf16_f32 v194, v112, v113
	v_cvt_pk_bf16_f32 v195, v114, v115
	global_store_dwordx4 v[202:203], v[192:195], off offset:256
	s_cbranch_vccnz .LBB0_264
	v_mul_f32_e32 v113, v113, v113
	v_mul_f32_e32 v125, v125, v125
	v_mul_f32_e32 v121, v121, v121
	v_mul_f32_e32 v117, v117, v117
	v_fmac_f32_e32 v113, v112, v112
	v_mul_f32_e32 v112, v115, v115
	v_fmac_f32_e32 v125, v124, v124
	v_mul_f32_e32 v124, v127, v127
	v_fmac_f32_e32 v121, v120, v120
	v_mul_f32_e32 v120, v123, v123
	v_fmac_f32_e32 v117, v116, v116
	v_mul_f32_e32 v116, v119, v119
	v_fmac_f32_e32 v112, v114, v114
	v_and_b32_e32 v114, 64, v191
	v_fmac_f32_e32 v124, v126, v126
	v_fmac_f32_e32 v120, v122, v122
	v_fmac_f32_e32 v116, v118, v118
	v_add_f32_e32 v112, v113, v112
	v_xor_b32_e32 v113, 16, v191
	v_add_u32_e32 v114, 64, v114
	v_add_f32_e32 v124, v125, v124
	v_add_f32_e32 v120, v121, v120
	v_add_f32_e32 v116, v117, v116
	v_cmp_lt_i32_e32 vcc, v113, v114
	v_add_f32_e32 v120, v124, v120
	v_add_f32_e32 v112, v116, v112
	v_cndmask_b32_e32 v113, v191, v113, vcc
	v_add_f32_e32 v112, v120, v112
	v_lshlrev_b32_e32 v113, 2, v113
	v_mov_b32_e32 v236, v112
	v_mov_b32_e32 v237, v112
	s_nop 1
	v_permlane16_swap_b32_e32 v236, v237
	v_cndmask_b32_e64 v113, v237, v236, s[98:99]
	s_waitcnt lgkmcnt(0)
	v_add_f32_e32 v112, v112, v113
	v_xor_b32_e32 v113, 32, v191
	v_cmp_lt_i32_e32 vcc, v113, v114
	s_nop 1
	v_cndmask_b32_e32 v113, v191, v113, vcc
	v_lshlrev_b32_e32 v113, 2, v113
	v_mov_b32_e32 v236, v112
	v_mov_b32_e32 v237, v112
	s_nop 1
	v_permlane32_swap_b32_e32 v236, v237
	v_cndmask_b32_e64 v113, v237, v236, s[100:101]
	s_and_saveexec_b64 s[2:3], s[4:5]
	s_cbranch_execz .LBB0_263
	v_readlane_b32 s30, v235, 50
	v_lshlrev_b64 v[114:115], 6, v[168:169]
	v_readlane_b32 s31, v235, 51
	s_lshl_b32 s16, s39, 2
	s_waitcnt lgkmcnt(0)
	v_add_f32_e32 v112, v112, v113
	v_lshl_add_u64 v[114:115], s[30:31], 0, v[114:115]
	v_lshl_add_u64 v[114:115], s[26:27], 2, v[114:115]
	v_lshl_add_u64 v[114:115], v[114:115], 0, s[16:17]
	global_store_dword v[114:115], v112, off

; __device__ __forceinline__ unsigned cvt_pk_bf16(float lo, float hi) { unsigned r; asm volatile("v_cvt_pk_bf16_f32 %0, %1, %2" : "=v"(r) : "v"(lo), "v"(hi)); return r; }
; __device__ __forceinline__ float bf_lo(unsigned w) { return __uint_as_float(w << 16); }
; __device__ __forceinline__ float bf_hi(unsigned w) { return __uint_as_float(w & 0xffff0000u); }
;     __device__ __forceinline__ void operator()(const f32x4 (&acc)[2][2][4][2], const Unit& u, int wr, int wc, int fr, int fq) const {
;     ...
;             for (int mm = 0; mm < RB; ++mm) {
;                 const int m = mh + mm;
;                 const int row = row0 + ai * HALF + m * 16; const size_t off = (size_t)row * D_MODEL + col0; float s = 0.f;
; #pragma unroll
;                 for (int bj = 0; bj < 2; ++bj) {
;                     f32x4 b0, b1;
;                     if (BASE_F32) { b0 = bf[mm][bj][0]; b1 = bf[mm][bj][1]; }
;                     else { const u32x4 w = bb[mm][bj]; b0 = (f32x4){bf_lo(w.x), bf_hi(w.x), bf_lo(w.y), bf_hi(w.y)}; b1 = (f32x4){bf_lo(w.z), bf_hi(w.z), bf_lo(w.w), bf_hi(w.w)}; }
;                     const f32x4 o0 = b0 + acc[ai][bj][m][0] * alpha, o1 = b1 + acc[ai][bj][m][1] * alpha;
;                     if (OUT_F32) { *(f32x4*)(out + off + bj * HALF) = o0; *(f32x4*)(out + off + bj * HALF + 4) = o1; }
;                     else { u32x4 w; w.x = cvt_pk_bf16(o0[0], o0[1]); w.y = cvt_pk_bf16(o0[2], o0[3]); w.z = cvt_pk_bf16(o1[0], o1[1]); w.w = cvt_pk_bf16(o1[2], o1[3]); *(u32x4*)(xb + off + bj * HALF) = w; }
;                     s += ((o0[0] * o0[0] + o0[1] * o0[1]) + (o0[2] * o0[2] + o0[3] * o0[3])) + ((o1[0] * o1[0] + o1[1] * o1[1]) + (o1[2] * o1[2] + o1[3] * o1[3]));
;                 }
;                 if (ssp) { s += __shfl_xor(s, 16); s += __shfl_xor(s, 32); if (fq == 0) ssp[(size_t)row * 16 + u.pn * 4 + wc] = s; }
.LBB0_264:
	v_readlane_b32 s2, v235, 38
	v_lshlrev_b32_e32 v116, 16, v150
	v_and_b32_e32 v117, 0xffff0000, v150
	v_readlane_b32 s3, v235, 39
	v_lshlrev_b32_e32 v112, 16, v148
	s_waitcnt lgkmcnt(0)
	v_and_b32_e32 v113, 0xffff0000, v148
	v_lshlrev_b32_e32 v114, 16, v149
	v_and_b32_e32 v115, 0xffff0000, v149
	v_lshlrev_b32_e32 v118, 16, v151
	v_and_b32_e32 v119, 0xffff0000, v151
	v_pk_fma_f32 v[104:105], v[104:105], 0.5, v[116:117] op_sel_hi:[1,0,1]
	v_lshl_add_u64 v[116:117], s[2:3], 0, v[182:183]
	v_pk_fma_f32 v[110:111], v[110:111], 0.5, v[114:115] op_sel_hi:[1,0,1]
	v_pk_fma_f32 v[108:109], v[108:109], 0.5, v[112:113] op_sel_hi:[1,0,1]
	v_pk_fma_f32 v[106:107], v[106:107], 0.5, v[118:119] op_sel_hi:[1,0,1]
	v_cvt_pk_bf16_f32 v112, v108, v109
	v_cvt_pk_bf16_f32 v113, v110, v111
	v_cvt_pk_bf16_f32 v114, v104, v105
	v_lshl_add_u64 v[116:117], v[166:167], 1, v[116:117]
	v_cvt_pk_bf16_f32 v115, v106, v107
	global_store_dwordx4 v[116:117], v[112:115], off
	v_lshlrev_b32_e32 v118, 16, v146
	v_and_b32_e32 v119, 0xffff0000, v146
	v_lshlrev_b32_e32 v112, 16, v144
	v_and_b32_e32 v113, 0xffff0000, v144
	v_lshlrev_b32_e32 v114, 16, v145
	v_and_b32_e32 v115, 0xffff0000, v145
	v_lshlrev_b32_e32 v120, 16, v147
	v_and_b32_e32 v121, 0xffff0000, v147
	v_pk_fma_f32 v[102:103], v[102:103], 0.5, v[114:115] op_sel_hi:[1,0,1]
	v_pk_fma_f32 v[100:101], v[100:101], 0.5, v[112:113] op_sel_hi:[1,0,1]
	v_pk_fma_f32 v[98:99], v[98:99], 0.5, v[120:121] op_sel_hi:[1,0,1]
	v_pk_fma_f32 v[96:97], v[96:97], 0.5, v[118:119] op_sel_hi:[1,0,1]
	s_and_b64 vcc, exec, s[8:9]
	v_cvt_pk_bf16_f32 v112, v100, v101
	v_cvt_pk_bf16_f32 v113, v102, v103
	v_cvt_pk_bf16_f32 v114, v96, v97
	v_cvt_pk_bf16_f32 v115, v98, v99
	global_store_dwordx4 v[116:117], v[112:115], off offset:256
	s_cbranch_vccnz .LBB0_268
	v_mul_f32_e32 v97, v97, v97
	v_mul_f32_e32 v109, v109, v109
	v_mul_f32_e32 v105, v105, v105
	v_mul_f32_e32 v101, v101, v101
	v_fmac_f32_e32 v97, v96, v96
	v_mul_f32_e32 v96, v99, v99
	v_fmac_f32_e32 v109, v108, v108
	v_mul_f32_e32 v108, v111, v111
	v_fmac_f32_e32 v105, v104, v104
	v_mul_f32_e32 v104, v107, v107
	v_fmac_f32_e32 v101, v100, v100
	v_mul_f32_e32 v100, v103, v103
	v_fmac_f32_e32 v96, v98, v98
	v_and_b32_e32 v98, 64, v191
	v_fmac_f32_e32 v108, v110, v110
	v_fmac_f32_e32 v104, v106, v106
	v_fmac_f32_e32 v100, v102, v102
	v_add_f32_e32 v96, v97, v96
	v_xor_b32_e32 v97, 16, v191
	v_add_u32_e32 v98, 64, v98
	v_add_f32_e32 v108, v109, v108
	v_add_f32_e32 v104, v105, v104
	v_add_f32_e32 v100, v101, v100
	v_cmp_lt_i32_e32 vcc, v97, v98
	v_add_f32_e32 v104, v108, v104
	v_add_f32_e32 v96, v100, v96
	v_cndmask_b32_e32 v97, v191, v97, vcc
	v_add_f32_e32 v96, v104, v96
	v_lshlrev_b32_e32 v97, 2, v97
	v_mov_b32_e32 v236, v96
	v_mov_b32_e32 v237, v96
	s_nop 1
	v_permlane16_swap_b32_e32 v236, v237
	v_cndmask_b32_e64 v97, v237, v236, s[98:99]
	s_waitcnt lgkmcnt(0)
	v_add_f32_e32 v96, v96, v97
	v_xor_b32_e32 v97, 32, v191
	v_cmp_lt_i32_e32 vcc, v97, v98
	s_nop 1
	v_cndmask_b32_e32 v97, v191, v97, vcc
	v_lshlrev_b32_e32 v97, 2, v97
	v_mov_b32_e32 v236, v96
	v_mov_b32_e32 v237, v96
	s_nop 1
	v_permlane32_swap_b32_e32 v236, v237
	v_cndmask_b32_e64 v97, v237, v236, s[100:101]
	s_and_saveexec_b64 s[2:3], s[4:5]
	s_cbranch_execz .LBB0_267
	v_readlane_b32 s30, v235, 50
	v_lshlrev_b64 v[98:99], 6, v[180:181]
	v_readlane_b32 s31, v235, 51
	s_lshl_b32 s16, s39, 2
	s_waitcnt lgkmcnt(0)
	v_add_f32_e32 v96, v96, v97
	v_lshl_add_u64 v[98:99], s[30:31], 0, v[98:99]
	v_lshl_add_u64 v[98:99], s[26:27], 2, v[98:99]
	v_lshl_add_u64 v[98:99], v[98:99], 0, s[16:17]
	global_store_dword v[98:99], v96, off

; __device__ __forceinline__ unsigned cvt_pk_bf16(float lo, float hi) { unsigned r; asm volatile("v_cvt_pk_bf16_f32 %0, %1, %2" : "=v"(r) : "v"(lo), "v"(hi)); return r; }
; __device__ __forceinline__ float bf_lo(unsigned w) { return __uint_as_float(w << 16); }
; __device__ __forceinline__ float bf_hi(unsigned w) { return __uint_as_float(w & 0xffff0000u); }
;     __device__ __forceinline__ void operator()(const f32x4 (&acc)[2][2][4][2], const Unit& u, int wr, int wc, int fr, int fq) const {
;     ...
;             for (int mm = 0; mm < RB; ++mm) {
;                 const int m = mh + mm;
;                 const int row = row0 + ai * HALF + m * 16; const size_t off = (size_t)row * D_MODEL + col0; float s = 0.f;
; #pragma unroll
;                 for (int bj = 0; bj < 2; ++bj) {
;                     f32x4 b0, b1;
;                     if (BASE_F32) { b0 = bf[mm][bj][0]; b1 = bf[mm][bj][1]; }
;                     else { const u32x4 w = bb[mm][bj]; b0 = (f32x4){bf_lo(w.x), bf_hi(w.x), bf_lo(w.y), bf_hi(w.y)}; b1 = (f32x4){bf_lo(w.z), bf_hi(w.z), bf_lo(w.w), bf_hi(w.w)}; }
;                     const f32x4 o0 = b0 + acc[ai][bj][m][0] * alpha, o1 = b1 + acc[ai][bj][m][1] * alpha;
;                     if (OUT_F32) { *(f32x4*)(out + off + bj * HALF) = o0; *(f32x4*)(out + off + bj * HALF + 4) = o1; }
;                     else { u32x4 w; w.x = cvt_pk_bf16(o0[0], o0[1]); w.y = cvt_pk_bf16(o0[2], o0[3]); w.z = cvt_pk_bf16(o1[0], o1[1]); w.w = cvt_pk_bf16(o1[2], o1[3]); *(u32x4*)(xb + off + bj * HALF) = w; }
;                     s += ((o0[0] * o0[0] + o0[1] * o0[1]) + (o0[2] * o0[2] + o0[3] * o0[3])) + ((o1[0] * o1[0] + o1[1] * o1[1]) + (o1[2] * o1[2] + o1[3] * o1[3]));
;                 }
;                 if (ssp) { s += __shfl_xor(s, 16); s += __shfl_xor(s, 32); if (fq == 0) ssp[(size_t)row * 16 + u.pn * 4 + wc] = s; }
.LBB0_268:
	v_readlane_b32 s2, v235, 38
	v_lshlrev_b32_e32 v100, 16, v142
	v_and_b32_e32 v101, 0xffff0000, v142
	v_readlane_b32 s3, v235, 39
	v_lshlrev_b32_e32 v96, 16, v140
	s_waitcnt lgkmcnt(0)
	v_and_b32_e32 v97, 0xffff0000, v140
	v_lshlrev_b32_e32 v98, 16, v141
	v_and_b32_e32 v99, 0xffff0000, v141
	v_lshlrev_b32_e32 v102, 16, v143
	v_and_b32_e32 v103, 0xffff0000, v143
	v_pk_fma_f32 v[88:89], v[88:89], 0.5, v[100:101] op_sel_hi:[1,0,1]
	v_lshl_add_u64 v[100:101], s[2:3], 0, v[178:179]
	v_pk_fma_f32 v[94:95], v[94:95], 0.5, v[98:99] op_sel_hi:[1,0,1]
	v_pk_fma_f32 v[92:93], v[92:93], 0.5, v[96:97] op_sel_hi:[1,0,1]
	v_pk_fma_f32 v[90:91], v[90:91], 0.5, v[102:103] op_sel_hi:[1,0,1]
	v_cvt_pk_bf16_f32 v96, v92, v93
	v_cvt_pk_bf16_f32 v97, v94, v95
	v_cvt_pk_bf16_f32 v98, v88, v89
	v_lshl_add_u64 v[100:101], v[166:167], 1, v[100:101]
	v_cvt_pk_bf16_f32 v99, v90, v91
	global_store_dwordx4 v[100:101], v[96:99], off
	v_lshlrev_b32_e32 v102, 16, v138
	v_and_b32_e32 v103, 0xffff0000, v138
	v_lshlrev_b32_e32 v96, 16, v136
	v_and_b32_e32 v97, 0xffff0000, v136
	v_lshlrev_b32_e32 v98, 16, v137
	v_and_b32_e32 v99, 0xffff0000, v137
	v_lshlrev_b32_e32 v104, 16, v139
	v_and_b32_e32 v105, 0xffff0000, v139
	v_pk_fma_f32 v[86:87], v[86:87], 0.5, v[98:99] op_sel_hi:[1,0,1]
	v_pk_fma_f32 v[84:85], v[84:85], 0.5, v[96:97] op_sel_hi:[1,0,1]
	v_pk_fma_f32 v[82:83], v[82:83], 0.5, v[104:105] op_sel_hi:[1,0,1]
	v_pk_fma_f32 v[80:81], v[80:81], 0.5, v[102:103] op_sel_hi:[1,0,1]
	s_and_b64 vcc, exec, s[8:9]
	v_cvt_pk_bf16_f32 v96, v84, v85
	v_cvt_pk_bf16_f32 v97, v86, v87
	v_cvt_pk_bf16_f32 v98, v80, v81
	v_cvt_pk_bf16_f32 v99, v82, v83
	global_store_dwordx4 v[100:101], v[96:99], off offset:256
	s_cbranch_vccnz .LBB0_272
	v_mul_f32_e32 v81, v81, v81
	v_mul_f32_e32 v93, v93, v93
	v_mul_f32_e32 v89, v89, v89
	v_mul_f32_e32 v85, v85, v85
	v_fmac_f32_e32 v81, v80, v80
	v_mul_f32_e32 v80, v83, v83
	v_fmac_f32_e32 v93, v92, v92
	v_mul_f32_e32 v92, v95, v95
	v_fmac_f32_e32 v89, v88, v88
	v_mul_f32_e32 v88, v91, v91
	v_fmac_f32_e32 v85, v84, v84
	v_mul_f32_e32 v84, v87, v87
	v_fmac_f32_e32 v80, v82, v82
	v_and_b32_e32 v82, 64, v191
	v_fmac_f32_e32 v92, v94, v94
	v_fmac_f32_e32 v88, v90, v90
	v_fmac_f32_e32 v84, v86, v86
	v_add_f32_e32 v80, v81, v80
	v_xor_b32_e32 v81, 16, v191
	v_add_u32_e32 v82, 64, v82
	v_add_f32_e32 v92, v93, v92
	v_add_f32_e32 v88, v89, v88
	v_add_f32_e32 v84, v85, v84
	v_cmp_lt_i32_e32 vcc, v81, v82
	v_add_f32_e32 v88, v92, v88
	v_add_f32_e32 v80, v84, v80
	v_cndmask_b32_e32 v81, v191, v81, vcc
	v_add_f32_e32 v80, v88, v80
	v_lshlrev_b32_e32 v81, 2, v81
	v_mov_b32_e32 v236, v80
	v_mov_b32_e32 v237, v80
	s_nop 1
	v_permlane16_swap_b32_e32 v236, v237
	v_cndmask_b32_e64 v81, v237, v236, s[98:99]
	s_waitcnt lgkmcnt(0)
	v_add_f32_e32 v80, v80, v81
	v_xor_b32_e32 v81, 32, v191
	v_cmp_lt_i32_e32 vcc, v81, v82
	s_nop 1
	v_cndmask_b32_e32 v81, v191, v81, vcc
	v_lshlrev_b32_e32 v81, 2, v81
	v_mov_b32_e32 v236, v80
	v_mov_b32_e32 v237, v80
	s_nop 1
	v_permlane32_swap_b32_e32 v236, v237
	v_cndmask_b32_e64 v81, v237, v236, s[100:101]
	s_and_saveexec_b64 s[2:3], s[4:5]
	s_cbranch_execz .LBB0_271
	v_readlane_b32 s30, v235, 50
	v_lshlrev_b64 v[82:83], 6, v[176:177]
	v_readlane_b32 s31, v235, 51
	s_lshl_b32 s16, s39, 2
	s_waitcnt lgkmcnt(0)
	v_add_f32_e32 v80, v80, v81
	v_lshl_add_u64 v[82:83], s[30:31], 0, v[82:83]
	v_lshl_add_u64 v[82:83], s[26:27], 2, v[82:83]
	v_lshl_add_u64 v[82:83], v[82:83], 0, s[16:17]
	global_store_dword v[82:83], v80, off

; __device__ __forceinline__ unsigned cvt_pk_bf16(float lo, float hi) { unsigned r; asm volatile("v_cvt_pk_bf16_f32 %0, %1, %2" : "=v"(r) : "v"(lo), "v"(hi)); return r; }
; __device__ __forceinline__ float bf_lo(unsigned w) { return __uint_as_float(w << 16); }
; __device__ __forceinline__ float bf_hi(unsigned w) { return __uint_as_float(w & 0xffff0000u); }
;     __device__ __forceinline__ void operator()(const f32x4 (&acc)[2][2][4][2], const Unit& u, int wr, int wc, int fr, int fq) const {
;     ...
;             for (int mm = 0; mm < RB; ++mm) {
;                 const int m = mh + mm;
;                 const int row = row0 + ai * HALF + m * 16; const size_t off = (size_t)row * D_MODEL + col0; float s = 0.f;
; #pragma unroll
;                 for (int bj = 0; bj < 2; ++bj) {
;                     f32x4 b0, b1;
;                     if (BASE_F32) { b0 = bf[mm][bj][0]; b1 = bf[mm][bj][1]; }
;                     else { const u32x4 w = bb[mm][bj]; b0 = (f32x4){bf_lo(w.x), bf_hi(w.x), bf_lo(w.y), bf_hi(w.y)}; b1 = (f32x4){bf_lo(w.z), bf_hi(w.z), bf_lo(w.w), bf_hi(w.w)}; }
;                     const f32x4 o0 = b0 + acc[ai][bj][m][0] * alpha, o1 = b1 + acc[ai][bj][m][1] * alpha;
;                     if (OUT_F32) { *(f32x4*)(out + off + bj * HALF) = o0; *(f32x4*)(out + off + bj * HALF + 4) = o1; }
;                     else { u32x4 w; w.x = cvt_pk_bf16(o0[0], o0[1]); w.y = cvt_pk_bf16(o0[2], o0[3]); w.z = cvt_pk_bf16(o1[0], o1[1]); w.w = cvt_pk_bf16(o1[2], o1[3]); *(u32x4*)(xb + off + bj * HALF) = w; }
;                     s += ((o0[0] * o0[0] + o0[1] * o0[1]) + (o0[2] * o0[2] + o0[3] * o0[3])) + ((o1[0] * o1[0] + o1[1] * o1[1]) + (o1[2] * o1[2] + o1[3] * o1[3]));
;                 }
;                 if (ssp) { s += __shfl_xor(s, 16); s += __shfl_xor(s, 32); if (fq == 0) ssp[(size_t)row * 16 + u.pn * 4 + wc] = s; }
.LBB0_272:
	v_readlane_b32 s2, v235, 38
	v_lshlrev_b32_e32 v84, 16, v134
	v_and_b32_e32 v85, 0xffff0000, v134
	v_readlane_b32 s3, v235, 39
	v_lshlrev_b32_e32 v80, 16, v132
	s_waitcnt lgkmcnt(0)
	v_and_b32_e32 v81, 0xffff0000, v132
	v_lshlrev_b32_e32 v82, 16, v133
	v_and_b32_e32 v83, 0xffff0000, v133
	v_lshlrev_b32_e32 v86, 16, v135
	v_and_b32_e32 v87, 0xffff0000, v135
	v_pk_fma_f32 v[72:73], v[72:73], 0.5, v[84:85] op_sel_hi:[1,0,1]
	v_lshl_add_u64 v[84:85], s[2:3], 0, v[174:175]
	v_pk_fma_f32 v[78:79], v[78:79], 0.5, v[82:83] op_sel_hi:[1,0,1]
	v_pk_fma_f32 v[76:77], v[76:77], 0.5, v[80:81] op_sel_hi:[1,0,1]
	v_pk_fma_f32 v[74:75], v[74:75], 0.5, v[86:87] op_sel_hi:[1,0,1]
	v_cvt_pk_bf16_f32 v80, v76, v77
	v_cvt_pk_bf16_f32 v81, v78, v79
	v_cvt_pk_bf16_f32 v82, v72, v73
	v_lshl_add_u64 v[84:85], v[166:167], 1, v[84:85]
	v_cvt_pk_bf16_f32 v83, v74, v75
	global_store_dwordx4 v[84:85], v[80:83], off
	v_lshlrev_b32_e32 v86, 16, v130
	v_and_b32_e32 v87, 0xffff0000, v130
	v_lshlrev_b32_e32 v80, 16, v128
	v_and_b32_e32 v81, 0xffff0000, v128
	v_lshlrev_b32_e32 v82, 16, v129
	v_and_b32_e32 v83, 0xffff0000, v129
	v_lshlrev_b32_e32 v88, 16, v131
	v_and_b32_e32 v89, 0xffff0000, v131
	v_pk_fma_f32 v[70:71], v[70:71], 0.5, v[82:83] op_sel_hi:[1,0,1]
	v_pk_fma_f32 v[68:69], v[68:69], 0.5, v[80:81] op_sel_hi:[1,0,1]
	v_pk_fma_f32 v[66:67], v[66:67], 0.5, v[88:89] op_sel_hi:[1,0,1]
	v_pk_fma_f32 v[64:65], v[64:65], 0.5, v[86:87] op_sel_hi:[1,0,1]
	s_and_b64 vcc, exec, s[8:9]
	v_cvt_pk_bf16_f32 v80, v68, v69
	v_cvt_pk_bf16_f32 v81, v70, v71
	v_cvt_pk_bf16_f32 v82, v64, v65
	v_cvt_pk_bf16_f32 v83, v66, v67
	global_store_dwordx4 v[84:85], v[80:83], off offset:256
	s_cbranch_vccnz .LBB0_276
	v_mul_f32_e32 v65, v65, v65
	v_mul_f32_e32 v77, v77, v77
	v_mul_f32_e32 v73, v73, v73
	v_mul_f32_e32 v69, v69, v69
	v_fmac_f32_e32 v65, v64, v64
	v_mul_f32_e32 v64, v67, v67
	v_fmac_f32_e32 v77, v76, v76
	v_mul_f32_e32 v76, v79, v79
	v_fmac_f32_e32 v73, v72, v72
	v_mul_f32_e32 v72, v75, v75
	v_fmac_f32_e32 v69, v68, v68
	v_mul_f32_e32 v68, v71, v71
	v_fmac_f32_e32 v64, v66, v66
	v_and_b32_e32 v66, 64, v191
	v_fmac_f32_e32 v76, v78, v78
	v_fmac_f32_e32 v72, v74, v74
	v_fmac_f32_e32 v68, v70, v70
	v_add_f32_e32 v64, v65, v64
	v_xor_b32_e32 v65, 16, v191
	v_add_u32_e32 v66, 64, v66
	v_add_f32_e32 v76, v77, v76
	v_add_f32_e32 v72, v73, v72
	v_add_f32_e32 v68, v69, v68
	v_cmp_lt_i32_e32 vcc, v65, v66
	v_add_f32_e32 v72, v76, v72
	v_add_f32_e32 v64, v68, v64
	v_cndmask_b32_e32 v65, v191, v65, vcc
	v_add_f32_e32 v64, v72, v64
	v_lshlrev_b32_e32 v65, 2, v65
	v_mov_b32_e32 v236, v64
	v_mov_b32_e32 v237, v64
	s_nop 1
	v_permlane16_swap_b32_e32 v236, v237
	v_cndmask_b32_e64 v65, v237, v236, s[98:99]
	s_waitcnt lgkmcnt(0)
	v_add_f32_e32 v64, v64, v65
	v_xor_b32_e32 v65, 32, v191
	v_cmp_lt_i32_e32 vcc, v65, v66
	s_nop 1
	v_cndmask_b32_e32 v65, v191, v65, vcc
	v_lshlrev_b32_e32 v65, 2, v65
	v_mov_b32_e32 v236, v64
	v_mov_b32_e32 v237, v64
	s_nop 1
	v_permlane32_swap_b32_e32 v236, v237
	v_cndmask_b32_e64 v65, v237, v236, s[100:101]
	s_and_saveexec_b64 s[2:3], s[4:5]
	s_cbranch_execz .LBB0_275
	v_readlane_b32 s30, v235, 50
	v_lshlrev_b64 v[66:67], 6, v[172:173]
	v_readlane_b32 s31, v235, 51
	s_lshl_b32 s16, s39, 2
	s_waitcnt lgkmcnt(0)
	v_add_f32_e32 v64, v64, v65
	v_lshl_add_u64 v[66:67], s[30:31], 0, v[66:67]
	v_lshl_add_u64 v[66:67], s[26:27], 2, v[66:67]
	v_lshl_add_u64 v[66:67], v[66:67], 0, s[16:17]
	global_store_dword v[66:67], v64, off

; __device__ __forceinline__ unsigned cvt_pk_bf16(float lo, float hi) { unsigned r; asm volatile("v_cvt_pk_bf16_f32 %0, %1, %2" : "=v"(r) : "v"(lo), "v"(hi)); return r; }
; __device__ __forceinline__ float bf_lo(unsigned w) { return __uint_as_float(w << 16); }
; __device__ __forceinline__ float bf_hi(unsigned w) { return __uint_as_float(w & 0xffff0000u); }
;     __device__ __forceinline__ void operator()(const f32x4 (&acc)[2][2][4][2], const Unit& u, int wr, int wc, int fr, int fq) const {
;     ...
;             for (int mm = 0; mm < RB; ++mm) { const size_t off = (size_t)(row0 + ai * HALF + (mh + mm) * 16) * D_MODEL + col0;
; #pragma unroll
;                 for (int bj = 0; bj < 2; ++bj) {
;                     if (BASE_F32) { bf[mm][bj][0] = *(const f32x4*)(basef + off + bj * HALF); bf[mm][bj][1] = *(const f32x4*)(basef + off + bj * HALF + 4); }
;                     else bb[mm][bj] = *(const u32x4*)(xb + off + bj * HALF);
;                 } }
;             asm volatile("" ::: "memory");
; #pragma unroll
;             for (int mm = 0; mm < RB; ++mm) {
;                 const int m = mh + mm;
;                 const int row = row0 + ai * HALF + m * 16; const size_t off = (size_t)row * D_MODEL + col0; float s = 0.f;
; #pragma unroll
;                 for (int bj = 0; bj < 2; ++bj) {
;                     f32x4 b0, b1;
;                     if (BASE_F32) { b0 = bf[mm][bj][0]; b1 = bf[mm][bj][1]; }
;                     else { const u32x4 w = bb[mm][bj]; b0 = (f32x4){bf_lo(w.x), bf_hi(w.x), bf_lo(w.y), bf_hi(w.y)}; b1 = (f32x4){bf_lo(w.z), bf_hi(w.z), bf_lo(w.w), bf_hi(w.w)}; }
;                     const f32x4 o0 = b0 + acc[ai][bj][m][0] * alpha, o1 = b1 + acc[ai][bj][m][1] * alpha;
;                     if (OUT_F32) { *(f32x4*)(out + off + bj * HALF) = o0; *(f32x4*)(out + off + bj * HALF + 4) = o1; }
;                     else { u32x4 w; w.x = cvt_pk_bf16(o0[0], o0[1]); w.y = cvt_pk_bf16(o0[2], o0[3]); w.z = cvt_pk_bf16(o1[0], o1[1]); w.w = cvt_pk_bf16(o1[2], o1[3]); *(u32x4*)(xb + off + bj * HALF) = w; }
;                     s += ((o0[0] * o0[0] + o0[1] * o0[1]) + (o0[2] * o0[2] + o0[3] * o0[3])) + ((o1[0] * o1[0] + o1[1] * o1[1]) + (o1[2] * o1[2] + o1[3] * o1[3]));
;                 }
;                 if (ssp) { s += __shfl_xor(s, 16); s += __shfl_xor(s, 32); if (fq == 0) ssp[(size_t)row * 16 + u.pn * 4 + wc] = s; }
.LBB0_276:
	v_add_u32_e32 v100, 0x80, v168
	v_ashrrev_i32_e32 v101, 31, v100
	v_add_u32_e32 v96, 0x90, v168
	v_add_u32_e32 v92, 0xa0, v168
	v_lshlrev_b64 v[110:111], 11, v[100:101]
	v_add_u32_e32 v88, 0xb0, v168
	v_ashrrev_i32_e32 v97, 31, v96
	v_ashrrev_i32_e32 v93, 31, v92
	s_waitcnt lgkmcnt(0)
	v_lshl_add_u64 v[64:65], v[170:171], 0, v[110:111]
	v_ashrrev_i32_e32 v89, 31, v88
	v_lshlrev_b64 v[98:99], 11, v[96:97]
	v_lshlrev_b64 v[94:95], 11, v[92:93]
	global_load_dwordx4 v[102:105], v[64:65], off
	global_load_dwordx4 v[106:109], v[64:65], off offset:256
	v_lshlrev_b64 v[90:91], 11, v[88:89]
	v_lshl_add_u64 v[64:65], v[170:171], 0, v[98:99]
	v_lshl_add_u64 v[66:67], v[170:171], 0, v[94:95]
	v_lshl_add_u64 v[112:113], v[170:171], 0, v[90:91]
	global_load_dwordx4 v[84:87], v[64:65], off
	global_load_dwordx4 v[80:83], v[64:65], off offset:256
	global_load_dwordx4 v[76:79], v[66:67], off
	global_load_dwordx4 v[72:75], v[66:67], off offset:256
	global_load_dwordx4 v[68:71], v[112:113], off
	s_nop 0
	global_load_dwordx4 v[64:67], v[112:113], off offset:256
	v_readlane_b32 s2, v235, 38
	v_readlane_b32 s3, v235, 39
	s_and_b64 vcc, exec, s[8:9]
	s_waitcnt vmcnt(7)
	v_lshlrev_b32_e32 v112, 16, v102
	v_lshl_add_u64 v[110:111], s[2:3], 0, v[110:111]
	v_and_b32_e32 v113, 0xffff0000, v102
	v_lshlrev_b32_e32 v102, 16, v103
	v_and_b32_e32 v103, 0xffff0000, v103
	v_lshlrev_b32_e32 v114, 16, v104
	v_and_b32_e32 v115, 0xffff0000, v104
	v_lshlrev_b32_e32 v104, 16, v105
	v_and_b32_e32 v105, 0xffff0000, v105
	s_waitcnt vmcnt(6)
	v_lshlrev_b32_e32 v116, 16, v106
	v_and_b32_e32 v117, 0xffff0000, v106
	v_lshlrev_b32_e32 v106, 16, v107
	v_and_b32_e32 v107, 0xffff0000, v107
	v_lshlrev_b32_e32 v118, 16, v108
	v_and_b32_e32 v119, 0xffff0000, v108
	v_lshlrev_b32_e32 v108, 16, v109
	v_and_b32_e32 v109, 0xffff0000, v109
	v_lshl_add_u64 v[110:111], v[166:167], 1, v[110:111]
	v_pk_fma_f32 v[62:63], v[62:63], 0.5, v[102:103] op_sel_hi:[1,0,1]
	v_pk_fma_f32 v[60:61], v[60:61], 0.5, v[112:113] op_sel_hi:[1,0,1]
	v_pk_fma_f32 v[58:59], v[58:59], 0.5, v[104:105] op_sel_hi:[1,0,1]
	v_pk_fma_f32 v[56:57], v[56:57], 0.5, v[114:115] op_sel_hi:[1,0,1]
	v_pk_fma_f32 v[54:55], v[54:55], 0.5, v[106:107] op_sel_hi:[1,0,1]
	v_pk_fma_f32 v[52:53], v[52:53], 0.5, v[116:117] op_sel_hi:[1,0,1]
	v_pk_fma_f32 v[50:51], v[50:51], 0.5, v[108:109] op_sel_hi:[1,0,1]
	v_pk_fma_f32 v[48:49], v[48:49], 0.5, v[118:119] op_sel_hi:[1,0,1]
	v_cvt_pk_bf16_f32 v102, v60, v61
	v_cvt_pk_bf16_f32 v103, v62, v63
	v_cvt_pk_bf16_f32 v104, v56, v57
	v_cvt_pk_bf16_f32 v105, v58, v59
	global_store_dwordx4 v[110:111], v[102:105], off
	s_nop 1
	v_cvt_pk_bf16_f32 v102, v52, v53
	v_cvt_pk_bf16_f32 v103, v54, v55
	v_cvt_pk_bf16_f32 v104, v48, v49
	v_cvt_pk_bf16_f32 v105, v50, v51
	global_store_dwordx4 v[110:111], v[102:105], off offset:256
	s_cbranch_vccnz .LBB0_280
	v_mul_f32_e32 v49, v49, v49
	v_mul_f32_e32 v61, v61, v61
	v_mul_f32_e32 v57, v57, v57
	v_mul_f32_e32 v53, v53, v53
	v_fmac_f32_e32 v49, v48, v48
	v_mul_f32_e32 v48, v51, v51
	v_fmac_f32_e32 v61, v60, v60
	v_mul_f32_e32 v60, v63, v63
	v_fmac_f32_e32 v57, v56, v56
	v_mul_f32_e32 v56, v59, v59
	v_fmac_f32_e32 v53, v52, v52
	v_mul_f32_e32 v52, v55, v55
	v_fmac_f32_e32 v48, v50, v50
	v_and_b32_e32 v50, 64, v191
	v_fmac_f32_e32 v60, v62, v62
	v_fmac_f32_e32 v56, v58, v58
	v_fmac_f32_e32 v52, v54, v54
	v_add_f32_e32 v48, v49, v48
	v_xor_b32_e32 v49, 16, v191
	v_add_u32_e32 v50, 64, v50
	v_add_f32_e32 v60, v61, v60
	v_add_f32_e32 v56, v57, v56
	v_add_f32_e32 v52, v53, v52
	v_cmp_lt_i32_e32 vcc, v49, v50
	v_add_f32_e32 v56, v60, v56
	v_add_f32_e32 v48, v52, v48
	v_cndmask_b32_e32 v49, v191, v49, vcc
	v_add_f32_e32 v48, v56, v48
	v_lshlrev_b32_e32 v49, 2, v49
	v_mov_b32_e32 v236, v48
	v_mov_b32_e32 v237, v48
	s_nop 1
	v_permlane16_swap_b32_e32 v236, v237
	v_cndmask_b32_e64 v49, v237, v236, s[98:99]
	s_waitcnt lgkmcnt(0)
	v_add_f32_e32 v48, v48, v49
	v_xor_b32_e32 v49, 32, v191
	v_cmp_lt_i32_e32 vcc, v49, v50
	s_nop 1
	v_cndmask_b32_e32 v49, v191, v49, vcc
	v_lshlrev_b32_e32 v49, 2, v49
	v_mov_b32_e32 v236, v48
	v_mov_b32_e32 v237, v48
	s_nop 1
	v_permlane32_swap_b32_e32 v236, v237
	v_cndmask_b32_e64 v49, v237, v236, s[100:101]
	s_and_saveexec_b64 s[2:3], s[4:5]
	s_cbranch_execz .LBB0_279
	v_readlane_b32 s30, v235, 50
	v_lshlrev_b64 v[50:51], 6, v[100:101]
	v_readlane_b32 s31, v235, 51
	s_lshl_b32 s16, s39, 2
	s_waitcnt lgkmcnt(0)
	v_add_f32_e32 v48, v48, v49
	v_lshl_add_u64 v[50:51], s[30:31], 0, v[50:51]
	v_lshl_add_u64 v[50:51], s[26:27], 2, v[50:51]
	v_lshl_add_u64 v[50:51], v[50:51], 0, s[16:17]
	global_store_dword v[50:51], v48, off

; __device__ __forceinline__ unsigned cvt_pk_bf16(float lo, float hi) { unsigned r; asm volatile("v_cvt_pk_bf16_f32 %0, %1, %2" : "=v"(r) : "v"(lo), "v"(hi)); return r; }
; __device__ __forceinline__ float bf_lo(unsigned w) { return __uint_as_float(w << 16); }
; __device__ __forceinline__ float bf_hi(unsigned w) { return __uint_as_float(w & 0xffff0000u); }
;     __device__ __forceinline__ void operator()(const f32x4 (&acc)[2][2][4][2], const Unit& u, int wr, int wc, int fr, int fq) const {
;     ...
;             for (int mm = 0; mm < RB; ++mm) {
;                 const int m = mh + mm;
;                 const int row = row0 + ai * HALF + m * 16; const size_t off = (size_t)row * D_MODEL + col0; float s = 0.f;
; #pragma unroll
;                 for (int bj = 0; bj < 2; ++bj) {
;                     f32x4 b0, b1;
;                     if (BASE_F32) { b0 = bf[mm][bj][0]; b1 = bf[mm][bj][1]; }
;                     else { const u32x4 w = bb[mm][bj]; b0 = (f32x4){bf_lo(w.x), bf_hi(w.x), bf_lo(w.y), bf_hi(w.y)}; b1 = (f32x4){bf_lo(w.z), bf_hi(w.z), bf_lo(w.w), bf_hi(w.w)}; }
;                     const f32x4 o0 = b0 + acc[ai][bj][m][0] * alpha, o1 = b1 + acc[ai][bj][m][1] * alpha;
;                     if (OUT_F32) { *(f32x4*)(out + off + bj * HALF) = o0; *(f32x4*)(out + off + bj * HALF + 4) = o1; }
;                     else { u32x4 w; w.x = cvt_pk_bf16(o0[0], o0[1]); w.y = cvt_pk_bf16(o0[2], o0[3]); w.z = cvt_pk_bf16(o1[0], o1[1]); w.w = cvt_pk_bf16(o1[2], o1[3]); *(u32x4*)(xb + off + bj * HALF) = w; }
;                     s += ((o0[0] * o0[0] + o0[1] * o0[1]) + (o0[2] * o0[2] + o0[3] * o0[3])) + ((o1[0] * o1[0] + o1[1] * o1[1]) + (o1[2] * o1[2] + o1[3] * o1[3]));
;                 }
;                 if (ssp) { s += __shfl_xor(s, 16); s += __shfl_xor(s, 32); if (fq == 0) ssp[(size_t)row * 16 + u.pn * 4 + wc] = s; }
.LBB0_280:
	v_readlane_b32 s2, v235, 38
	s_waitcnt vmcnt(7)
	v_lshlrev_b32_e32 v52, 16, v86
	v_and_b32_e32 v53, 0xffff0000, v86
	v_readlane_b32 s3, v235, 39
	v_lshlrev_b32_e32 v48, 16, v84
	s_waitcnt lgkmcnt(0)
	v_and_b32_e32 v49, 0xffff0000, v84
	v_lshlrev_b32_e32 v50, 16, v85
	v_and_b32_e32 v51, 0xffff0000, v85
	v_lshlrev_b32_e32 v54, 16, v87
	v_and_b32_e32 v55, 0xffff0000, v87
	v_pk_fma_f32 v[40:41], v[40:41], 0.5, v[52:53] op_sel_hi:[1,0,1]
	v_lshl_add_u64 v[52:53], s[2:3], 0, v[98:99]
	v_pk_fma_f32 v[46:47], v[46:47], 0.5, v[50:51] op_sel_hi:[1,0,1]
	v_pk_fma_f32 v[44:45], v[44:45], 0.5, v[48:49] op_sel_hi:[1,0,1]
	v_pk_fma_f32 v[42:43], v[42:43], 0.5, v[54:55] op_sel_hi:[1,0,1]
	v_cvt_pk_bf16_f32 v48, v44, v45
	v_cvt_pk_bf16_f32 v49, v46, v47
	v_cvt_pk_bf16_f32 v50, v40, v41
	v_lshl_add_u64 v[52:53], v[166:167], 1, v[52:53]
	v_cvt_pk_bf16_f32 v51, v42, v43
	global_store_dwordx4 v[52:53], v[48:51], off
	s_waitcnt vmcnt(7)
	v_lshlrev_b32_e32 v54, 16, v82
	v_and_b32_e32 v55, 0xffff0000, v82
	v_lshlrev_b32_e32 v48, 16, v80
	v_and_b32_e32 v49, 0xffff0000, v80
	v_lshlrev_b32_e32 v50, 16, v81
	v_and_b32_e32 v51, 0xffff0000, v81
	v_lshlrev_b32_e32 v56, 16, v83
	v_and_b32_e32 v57, 0xffff0000, v83
	v_pk_fma_f32 v[38:39], v[38:39], 0.5, v[50:51] op_sel_hi:[1,0,1]
	v_pk_fma_f32 v[36:37], v[36:37], 0.5, v[48:49] op_sel_hi:[1,0,1]
	v_pk_fma_f32 v[34:35], v[34:35], 0.5, v[56:57] op_sel_hi:[1,0,1]
	v_pk_fma_f32 v[32:33], v[32:33], 0.5, v[54:55] op_sel_hi:[1,0,1]
	s_and_b64 vcc, exec, s[8:9]
	v_cvt_pk_bf16_f32 v48, v36, v37
	v_cvt_pk_bf16_f32 v49, v38, v39
	v_cvt_pk_bf16_f32 v50, v32, v33
	v_cvt_pk_bf16_f32 v51, v34, v35
	global_store_dwordx4 v[52:53], v[48:51], off offset:256
	s_cbranch_vccnz .LBB0_284
	v_mul_f32_e32 v33, v33, v33
	v_mul_f32_e32 v45, v45, v45
	v_mul_f32_e32 v41, v41, v41
	v_mul_f32_e32 v37, v37, v37
	v_fmac_f32_e32 v33, v32, v32
	v_mul_f32_e32 v32, v35, v35
	v_fmac_f32_e32 v45, v44, v44
	v_mul_f32_e32 v44, v47, v47
	v_fmac_f32_e32 v41, v40, v40
	v_mul_f32_e32 v40, v43, v43
	v_fmac_f32_e32 v37, v36, v36
	v_mul_f32_e32 v36, v39, v39
	v_fmac_f32_e32 v32, v34, v34
	v_and_b32_e32 v34, 64, v191
	v_fmac_f32_e32 v44, v46, v46
	v_fmac_f32_e32 v40, v42, v42
	v_fmac_f32_e32 v36, v38, v38
	v_add_f32_e32 v32, v33, v32
	v_xor_b32_e32 v33, 16, v191
	v_add_u32_e32 v34, 64, v34
	v_add_f32_e32 v44, v45, v44
	v_add_f32_e32 v40, v41, v40
	v_add_f32_e32 v36, v37, v36
	v_cmp_lt_i32_e32 vcc, v33, v34
	v_add_f32_e32 v40, v44, v40
	v_add_f32_e32 v32, v36, v32
	v_cndmask_b32_e32 v33, v191, v33, vcc
	v_add_f32_e32 v32, v40, v32
	v_lshlrev_b32_e32 v33, 2, v33
	v_mov_b32_e32 v236, v32
	v_mov_b32_e32 v237, v32
	s_nop 1
	v_permlane16_swap_b32_e32 v236, v237
	v_cndmask_b32_e64 v33, v237, v236, s[98:99]
	s_waitcnt lgkmcnt(0)
	v_add_f32_e32 v32, v32, v33
	v_xor_b32_e32 v33, 32, v191
	v_cmp_lt_i32_e32 vcc, v33, v34
	s_nop 1
	v_cndmask_b32_e32 v33, v191, v33, vcc
	v_lshlrev_b32_e32 v33, 2, v33
	v_mov_b32_e32 v236, v32
	v_mov_b32_e32 v237, v32
	s_nop 1
	v_permlane32_swap_b32_e32 v236, v237
	v_cndmask_b32_e64 v33, v237, v236, s[100:101]
	s_and_saveexec_b64 s[2:3], s[4:5]
	s_cbranch_execz .LBB0_283
	v_readlane_b32 s30, v235, 50
	v_lshlrev_b64 v[34:35], 6, v[96:97]
	v_readlane_b32 s31, v235, 51
	s_lshl_b32 s16, s39, 2
	s_waitcnt lgkmcnt(0)
	v_add_f32_e32 v32, v32, v33
	v_lshl_add_u64 v[34:35], s[30:31], 0, v[34:35]
	v_lshl_add_u64 v[34:35], s[26:27], 2, v[34:35]
	v_lshl_add_u64 v[34:35], v[34:35], 0, s[16:17]
	global_store_dword v[34:35], v32, off

; __device__ __forceinline__ unsigned cvt_pk_bf16(float lo, float hi) { unsigned r; asm volatile("v_cvt_pk_bf16_f32 %0, %1, %2" : "=v"(r) : "v"(lo), "v"(hi)); return r; }
; __device__ __forceinline__ float bf_lo(unsigned w) { return __uint_as_float(w << 16); }
; __device__ __forceinline__ float bf_hi(unsigned w) { return __uint_as_float(w & 0xffff0000u); }
;     __device__ __forceinline__ void operator()(const f32x4 (&acc)[2][2][4][2], const Unit& u, int wr, int wc, int fr, int fq) const {
;     ...
;             for (int mm = 0; mm < RB; ++mm) {
;                 const int m = mh + mm;
;                 const int row = row0 + ai * HALF + m * 16; const size_t off = (size_t)row * D_MODEL + col0; float s = 0.f;
; #pragma unroll
;                 for (int bj = 0; bj < 2; ++bj) {
;                     f32x4 b0, b1;
;                     if (BASE_F32) { b0 = bf[mm][bj][0]; b1 = bf[mm][bj][1]; }
;                     else { const u32x4 w = bb[mm][bj]; b0 = (f32x4){bf_lo(w.x), bf_hi(w.x), bf_lo(w.y), bf_hi(w.y)}; b1 = (f32x4){bf_lo(w.z), bf_hi(w.z), bf_lo(w.w), bf_hi(w.w)}; }
;                     const f32x4 o0 = b0 + acc[ai][bj][m][0] * alpha, o1 = b1 + acc[ai][bj][m][1] * alpha;
;                     if (OUT_F32) { *(f32x4*)(out + off + bj * HALF) = o0; *(f32x4*)(out + off + bj * HALF + 4) = o1; }
;                     else { u32x4 w; w.x = cvt_pk_bf16(o0[0], o0[1]); w.y = cvt_pk_bf16(o0[2], o0[3]); w.z = cvt_pk_bf16(o1[0], o1[1]); w.w = cvt_pk_bf16(o1[2], o1[3]); *(u32x4*)(xb + off + bj * HALF) = w; }
;                     s += ((o0[0] * o0[0] + o0[1] * o0[1]) + (o0[2] * o0[2] + o0[3] * o0[3])) + ((o1[0] * o1[0] + o1[1] * o1[1]) + (o1[2] * o1[2] + o1[3] * o1[3]));
;                 }
;                 if (ssp) { s += __shfl_xor(s, 16); s += __shfl_xor(s, 32); if (fq == 0) ssp[(size_t)row * 16 + u.pn * 4 + wc] = s; }
.LBB0_284:
	v_readlane_b32 s2, v235, 38
	s_waitcnt vmcnt(7)
	v_lshlrev_b32_e32 v36, 16, v78
	v_and_b32_e32 v37, 0xffff0000, v78
	v_readlane_b32 s3, v235, 39
	v_lshlrev_b32_e32 v32, 16, v76
	s_waitcnt lgkmcnt(0)
	v_and_b32_e32 v33, 0xffff0000, v76
	v_lshlrev_b32_e32 v34, 16, v77
	v_and_b32_e32 v35, 0xffff0000, v77
	v_lshlrev_b32_e32 v38, 16, v79
	v_and_b32_e32 v39, 0xffff0000, v79
	v_pk_fma_f32 v[24:25], v[24:25], 0.5, v[36:37] op_sel_hi:[1,0,1]
	v_lshl_add_u64 v[36:37], s[2:3], 0, v[94:95]
	v_pk_fma_f32 v[30:31], v[30:31], 0.5, v[34:35] op_sel_hi:[1,0,1]
	v_pk_fma_f32 v[28:29], v[28:29], 0.5, v[32:33] op_sel_hi:[1,0,1]
	v_pk_fma_f32 v[26:27], v[26:27], 0.5, v[38:39] op_sel_hi:[1,0,1]
	v_cvt_pk_bf16_f32 v32, v28, v29
	v_cvt_pk_bf16_f32 v33, v30, v31
	v_cvt_pk_bf16_f32 v34, v24, v25
	v_lshl_add_u64 v[36:37], v[166:167], 1, v[36:37]
	v_cvt_pk_bf16_f32 v35, v26, v27
	global_store_dwordx4 v[36:37], v[32:35], off
	s_waitcnt vmcnt(7)
	v_lshlrev_b32_e32 v38, 16, v74
	v_and_b32_e32 v39, 0xffff0000, v74
	v_lshlrev_b32_e32 v32, 16, v72
	v_and_b32_e32 v33, 0xffff0000, v72
	v_lshlrev_b32_e32 v34, 16, v73
	v_and_b32_e32 v35, 0xffff0000, v73
	v_lshlrev_b32_e32 v40, 16, v75
	v_and_b32_e32 v41, 0xffff0000, v75
	v_pk_fma_f32 v[22:23], v[22:23], 0.5, v[34:35] op_sel_hi:[1,0,1]
	v_pk_fma_f32 v[20:21], v[20:21], 0.5, v[32:33] op_sel_hi:[1,0,1]
	v_pk_fma_f32 v[18:19], v[18:19], 0.5, v[40:41] op_sel_hi:[1,0,1]
	v_pk_fma_f32 v[16:17], v[16:17], 0.5, v[38:39] op_sel_hi:[1,0,1]
	s_and_b64 vcc, exec, s[8:9]
	v_cvt_pk_bf16_f32 v32, v20, v21
	v_cvt_pk_bf16_f32 v33, v22, v23
	v_cvt_pk_bf16_f32 v34, v16, v17
	v_cvt_pk_bf16_f32 v35, v18, v19
	global_store_dwordx4 v[36:37], v[32:35], off offset:256
	s_cbranch_vccnz .LBB0_288
	v_mul_f32_e32 v17, v17, v17
	v_mul_f32_e32 v29, v29, v29
	v_mul_f32_e32 v25, v25, v25
	v_mul_f32_e32 v21, v21, v21
	v_fmac_f32_e32 v17, v16, v16
	v_mul_f32_e32 v16, v19, v19
	v_fmac_f32_e32 v29, v28, v28
	v_mul_f32_e32 v28, v31, v31
	v_fmac_f32_e32 v25, v24, v24
	v_mul_f32_e32 v24, v27, v27
	v_fmac_f32_e32 v21, v20, v20
	v_mul_f32_e32 v20, v23, v23
	v_fmac_f32_e32 v16, v18, v18
	v_and_b32_e32 v18, 64, v191
	v_fmac_f32_e32 v28, v30, v30
	v_fmac_f32_e32 v24, v26, v26
	v_fmac_f32_e32 v20, v22, v22
	v_add_f32_e32 v16, v17, v16
	v_xor_b32_e32 v17, 16, v191
	v_add_u32_e32 v18, 64, v18
	v_add_f32_e32 v28, v29, v28
	v_add_f32_e32 v24, v25, v24
	v_add_f32_e32 v20, v21, v20
	v_cmp_lt_i32_e32 vcc, v17, v18
	v_add_f32_e32 v24, v28, v24
	v_add_f32_e32 v16, v20, v16
	v_cndmask_b32_e32 v17, v191, v17, vcc
	v_add_f32_e32 v16, v24, v16
	v_lshlrev_b32_e32 v17, 2, v17
	v_mov_b32_e32 v236, v16
	v_mov_b32_e32 v237, v16
	s_nop 1
	v_permlane16_swap_b32_e32 v236, v237
	v_cndmask_b32_e64 v17, v237, v236, s[98:99]
	s_waitcnt lgkmcnt(0)
	v_add_f32_e32 v16, v16, v17
	v_xor_b32_e32 v17, 32, v191
	v_cmp_lt_i32_e32 vcc, v17, v18
	s_nop 1
	v_cndmask_b32_e32 v17, v191, v17, vcc
	v_lshlrev_b32_e32 v17, 2, v17
	v_mov_b32_e32 v236, v16
	v_mov_b32_e32 v237, v16
	s_nop 1
	v_permlane32_swap_b32_e32 v236, v237
	v_cndmask_b32_e64 v17, v237, v236, s[100:101]
	s_and_saveexec_b64 s[2:3], s[4:5]
	s_cbranch_execz .LBB0_287
	v_readlane_b32 s30, v235, 50
	v_lshlrev_b64 v[18:19], 6, v[92:93]
	v_readlane_b32 s31, v235, 51
	s_lshl_b32 s16, s39, 2
	s_waitcnt lgkmcnt(0)
	v_add_f32_e32 v16, v16, v17
	v_lshl_add_u64 v[18:19], s[30:31], 0, v[18:19]
	v_lshl_add_u64 v[18:19], s[26:27], 2, v[18:19]
	v_lshl_add_u64 v[18:19], v[18:19], 0, s[16:17]
	global_store_dword v[18:19], v16, off

; __device__ __forceinline__ unsigned cvt_pk_bf16(float lo, float hi) { unsigned r; asm volatile("v_cvt_pk_bf16_f32 %0, %1, %2" : "=v"(r) : "v"(lo), "v"(hi)); return r; }
; __device__ __forceinline__ float bf_lo(unsigned w) { return __uint_as_float(w << 16); }
; __device__ __forceinline__ float bf_hi(unsigned w) { return __uint_as_float(w & 0xffff0000u); }
;     __device__ __forceinline__ void operator()(const f32x4 (&acc)[2][2][4][2], const Unit& u, int wr, int wc, int fr, int fq) const {
;     ...
;             for (int mm = 0; mm < RB; ++mm) {
;                 const int m = mh + mm;
;                 const int row = row0 + ai * HALF + m * 16; const size_t off = (size_t)row * D_MODEL + col0; float s = 0.f;
; #pragma unroll
;                 for (int bj = 0; bj < 2; ++bj) {
;                     f32x4 b0, b1;
;                     if (BASE_F32) { b0 = bf[mm][bj][0]; b1 = bf[mm][bj][1]; }
;                     else { const u32x4 w = bb[mm][bj]; b0 = (f32x4){bf_lo(w.x), bf_hi(w.x), bf_lo(w.y), bf_hi(w.y)}; b1 = (f32x4){bf_lo(w.z), bf_hi(w.z), bf_lo(w.w), bf_hi(w.w)}; }
;                     const f32x4 o0 = b0 + acc[ai][bj][m][0] * alpha, o1 = b1 + acc[ai][bj][m][1] * alpha;
;                     if (OUT_F32) { *(f32x4*)(out + off + bj * HALF) = o0; *(f32x4*)(out + off + bj * HALF + 4) = o1; }
;                     else { u32x4 w; w.x = cvt_pk_bf16(o0[0], o0[1]); w.y = cvt_pk_bf16(o0[2], o0[3]); w.z = cvt_pk_bf16(o1[0], o1[1]); w.w = cvt_pk_bf16(o1[2], o1[3]); *(u32x4*)(xb + off + bj * HALF) = w; }
;                     s += ((o0[0] * o0[0] + o0[1] * o0[1]) + (o0[2] * o0[2] + o0[3] * o0[3])) + ((o1[0] * o1[0] + o1[1] * o1[1]) + (o1[2] * o1[2] + o1[3] * o1[3]));
;                 }
;                 if (ssp) { s += __shfl_xor(s, 16); s += __shfl_xor(s, 32); if (fq == 0) ssp[(size_t)row * 16 + u.pn * 4 + wc] = s; }
.LBB0_288:
	v_readlane_b32 s2, v235, 38
	s_waitcnt vmcnt(7)
	v_lshlrev_b32_e32 v20, 16, v70
	v_and_b32_e32 v21, 0xffff0000, v70
	v_readlane_b32 s3, v235, 39
	v_lshlrev_b32_e32 v16, 16, v68
	s_waitcnt lgkmcnt(0)
	v_and_b32_e32 v17, 0xffff0000, v68
	v_lshlrev_b32_e32 v18, 16, v69
	v_and_b32_e32 v19, 0xffff0000, v69
	v_lshlrev_b32_e32 v22, 16, v71
	v_and_b32_e32 v23, 0xffff0000, v71
	v_pk_fma_f32 v[8:9], v[8:9], 0.5, v[20:21] op_sel_hi:[1,0,1]
	v_lshl_add_u64 v[20:21], s[2:3], 0, v[90:91]
	v_pk_fma_f32 v[14:15], v[14:15], 0.5, v[18:19] op_sel_hi:[1,0,1]
	v_pk_fma_f32 v[12:13], v[12:13], 0.5, v[16:17] op_sel_hi:[1,0,1]
	v_pk_fma_f32 v[10:11], v[10:11], 0.5, v[22:23] op_sel_hi:[1,0,1]
	v_cvt_pk_bf16_f32 v16, v12, v13
	v_cvt_pk_bf16_f32 v17, v14, v15
	v_cvt_pk_bf16_f32 v18, v8, v9
	v_lshl_add_u64 v[20:21], v[166:167], 1, v[20:21]
	v_cvt_pk_bf16_f32 v19, v10, v11
	global_store_dwordx4 v[20:21], v[16:19], off
	s_waitcnt vmcnt(7)
	v_lshlrev_b32_e32 v22, 16, v66
	v_and_b32_e32 v23, 0xffff0000, v66
	v_lshlrev_b32_e32 v16, 16, v64
	v_and_b32_e32 v17, 0xffff0000, v64
	v_lshlrev_b32_e32 v18, 16, v65
	v_and_b32_e32 v19, 0xffff0000, v65
	v_lshlrev_b32_e32 v24, 16, v67
	v_and_b32_e32 v25, 0xffff0000, v67
	v_pk_fma_f32 v[6:7], v[6:7], 0.5, v[18:19] op_sel_hi:[1,0,1]
	v_pk_fma_f32 v[4:5], v[4:5], 0.5, v[16:17] op_sel_hi:[1,0,1]
	v_pk_fma_f32 v[2:3], v[2:3], 0.5, v[24:25] op_sel_hi:[1,0,1]
	v_pk_fma_f32 v[0:1], v[0:1], 0.5, v[22:23] op_sel_hi:[1,0,1]
	s_and_b64 vcc, exec, s[8:9]
	v_cvt_pk_bf16_f32 v16, v4, v5
	v_cvt_pk_bf16_f32 v17, v6, v7
	v_cvt_pk_bf16_f32 v18, v0, v1
	v_cvt_pk_bf16_f32 v19, v2, v3
	global_store_dwordx4 v[20:21], v[16:19], off offset:256
	s_cbranch_vccnz .LBB0_292
	v_mul_f32_e32 v1, v1, v1
	v_mul_f32_e32 v13, v13, v13
	v_mul_f32_e32 v9, v9, v9
	v_mul_f32_e32 v5, v5, v5
	v_fmac_f32_e32 v1, v0, v0
	v_mul_f32_e32 v0, v3, v3
	v_fmac_f32_e32 v13, v12, v12
	v_mul_f32_e32 v12, v15, v15
	v_fmac_f32_e32 v9, v8, v8
	v_mul_f32_e32 v8, v11, v11
	v_fmac_f32_e32 v5, v4, v4
	v_mul_f32_e32 v4, v7, v7
	v_fmac_f32_e32 v0, v2, v2
	v_and_b32_e32 v2, 64, v191
	v_fmac_f32_e32 v12, v14, v14
	v_fmac_f32_e32 v8, v10, v10
	v_fmac_f32_e32 v4, v6, v6
	v_add_f32_e32 v0, v1, v0
	v_xor_b32_e32 v1, 16, v191
	v_add_u32_e32 v2, 64, v2
	v_add_f32_e32 v12, v13, v12
	v_add_f32_e32 v8, v9, v8
	v_add_f32_e32 v4, v5, v4
	v_cmp_lt_i32_e32 vcc, v1, v2
	v_add_f32_e32 v8, v12, v8
	v_add_f32_e32 v0, v4, v0
	v_cndmask_b32_e32 v1, v191, v1, vcc
	v_add_f32_e32 v0, v8, v0
	v_lshlrev_b32_e32 v1, 2, v1
	v_mov_b32_e32 v236, v0
	v_mov_b32_e32 v237, v0
	s_nop 1
	v_permlane16_swap_b32_e32 v236, v237
	v_cndmask_b32_e64 v1, v237, v236, s[98:99]
	s_waitcnt lgkmcnt(0)
	v_add_f32_e32 v0, v0, v1
	v_xor_b32_e32 v1, 32, v191
	v_cmp_lt_i32_e32 vcc, v1, v2
	s_nop 1
	v_cndmask_b32_e32 v1, v191, v1, vcc
	v_lshlrev_b32_e32 v1, 2, v1
	v_mov_b32_e32 v236, v0
	v_mov_b32_e32 v237, v0
	s_nop 1
	v_permlane32_swap_b32_e32 v236, v237
	v_cndmask_b32_e64 v1, v237, v236, s[100:101]
	s_and_saveexec_b64 s[2:3], s[4:5]
	s_cbranch_execz .LBB0_291
	v_readlane_b32 s8, v235, 50
	v_lshlrev_b64 v[2:3], 6, v[88:89]
	v_readlane_b32 s9, v235, 51
	s_lshl_b32 s16, s39, 2
	s_waitcnt lgkmcnt(0)
	v_add_f32_e32 v0, v0, v1
	v_lshl_add_u64 v[2:3], s[8:9], 0, v[2:3]
	v_lshl_add_u64 v[2:3], s[26:27], 2, v[2:3]
	v_lshl_add_u64 v[2:3], v[2:3], 0, s[16:17]
	global_store_dword v[2:3], v0, off

; template <int NP> __device__ __forceinline__ void load_rs(const float* ssp, int row0, int fq, float (&rs)[2][4]) {
;     ...
;             for (int m = 0; m < 4; ++m) p[ai][m] = *(const f32x4*)(ssp + (size_t)(row0 + ai * HALF + m * 16) * 16 + 4 * fq);
; #pragma unroll
;         for (int ai = 0; ai < 2; ++ai)
; #pragma unroll
;             for (int m = 0; m < 4; ++m) { float s = (p[ai][m][0] + p[ai][m][1]) + (p[ai][m][2] + p[ai][m][3]); s += __shfl_xor(s, 16); s += __shfl_xor(s, 32); rs[ai][m] = s; }
;     __device__ __forceinline__ void operator()(const f32x4 (&acc)[2][2][4][2], const Unit& u, int wr, int wc, int fr, int fq) const {
;         if (u.pn >= 9) body<true>(acc, u, wr, wc, fr, fq); else body<false>(acc, u, wr, wc, fr, fq);
.LBB0_382:
	v_lshl_add_u32 v186, s33, 8, v193
	v_or_b32_e32 v184, 16, v186
	v_ashrrev_i32_e32 v187, 31, v186
	v_ashrrev_i32_e32 v185, 31, v184
	v_lshlrev_b64 v[128:129], 6, v[186:187]
	v_lshlrev_b64 v[130:131], 6, v[184:185]
	v_or_b32_e32 v182, 32, v186
	v_or_b32_e32 v180, 48, v186
	v_lshl_add_u64 v[128:129], v[162:163], 0, v[128:129]
	v_lshl_add_u64 v[130:131], v[162:163], 0, v[130:131]
	v_ashrrev_i32_e32 v183, 31, v182
	v_ashrrev_i32_e32 v181, 31, v180
	global_load_dwordx4 v[148:151], v[128:129], off
	global_load_dwordx4 v[204:207], v[130:131], off
	v_lshlrev_b64 v[128:129], 6, v[182:183]
	v_lshlrev_b64 v[130:131], 6, v[180:181]
	v_add_u32_e32 v178, 0x80, v186
	v_add_u32_e32 v176, 0x90, v186
	v_lshl_add_u64 v[128:129], v[162:163], 0, v[128:129]
	v_lshl_add_u64 v[130:131], v[162:163], 0, v[130:131]
	v_ashrrev_i32_e32 v179, 31, v178
	v_ashrrev_i32_e32 v177, 31, v176
	global_load_dwordx4 v[208:211], v[128:129], off
	global_load_dwordx4 v[140:143], v[130:131], off
	v_lshlrev_b64 v[128:129], 6, v[178:179]
	v_lshlrev_b64 v[130:131], 6, v[176:177]
	v_add_u32_e32 v174, 0xa0, v186
	v_add_u32_e32 v170, 0xb0, v186
	v_lshl_add_u64 v[128:129], v[162:163], 0, v[128:129]
	v_lshl_add_u64 v[130:131], v[162:163], 0, v[130:131]
	v_ashrrev_i32_e32 v175, 31, v174
	v_ashrrev_i32_e32 v171, 31, v170
	global_load_dwordx4 v[144:147], v[128:129], off
	global_load_dwordx4 v[132:135], v[130:131], off
	v_lshlrev_b64 v[128:129], 6, v[174:175]
	v_lshlrev_b64 v[130:131], 6, v[170:171]
	v_lshl_add_u64 v[128:129], v[162:163], 0, v[128:129]
	v_lshl_add_u64 v[130:131], v[162:163], 0, v[130:131]
	global_load_dwordx4 v[136:139], v[128:129], off
	s_nop 0
	global_load_dwordx4 v[128:131], v[130:131], off
	v_and_b32_e32 v172, 64, v201
	v_xor_b32_e32 v171, 16, v201
	v_add_u32_e32 v172, 64, v172
	v_xor_b32_e32 v173, 32, v201
	v_cmp_lt_i32_e32 vcc, v171, v172
	s_cmp_lt_i32 s43, 9
	v_lshl_or_b32 v160, s43, 8, v197
	v_cndmask_b32_e32 v171, v201, v171, vcc
	v_cmp_lt_i32_e32 vcc, v173, v172
	v_lshlrev_b32_e32 v175, 2, v171
	s_waitcnt vmcnt(0)
	v_add_f32_e32 v148, v148, v149
	v_add_f32_e32 v149, v150, v151
	v_cndmask_b32_e32 v172, v201, v173, vcc
	v_add_f32_e32 v177, v148, v149
	v_add_f32_e32 v148, v204, v205
	v_add_f32_e32 v149, v206, v207
	v_lshlrev_b32_e32 v171, 2, v172
	v_add_f32_e32 v179, v148, v149
	v_add_f32_e32 v150, v208, v209
	v_add_f32_e32 v151, v210, v211
	v_add_f32_e32 v181, v150, v151
	s_cbranch_scc0 .LBB0_384
	v_mov_b32_e32 v236, v177
	v_mov_b32_e32 v237, v177
	s_nop 1
	v_permlane16_swap_b32_e32 v236, v237
	v_cndmask_b32_e64 v150, v237, v236, s[98:99]
	v_mov_b32_e32 v236, v179
	v_mov_b32_e32 v237, v179
	s_nop 1
	v_permlane16_swap_b32_e32 v236, v237
	v_cndmask_b32_e64 v151, v237, v236, s[98:99]
	v_mov_b32_e32 v148, v141
	v_mov_b32_e32 v149, v142
	v_mov_b32_e32 v236, v181
	v_mov_b32_e32 v237, v181
	s_nop 1
	v_permlane16_swap_b32_e32 v236, v237
	v_cndmask_b32_e64 v172, v237, v236, s[98:99]
	s_waitcnt lgkmcnt(2)
	v_add_f32_e32 v150, v177, v150
	v_mov_b32_e32 v236, v150
	v_mov_b32_e32 v237, v150
	s_nop 1
	v_permlane32_swap_b32_e32 v236, v237
	v_cndmask_b32_e64 v173, v237, v236, s[100:101]
	s_waitcnt lgkmcnt(2)
	v_add_f32_e32 v183, v179, v151
	v_mov_b32_e32 v151, v143
	v_mov_b32_e32 v236, v183
	v_mov_b32_e32 v237, v183
	s_nop 1
	v_permlane32_swap_b32_e32 v236, v237
	v_cndmask_b32_e64 v185, v237, v236, s[100:101]
	s_waitcnt lgkmcnt(2)
	v_add_f32_e32 v172, v181, v172
	s_waitcnt lgkmcnt(1)
	v_add_f32_e32 v173, v150, v173
	v_mov_b32_e32 v150, v140
	v_pk_add_f32 v[148:149], v[148:149], v[150:151]
	v_mov_b32_e32 v150, v144
	v_add_f32_e32 v188, v148, v149
	v_mov_b32_e32 v148, v145
	v_mov_b32_e32 v149, v146
	v_mov_b32_e32 v151, v147
	v_pk_add_f32 v[148:149], v[148:149], v[150:151]
	v_mov_b32_e32 v236, v188
	v_mov_b32_e32 v237, v188
	s_nop 1
	v_permlane16_swap_b32_e32 v236, v237
	v_cndmask_b32_e64 v190, v237, v236, s[98:99]
	v_add_f32_e32 v148, v148, v149
	v_mov_b32_e32 v236, v148
	v_mov_b32_e32 v237, v148
	s_nop 1
	v_permlane16_swap_b32_e32 v236, v237
	v_cndmask_b32_e64 v149, v237, v236, s[98:99]
	s_waitcnt lgkmcnt(2)
	v_add_f32_e32 v183, v183, v185
	v_mov_b32_e32 v150, v132
	s_waitcnt lgkmcnt(1)
	v_add_f32_e32 v185, v188, v190
	v_mov_b32_e32 v151, v135
	s_waitcnt lgkmcnt(0)
	v_add_f32_e32 v188, v148, v149
	v_mov_b32_e32 v148, v133
	v_mov_b32_e32 v149, v134
	v_pk_add_f32 v[148:149], v[148:149], v[150:151]
	v_mov_b32_e32 v150, v136
	v_add_f32_e32 v191, v148, v149
	v_mov_b32_e32 v148, v137
	v_mov_b32_e32 v149, v138
	v_mov_b32_e32 v151, v139
	v_pk_add_f32 v[148:149], v[148:149], v[150:151]
	v_mov_b32_e32 v150, v128
	v_add_f32_e32 v194, v148, v149
	v_mov_b32_e32 v148, v129
	v_mov_b32_e32 v149, v130
	v_mov_b32_e32 v151, v131
	v_pk_add_f32 v[148:149], v[148:149], v[150:151]
	v_mov_b32_e32 v236, v172
	v_mov_b32_e32 v237, v172
	s_nop 1
	v_permlane32_swap_b32_e32 v236, v237
	v_cndmask_b32_e64 v187, v237, v236, s[100:101]
	v_add_f32_e32 v148, v148, v149
	v_mov_b32_e32 v236, v148
	v_mov_b32_e32 v237, v148
	s_nop 1
	v_permlane16_swap_b32_e32 v236, v237
	v_cndmask_b32_e64 v149, v237, v236, s[98:99]
	v_mov_b32_e32 v236, v191
	v_mov_b32_e32 v237, v191
	s_nop 1
	v_permlane16_swap_b32_e32 v236, v237
	v_cndmask_b32_e64 v192, v237, v236, s[98:99]
	v_mov_b32_e32 v236, v194
	v_mov_b32_e32 v237, v194
	s_nop 1
	v_permlane16_swap_b32_e32 v236, v237
	v_cndmask_b32_e64 v203, v237, v236, s[98:99]
	s_waitcnt lgkmcnt(3)
	v_add_f32_e32 v172, v172, v187
	v_mov_b32_e32 v236, v185
	v_mov_b32_e32 v237, v185
	s_nop 1
	v_permlane32_swap_b32_e32 v236, v237
	v_cndmask_b32_e64 v187, v237, v236, s[100:101]
	s_waitcnt lgkmcnt(3)
; __device__ __forceinline__ unsigned cvt_pk_bf16(float lo, float hi) { unsigned r; asm volatile("v_cvt_pk_bf16_f32 %0, %1, %2" : "=v"(r) : "v"(lo), "v"(hi)); return r; }
; template <int NP> __device__ __forceinline__ void load_rs(const float* ssp, int row0, int fq, float (&rs)[2][4]) {
;     ...
;             for (int m = 0; m < 4; ++m) { float s = (p[ai][m][0] + p[ai][m][1]) + (p[ai][m][2] + p[ai][m][3]); s += __shfl_xor(s, 16); s += __shfl_xor(s, 32); rs[ai][m] = s; }
;     }
; #pragma unroll
;     for (int ai = 0; ai < 2; ++ai)
; #pragma unroll
;         for (int m = 0; m < 4; ++m) rs[ai][m] = __builtin_amdgcn_rsqf(rs[ai][m] * (1.0f / D_MODEL) + RMS_EPS);
;     template <bool GATE> __device__ __forceinline__ void body(const f32x4 (&acc)[2][2][4][2], const Unit& u, int wr, int wc, int fr, int fq) const {
;     ...
;                 const int row = row0 + ai * HALF + m * 16; const float r = rs[ai][m], nrl = r * -1.44269504089f;
; #pragma unroll
;                 for (int bj = 0; bj < 2; ++bj) {
;                     unsigned pk[4];
; #pragma unroll
;                     for (int q = 0; q < 4; ++q) {
;                         const f32x4 va = acc[ai][bj][m][q >> 1]; const int e0 = 2 * (q & 1);
;                         const f32x2 v = (f32x2){va[e0], va[e0 + 1]};
;                         f32x2 o;
;                         if (GATE) { const f32x2 t = v * nrl; f32x2 ex; ex.x = __builtin_amdgcn_exp2f(t.x); ex.y = __builtin_amdgcn_exp2f(t.y);
;                             const f32x2 d = ex + 1.0f; o.x = __builtin_amdgcn_rcpf(d.x); o.y = __builtin_amdgcn_rcpf(d.y); }
;                         else o = v * r;
;                         pk[q] = cvt_pk_bf16(o.x, o.y);
;                     }
;                     u32x4 w; w.x = pk[0]; w.y = pk[1]; w.z = pk[2]; w.w = pk[3];
;                     *(u32x4*)(P + (size_t)row * PITCH + col0 + bj * HALF) = w;
	v_add_f32_e32 v148, v148, v149
	v_mov_b32_e32 v236, v148
	v_mov_b32_e32 v237, v148
	s_nop 1
	v_permlane32_swap_b32_e32 v236, v237
	v_cndmask_b32_e64 v149, v237, v236, s[100:101]
	v_mov_b32_e32 v236, v188
	v_mov_b32_e32 v237, v188
	s_nop 1
	v_permlane32_swap_b32_e32 v236, v237
	v_cndmask_b32_e64 v190, v237, v236, s[100:101]
	s_waitcnt lgkmcnt(4)
	v_add_f32_e32 v150, v191, v192
	v_mov_b32_e32 v236, v150
	v_mov_b32_e32 v237, v150
	s_nop 1
	v_permlane32_swap_b32_e32 v236, v237
	v_cndmask_b32_e64 v151, v237, v236, s[100:101]
	s_waitcnt lgkmcnt(4)
	v_add_f32_e32 v191, v194, v203
	v_mov_b32_e32 v236, v191
	v_mov_b32_e32 v237, v191
	s_nop 1
	v_permlane32_swap_b32_e32 v236, v237
	v_cndmask_b32_e64 v192, v237, v236, s[100:101]
	s_waitcnt lgkmcnt(3)
	v_add_f32_e32 v148, v148, v149
	v_fmamk_f32 v149, v173, 0x3a800000, v202
	v_rsq_f32_e32 v208, v149
	v_fmamk_f32 v149, v183, 0x3a800000, v202
	v_add_f32_e32 v185, v185, v187
	v_rsq_f32_e32 v210, v149
	v_fmamk_f32 v149, v172, 0x3a800000, v202
	s_waitcnt lgkmcnt(2)
	v_add_f32_e32 v187, v188, v190
	v_rsq_f32_e32 v212, v149
	v_fmamk_f32 v149, v185, 0x3a800000, v202
	s_waitcnt lgkmcnt(1)
	v_add_f32_e32 v150, v150, v151
	v_rsq_f32_e32 v214, v149
	v_fmamk_f32 v149, v187, 0x3a800000, v202
	s_waitcnt lgkmcnt(0)
	v_add_f32_e32 v151, v191, v192
	v_rsq_f32_e32 v194, v149
	v_fmamk_f32 v149, v150, 0x3a800000, v202
	v_rsq_f32_e32 v192, v149
	v_fmamk_f32 v149, v151, 0x3a800000, v202
	v_fmamk_f32 v148, v148, 0x3a800000, v202
	v_rsq_f32_e32 v190, v149
	v_rsq_f32_e32 v188, v148
	v_pk_mul_f32 v[148:149], v[124:125], v[208:209] op_sel_hi:[1,0]
	v_readlane_b32 s2, v235, 44
	v_cvt_pk_bf16_f32 v204, v148, v149
	v_pk_mul_f32 v[148:149], v[126:127], v[208:209] op_sel_hi:[1,0]
	v_readlane_b32 s3, v235, 45
	v_cvt_pk_bf16_f32 v205, v148, v149
	v_pk_mul_f32 v[148:149], v[120:121], v[208:209] op_sel_hi:[1,0]
	v_ashrrev_i32_e32 v173, 31, v160
	v_cvt_pk_bf16_f32 v206, v148, v149
	v_pk_mul_f32 v[148:149], v[122:123], v[208:209] op_sel_hi:[1,0]
	v_mov_b32_e32 v172, v160
	v_cvt_pk_bf16_f32 v207, v148, v149
	v_mov_b64_e32 v[148:149], s[2:3]
	v_mad_i64_i32 v[216:217], s[2:3], v186, s41, v[148:149]
	v_lshlrev_b64 v[150:151], 1, v[172:173]
	v_lshl_add_u64 v[216:217], v[216:217], 0, v[150:151]
	global_store_dwordx4 v[216:217], v[204:207], off
	s_nop 1
	v_pk_mul_f32 v[204:205], v[116:117], v[208:209] op_sel_hi:[1,0]
	v_pk_mul_f32 v[206:207], v[118:119], v[208:209] op_sel_hi:[1,0]
	v_cvt_pk_bf16_f32 v204, v204, v205
	s_nop 0
	v_cvt_pk_bf16_f32 v205, v206, v207
	v_pk_mul_f32 v[206:207], v[112:113], v[208:209] op_sel_hi:[1,0]
	v_pk_mul_f32 v[208:209], v[114:115], v[208:209] op_sel_hi:[1,0]
	v_cvt_pk_bf16_f32 v206, v206, v207
	s_nop 0
	v_cvt_pk_bf16_f32 v207, v208, v209
	global_store_dwordx4 v[216:217], v[204:207], off offset:256
	v_pk_mul_f32 v[208:209], v[106:107], v[210:211] op_sel_hi:[1,0]
	s_nop 0
	v_pk_mul_f32 v[204:205], v[108:109], v[210:211] op_sel_hi:[1,0]
	v_pk_mul_f32 v[206:207], v[110:111], v[210:211] op_sel_hi:[1,0]
	v_cvt_pk_bf16_f32 v204, v204, v205
	s_nop 0
	v_cvt_pk_bf16_f32 v205, v206, v207
	v_pk_mul_f32 v[206:207], v[104:105], v[210:211] op_sel_hi:[1,0]
	s_nop 0
	v_cvt_pk_bf16_f32 v206, v206, v207
	v_cvt_pk_bf16_f32 v207, v208, v209
	v_mad_i64_i32 v[208:209], s[2:3], v184, s41, v[148:149]
	v_lshl_add_u64 v[208:209], v[208:209], 0, v[150:151]
	global_store_dwordx4 v[208:209], v[204:207], off
	s_nop 1
	v_pk_mul_f32 v[204:205], v[100:101], v[210:211] op_sel_hi:[1,0]
	v_pk_mul_f32 v[206:207], v[102:103], v[210:211] op_sel_hi:[1,0]
	v_cvt_pk_bf16_f32 v204, v204, v205
	s_nop 0
	v_cvt_pk_bf16_f32 v205, v206, v207
	v_pk_mul_f32 v[206:207], v[96:97], v[210:211] op_sel_hi:[1,0]
	v_pk_mul_f32 v[210:211], v[98:99], v[210:211] op_sel_hi:[1,0]
	v_cvt_pk_bf16_f32 v206, v206, v207
	s_nop 0
	v_cvt_pk_bf16_f32 v207, v210, v211
	global_store_dwordx4 v[208:209], v[204:207], off offset:256
	v_pk_mul_f32 v[208:209], v[90:91], v[212:213] op_sel_hi:[1,0]
	v_pk_mul_f32 v[210:211], v[82:83], v[212:213] op_sel_hi:[1,0]
	v_pk_mul_f32 v[204:205], v[92:93], v[212:213] op_sel_hi:[1,0]
	v_pk_mul_f32 v[206:207], v[94:95], v[212:213] op_sel_hi:[1,0]
	v_cvt_pk_bf16_f32 v204, v204, v205
	s_nop 0
	v_cvt_pk_bf16_f32 v205, v206, v207
	v_pk_mul_f32 v[206:207], v[88:89], v[212:213] op_sel_hi:[1,0]
	s_nop 0
	v_cvt_pk_bf16_f32 v206, v206, v207
	v_cvt_pk_bf16_f32 v207, v208, v209
	v_mad_i64_i32 v[208:209], s[2:3], v182, s41, v[148:149]
	v_lshl_add_u64 v[208:209], v[208:209], 0, v[150:151]
	global_store_dwordx4 v[208:209], v[204:207], off
	s_nop 1
	v_pk_mul_f32 v[204:205], v[84:85], v[212:213] op_sel_hi:[1,0]
	v_pk_mul_f32 v[206:207], v[86:87], v[212:213] op_sel_hi:[1,0]
	v_cvt_pk_bf16_f32 v204, v204, v205
	s_nop 0
	v_cvt_pk_bf16_f32 v205, v206, v207
	v_pk_mul_f32 v[206:207], v[80:81], v[212:213] op_sel_hi:[1,0]
	s_nop 0
	v_cvt_pk_bf16_f32 v206, v206, v207
	v_cvt_pk_bf16_f32 v207, v210, v211
	global_store_dwordx4 v[208:209], v[204:207], off offset:256
	v_pk_mul_f32 v[208:209], v[74:75], v[214:215] op_sel_hi:[1,0]
	v_pk_mul_f32 v[210:211], v[66:67], v[214:215] op_sel_hi:[1,0]
	v_pk_mul_f32 v[204:205], v[76:77], v[214:215] op_sel_hi:[1,0]
; __device__ __forceinline__ unsigned cvt_pk_bf16(float lo, float hi) { unsigned r; asm volatile("v_cvt_pk_bf16_f32 %0, %1, %2" : "=v"(r) : "v"(lo), "v"(hi)); return r; }
;     template <bool GATE> __device__ __forceinline__ void body(const f32x4 (&acc)[2][2][4][2], const Unit& u, int wr, int wc, int fr, int fq) const {
;     ...
;                         const f32x4 va = acc[ai][bj][m][q >> 1]; const int e0 = 2 * (q & 1);
;                         const f32x2 v = (f32x2){va[e0], va[e0 + 1]};
;                         f32x2 o;
;                         if (GATE) { const f32x2 t = v * nrl; f32x2 ex; ex.x = __builtin_amdgcn_exp2f(t.x); ex.y = __builtin_amdgcn_exp2f(t.y);
;                             const f32x2 d = ex + 1.0f; o.x = __builtin_amdgcn_rcpf(d.x); o.y = __builtin_amdgcn_rcpf(d.y); }
;                         else o = v * r;
;                         pk[q] = cvt_pk_bf16(o.x, o.y);
;                     }
;                     u32x4 w; w.x = pk[0]; w.y = pk[1]; w.z = pk[2]; w.w = pk[3];
;                     *(u32x4*)(P + (size_t)row * PITCH + col0 + bj * HALF) = w;
	v_pk_mul_f32 v[206:207], v[78:79], v[214:215] op_sel_hi:[1,0]
	v_cvt_pk_bf16_f32 v204, v204, v205
	s_nop 0
	v_cvt_pk_bf16_f32 v205, v206, v207
	v_pk_mul_f32 v[206:207], v[72:73], v[214:215] op_sel_hi:[1,0]
	s_nop 0
	v_cvt_pk_bf16_f32 v206, v206, v207
	v_cvt_pk_bf16_f32 v207, v208, v209
	v_mad_i64_i32 v[208:209], s[2:3], v180, s41, v[148:149]
	v_lshl_add_u64 v[208:209], v[208:209], 0, v[150:151]
	global_store_dwordx4 v[208:209], v[204:207], off
	s_nop 1
	v_pk_mul_f32 v[204:205], v[68:69], v[214:215] op_sel_hi:[1,0]
	v_pk_mul_f32 v[206:207], v[70:71], v[214:215] op_sel_hi:[1,0]
	v_cvt_pk_bf16_f32 v204, v204, v205
	s_nop 0
	v_cvt_pk_bf16_f32 v205, v206, v207
	v_pk_mul_f32 v[206:207], v[64:65], v[214:215] op_sel_hi:[1,0]
	s_nop 0
	v_cvt_pk_bf16_f32 v206, v206, v207
	v_cvt_pk_bf16_f32 v207, v210, v211
	global_store_dwordx4 v[208:209], v[204:207], off offset:256
	v_pk_mul_f32 v[208:209], v[58:59], v[194:195] op_sel_hi:[1,0]
	v_pk_mul_f32 v[210:211], v[50:51], v[194:195] op_sel_hi:[1,0]
	v_pk_mul_f32 v[204:205], v[60:61], v[194:195] op_sel_hi:[1,0]
	v_pk_mul_f32 v[206:207], v[62:63], v[194:195] op_sel_hi:[1,0]
	v_cvt_pk_bf16_f32 v204, v204, v205
	s_nop 0
	v_cvt_pk_bf16_f32 v205, v206, v207
	v_pk_mul_f32 v[206:207], v[56:57], v[194:195] op_sel_hi:[1,0]
	s_nop 0
	v_cvt_pk_bf16_f32 v206, v206, v207
	v_cvt_pk_bf16_f32 v207, v208, v209
	v_mad_i64_i32 v[208:209], s[2:3], v178, s41, v[148:149]
	v_lshl_add_u64 v[208:209], v[208:209], 0, v[150:151]
	global_store_dwordx4 v[208:209], v[204:207], off
	s_nop 1
	v_pk_mul_f32 v[204:205], v[52:53], v[194:195] op_sel_hi:[1,0]
	v_pk_mul_f32 v[206:207], v[54:55], v[194:195] op_sel_hi:[1,0]
	v_cvt_pk_bf16_f32 v204, v204, v205
	s_nop 0
	v_cvt_pk_bf16_f32 v205, v206, v207
	v_pk_mul_f32 v[206:207], v[48:49], v[194:195] op_sel_hi:[1,0]
	s_nop 0
	v_cvt_pk_bf16_f32 v206, v206, v207
	v_cvt_pk_bf16_f32 v207, v210, v211
	global_store_dwordx4 v[208:209], v[204:207], off offset:256
	v_pk_mul_f32 v[208:209], v[42:43], v[192:193] op_sel_hi:[1,0]
	v_pk_mul_f32 v[210:211], v[34:35], v[192:193] op_sel_hi:[1,0]
	v_pk_mul_f32 v[204:205], v[44:45], v[192:193] op_sel_hi:[1,0]
	v_pk_mul_f32 v[206:207], v[46:47], v[192:193] op_sel_hi:[1,0]
	v_cvt_pk_bf16_f32 v204, v204, v205
	s_nop 0
	v_cvt_pk_bf16_f32 v205, v206, v207
	v_pk_mul_f32 v[206:207], v[40:41], v[192:193] op_sel_hi:[1,0]
	s_nop 0
	v_cvt_pk_bf16_f32 v206, v206, v207
	v_cvt_pk_bf16_f32 v207, v208, v209
	v_mad_i64_i32 v[208:209], s[2:3], v176, s41, v[148:149]
	v_lshl_add_u64 v[208:209], v[208:209], 0, v[150:151]
	global_store_dwordx4 v[208:209], v[204:207], off
	s_nop 1
	v_pk_mul_f32 v[204:205], v[36:37], v[192:193] op_sel_hi:[1,0]
	v_pk_mul_f32 v[206:207], v[38:39], v[192:193] op_sel_hi:[1,0]
	v_cvt_pk_bf16_f32 v204, v204, v205
	s_nop 0
	v_cvt_pk_bf16_f32 v205, v206, v207
	v_pk_mul_f32 v[206:207], v[32:33], v[192:193] op_sel_hi:[1,0]
	s_nop 0
	v_cvt_pk_bf16_f32 v206, v206, v207
	v_cvt_pk_bf16_f32 v207, v210, v211
	global_store_dwordx4 v[208:209], v[204:207], off offset:256
	v_pk_mul_f32 v[208:209], v[26:27], v[190:191] op_sel_hi:[1,0]
	s_nop 0
	v_pk_mul_f32 v[204:205], v[28:29], v[190:191] op_sel_hi:[1,0]
	v_pk_mul_f32 v[206:207], v[30:31], v[190:191] op_sel_hi:[1,0]
	v_cvt_pk_bf16_f32 v204, v204, v205
	s_nop 0
	v_cvt_pk_bf16_f32 v205, v206, v207
	v_pk_mul_f32 v[206:207], v[24:25], v[190:191] op_sel_hi:[1,0]
	s_nop 0
	v_cvt_pk_bf16_f32 v206, v206, v207
	v_cvt_pk_bf16_f32 v207, v208, v209
	v_mad_i64_i32 v[208:209], s[2:3], v174, s41, v[148:149]
	v_lshl_add_u64 v[208:209], v[208:209], 0, v[150:151]
	global_store_dwordx4 v[208:209], v[204:207], off
	v_mad_i64_i32 v[148:149], s[2:3], v170, s41, v[148:149]
	s_nop 0
	v_pk_mul_f32 v[204:205], v[20:21], v[190:191] op_sel_hi:[1,0]
	v_pk_mul_f32 v[206:207], v[22:23], v[190:191] op_sel_hi:[1,0]
	v_cvt_pk_bf16_f32 v204, v204, v205
	v_lshl_add_u64 v[148:149], v[148:149], 0, v[150:151]
	v_cvt_pk_bf16_f32 v205, v206, v207
	v_pk_mul_f32 v[206:207], v[16:17], v[190:191] op_sel_hi:[1,0]
	v_pk_mul_f32 v[190:191], v[18:19], v[190:191] op_sel_hi:[1,0]
	v_cvt_pk_bf16_f32 v206, v206, v207
	v_pk_mul_f32 v[150:151], v[6:7], v[188:189] op_sel_hi:[1,0]
	v_cvt_pk_bf16_f32 v207, v190, v191
	global_store_dwordx4 v[208:209], v[204:207], off offset:256
	v_pk_mul_f32 v[208:209], v[10:11], v[188:189] op_sel_hi:[1,0]
	v_mad_i64_i32 v[190:191], s[2:3], v170, s41, 0
	v_pk_mul_f32 v[204:205], v[12:13], v[188:189] op_sel_hi:[1,0]
	v_pk_mul_f32 v[206:207], v[14:15], v[188:189] op_sel_hi:[1,0]
	v_cvt_pk_bf16_f32 v204, v204, v205
	s_nop 0
	v_cvt_pk_bf16_f32 v205, v206, v207
	v_pk_mul_f32 v[206:207], v[8:9], v[188:189] op_sel_hi:[1,0]
	s_nop 0
	v_cvt_pk_bf16_f32 v206, v206, v207
	v_cvt_pk_bf16_f32 v207, v208, v209
	global_store_dwordx4 v[148:149], v[204:207], off
	v_pk_mul_f32 v[148:149], v[4:5], v[188:189] op_sel_hi:[1,0]
	s_nop 0
	v_cvt_pk_bf16_f32 v148, v148, v149
	v_cvt_pk_bf16_f32 v149, v150, v151
	v_pk_mul_f32 v[150:151], v[0:1], v[188:189] op_sel_hi:[1,0]
	v_pk_mul_f32 v[204:205], v[2:3], v[188:189] op_sel_hi:[1,0]
	v_cvt_pk_bf16_f32 v150, v150, v151
	s_nop 0
	v_cvt_pk_bf16_f32 v151, v204, v205
	s_cbranch_execz .LBB0_385
	s_branch .LBB0_386

; template <int NP> __device__ __forceinline__ void load_rs(const float* ssp, int row0, int fq, float (&rs)[2][4]) {
;     ...
;             for (int m = 0; m < 4; ++m) { float s = (p[ai][m][0] + p[ai][m][1]) + (p[ai][m][2] + p[ai][m][3]); s += __shfl_xor(s, 16); s += __shfl_xor(s, 32); rs[ai][m] = s; }
;     }
; #pragma unroll
;     for (int ai = 0; ai < 2; ++ai)
; #pragma unroll
;         for (int m = 0; m < 4; ++m) rs[ai][m] = __builtin_amdgcn_rsqf(rs[ai][m] * (1.0f / D_MODEL) + RMS_EPS);
;     template <bool GATE> __device__ __forceinline__ void body(const f32x4 (&acc)[2][2][4][2], const Unit& u, int wr, int wc, int fr, int fq) const {
;     ...
;                         if (GATE) { const f32x2 t = v * nrl; f32x2 ex; ex.x = __builtin_amdgcn_exp2f(t.x); ex.y = __builtin_amdgcn_exp2f(t.y);
;                             const f32x2 d = ex + 1.0f; o.x = __builtin_amdgcn_rcpf(d.x); o.y = __builtin_amdgcn_rcpf(d.y); }
.LBB0_385:
	v_mov_b32_e32 v236, v177
	v_mov_b32_e32 v237, v177
	s_nop 1
	v_permlane16_swap_b32_e32 v236, v237
	v_cndmask_b32_e64 v150, v237, v236, s[98:99]
	v_mov_b32_e32 v148, v141
	v_mov_b32_e32 v149, v142
	v_mov_b32_e32 v236, v179
	v_mov_b32_e32 v237, v179
	s_nop 1
	v_permlane16_swap_b32_e32 v236, v237
	v_cndmask_b32_e64 v151, v237, v236, s[98:99]
	v_mov_b32_e32 v236, v181
	v_mov_b32_e32 v237, v181
	s_nop 1
	v_permlane16_swap_b32_e32 v236, v237
	v_cndmask_b32_e64 v183, v237, v236, s[98:99]
	s_waitcnt lgkmcnt(2)
	v_add_f32_e32 v141, v177, v150
	v_mov_b32_e32 v236, v141
	v_mov_b32_e32 v237, v141
	s_nop 1
	v_permlane32_swap_b32_e32 v236, v237
	v_cndmask_b32_e64 v142, v237, v236, s[100:101]
	v_readlane_b32 s2, v235, 44
	s_waitcnt lgkmcnt(2)
	v_add_f32_e32 v150, v179, v151
	v_mov_b32_e32 v236, v150
	v_mov_b32_e32 v237, v150
	s_nop 1
	v_permlane32_swap_b32_e32 v236, v237
	v_cndmask_b32_e64 v177, v237, v236, s[100:101]
	s_waitcnt lgkmcnt(2)
	v_add_f32_e32 v151, v181, v183
	s_waitcnt lgkmcnt(1)
	v_add_f32_e32 v142, v141, v142
	v_mov_b32_e32 v141, v143
	v_pk_add_f32 v[140:141], v[148:149], v[140:141]
	v_mov_b32_e32 v236, v151
	v_mov_b32_e32 v237, v151
	s_nop 1
	v_permlane32_swap_b32_e32 v236, v237
	v_cndmask_b32_e64 v179, v237, v236, s[100:101]
	v_add_f32_e32 v143, v140, v141
	v_mov_b32_e32 v140, v145
	v_mov_b32_e32 v141, v146
	v_mov_b32_e32 v145, v147
	v_pk_add_f32 v[140:141], v[140:141], v[144:145]
	v_mov_b32_e32 v236, v143
	v_mov_b32_e32 v237, v143
	s_nop 1
	v_permlane16_swap_b32_e32 v236, v237
	v_cndmask_b32_e64 v148, v237, v236, s[98:99]
	v_add_f32_e32 v140, v140, v141
	v_mov_b32_e32 v236, v140
	v_mov_b32_e32 v237, v140
	s_nop 1
	v_permlane16_swap_b32_e32 v236, v237
	v_cndmask_b32_e64 v141, v237, v236, s[98:99]
	s_waitcnt lgkmcnt(3)
	v_add_f32_e32 v144, v150, v177
	s_waitcnt lgkmcnt(2)
	v_add_f32_e32 v145, v151, v179
	s_waitcnt lgkmcnt(1)
	v_add_f32_e32 v143, v143, v148
	v_mov_b32_e32 v236, v143
	v_mov_b32_e32 v237, v143
	s_nop 1
	v_permlane32_swap_b32_e32 v236, v237
	v_cndmask_b32_e64 v146, v237, v236, s[100:101]
	s_waitcnt lgkmcnt(1)
	v_add_f32_e32 v147, v140, v141
	v_mov_b32_e32 v140, v133
	v_mov_b32_e32 v141, v134
	v_mov_b32_e32 v133, v135
	v_pk_add_f32 v[132:133], v[140:141], v[132:133]
	v_mov_b32_e32 v236, v147
	v_mov_b32_e32 v237, v147
	s_nop 1
	v_permlane32_swap_b32_e32 v236, v237
	v_cndmask_b32_e64 v148, v237, v236, s[100:101]
	v_add_f32_e32 v134, v132, v133
	v_mov_b32_e32 v132, v137
	v_mov_b32_e32 v133, v138
	v_mov_b32_e32 v137, v139
	v_pk_add_f32 v[132:133], v[132:133], v[136:137]
	v_mov_b32_e32 v236, v134
	v_mov_b32_e32 v237, v134
	s_nop 1
	v_permlane16_swap_b32_e32 v236, v237
	v_cndmask_b32_e64 v135, v237, v236, s[98:99]
	v_add_f32_e32 v136, v132, v133
	v_mov_b32_e32 v132, v129
	v_mov_b32_e32 v133, v130
	v_mov_b32_e32 v129, v131
	v_pk_add_f32 v[128:129], v[132:133], v[128:129]
	v_mov_b32_e32 v236, v136
	v_mov_b32_e32 v237, v136
	s_nop 1
	v_permlane16_swap_b32_e32 v236, v237
	v_cndmask_b32_e64 v137, v237, v236, s[98:99]
	v_add_f32_e32 v128, v128, v129
	v_mov_b32_e32 v236, v128
	v_mov_b32_e32 v237, v128
	s_nop 1
	v_permlane16_swap_b32_e32 v236, v237
	v_cndmask_b32_e64 v129, v237, v236, s[98:99]
	s_waitcnt lgkmcnt(2)
	v_add_f32_e32 v130, v134, v135
	v_mov_b32_e32 v236, v130
	v_mov_b32_e32 v237, v130
	s_nop 1
	v_permlane32_swap_b32_e32 v236, v237
	v_cndmask_b32_e64 v131, v237, v236, s[100:101]
	s_waitcnt lgkmcnt(2)
	v_add_f32_e32 v132, v136, v137
	v_mov_b32_e32 v236, v132
	v_mov_b32_e32 v237, v132
	s_nop 1
	v_permlane32_swap_b32_e32 v236, v237
	v_cndmask_b32_e64 v133, v237, v236, s[100:101]
	s_waitcnt lgkmcnt(2)
	v_add_f32_e32 v128, v128, v129
	v_mov_b32_e32 v236, v128
	v_mov_b32_e32 v237, v128
	s_nop 1
	v_permlane32_swap_b32_e32 v236, v237
	v_cndmask_b32_e64 v129, v237, v236, s[100:101]
	s_waitcnt lgkmcnt(2)
	v_add_f32_e32 v130, v130, v131
	v_add_f32_e32 v134, v143, v146
	s_waitcnt lgkmcnt(1)
	v_add_f32_e32 v131, v132, v133
	v_add_f32_e32 v135, v147, v148
	s_waitcnt lgkmcnt(0)
	v_add_f32_e32 v128, v128, v129
	v_fmamk_f32 v129, v142, 0x3a800000, v202
	v_rsq_f32_e32 v132, v129
	v_fmamk_f32 v129, v144, 0x3a800000, v202
	v_rsq_f32_e32 v133, v129
	v_fmamk_f32 v129, v145, 0x3a800000, v202
	v_mul_f32_e32 v132, 0xbfb8aa3b, v132
	v_rsq_f32_e32 v136, v129
	v_pk_mul_f32 v[124:125], v[124:125], v[132:133] op_sel_hi:[1,0]
	v_pk_mul_f32 v[120:121], v[120:121], v[132:133] op_sel_hi:[1,0]
	v_exp_f32_e32 v124, v124
	v_exp_f32_e32 v125, v125
	v_pk_mul_f32 v[126:127], v[126:127], v[132:133] op_sel_hi:[1,0]
	v_exp_f32_e32 v120, v120
	v_exp_f32_e32 v121, v121
	v_pk_mul_f32 v[122:123], v[122:123], v[132:133] op_sel_hi:[1,0]
	v_exp_f32_e32 v126, v126
	v_exp_f32_e32 v127, v127
	v_exp_f32_e32 v122, v122
	v_exp_f32_e32 v123, v123
	v_fmamk_f32 v129, v134, 0x3a800000, v202
	v_rsq_f32_e32 v137, v129
	v_fmamk_f32 v129, v135, 0x3a800000, v202
	v_rsq_f32_e32 v138, v129
	v_fmamk_f32 v129, v130, 0x3a800000, v202
	v_pk_add_f32 v[124:125], v[124:125], 1.0 op_sel_hi:[1,0]
	v_pk_add_f32 v[120:121], v[120:121], 1.0 op_sel_hi:[1,0]
	v_pk_mul_f32 v[116:117], v[116:117], v[132:133] op_sel_hi:[1,0]
	v_pk_mul_f32 v[112:113], v[112:113], v[132:133] op_sel_hi:[1,0]
	v_rsq_f32_e32 v130, v129
	v_fmamk_f32 v129, v131, 0x3a800000, v202
	v_rcp_f32_e32 v131, v124
	v_rcp_f32_e32 v134, v125
	v_pk_add_f32 v[124:125], v[126:127], 1.0 op_sel_hi:[1,0]
	v_rcp_f32_e32 v127, v120
	v_rcp_f32_e32 v135, v121
	v_pk_add_f32 v[120:121], v[122:123], 1.0 op_sel_hi:[1,0]
	v_exp_f32_e32 v116, v116
	v_exp_f32_e32 v117, v117
	v_pk_mul_f32 v[118:119], v[118:119], v[132:133] op_sel_hi:[1,0]
	v_exp_f32_e32 v112, v112
	v_exp_f32_e32 v113, v113
	v_pk_mul_f32 v[114:115], v[114:115], v[132:133] op_sel_hi:[1,0]
; __device__ __forceinline__ unsigned cvt_pk_bf16(float lo, float hi) { unsigned r; asm volatile("v_cvt_pk_bf16_f32 %0, %1, %2" : "=v"(r) : "v"(lo), "v"(hi)); return r; }
;     template <bool GATE> __device__ __forceinline__ void body(const f32x4 (&acc)[2][2][4][2], const Unit& u, int wr, int wc, int fr, int fq) const {
;     ...
;                 const int row = row0 + ai * HALF + m * 16; const float r = rs[ai][m], nrl = r * -1.44269504089f;
; #pragma unroll
;                 for (int bj = 0; bj < 2; ++bj) {
;                     unsigned pk[4];
; #pragma unroll
;                     for (int q = 0; q < 4; ++q) {
;                         const f32x4 va = acc[ai][bj][m][q >> 1]; const int e0 = 2 * (q & 1);
;                         const f32x2 v = (f32x2){va[e0], va[e0 + 1]};
;                         f32x2 o;
;                         if (GATE) { const f32x2 t = v * nrl; f32x2 ex; ex.x = __builtin_amdgcn_exp2f(t.x); ex.y = __builtin_amdgcn_exp2f(t.y);
;                             const f32x2 d = ex + 1.0f; o.x = __builtin_amdgcn_rcpf(d.x); o.y = __builtin_amdgcn_rcpf(d.y); }
;                         else o = v * r;
;                         pk[q] = cvt_pk_bf16(o.x, o.y);
;                     }
;                     u32x4 w; w.x = pk[0]; w.y = pk[1]; w.z = pk[2]; w.w = pk[3];
;                     *(u32x4*)(P + (size_t)row * PITCH + col0 + bj * HALF) = w;
	v_rcp_f32_e32 v126, v124
	v_rcp_f32_e32 v125, v125
	v_rcp_f32_e32 v120, v120
	v_rcp_f32_e32 v121, v121
	v_readlane_b32 s3, v235, 45
	v_exp_f32_e32 v118, v118
	v_exp_f32_e32 v119, v119
	v_exp_f32_e32 v114, v114
	v_exp_f32_e32 v115, v115
	v_cvt_pk_bf16_f32 v124, v131, v134
	v_cvt_pk_bf16_f32 v125, v126, v125
	v_cvt_pk_bf16_f32 v126, v127, v135
	v_cvt_pk_bf16_f32 v127, v120, v121
	v_mov_b64_e32 v[120:121], s[2:3]
	v_mad_i64_i32 v[134:135], s[2:3], v186, s41, v[120:121]
	v_lshlrev_b64 v[122:123], 1, v[160:161]
	v_lshl_add_u64 v[134:135], v[134:135], 0, v[122:123]
	v_pk_add_f32 v[116:117], v[116:117], 1.0 op_sel_hi:[1,0]
	v_pk_add_f32 v[112:113], v[112:113], 1.0 op_sel_hi:[1,0]
	global_store_dwordx4 v[134:135], v[124:127], off
	v_rsq_f32_e32 v129, v129
	v_fmamk_f32 v128, v128, 0x3a800000, v202
	v_rcp_f32_e32 v124, v116
	v_rcp_f32_e32 v125, v117
	v_pk_add_f32 v[116:117], v[118:119], 1.0 op_sel_hi:[1,0]
	v_rcp_f32_e32 v118, v112
	v_rcp_f32_e32 v119, v113
	v_pk_add_f32 v[112:113], v[114:115], 1.0 op_sel_hi:[1,0]
	v_rcp_f32_e32 v116, v116
	v_rcp_f32_e32 v115, v112
	v_cvt_pk_bf16_f32 v112, v124, v125
	v_rcp_f32_e32 v117, v117
	v_rcp_f32_e32 v126, v113
	v_cvt_pk_bf16_f32 v113, v116, v117
	v_cvt_pk_bf16_f32 v114, v118, v119
	v_cvt_pk_bf16_f32 v115, v115, v126
	global_store_dwordx4 v[134:135], v[112:115], off offset:256
	v_rsq_f32_e32 v128, v128
	v_mad_i64_i32 v[190:191], s[2:3], v170, s41, 0
	v_mul_f32_e32 v112, 0xbfb8aa3b, v133
	v_pk_mul_f32 v[108:109], v[108:109], v[112:113] op_sel_hi:[1,0]
	v_pk_mul_f32 v[110:111], v[110:111], v[112:113] op_sel_hi:[1,0]
	v_exp_f32_e32 v108, v108
	v_exp_f32_e32 v109, v109
	v_exp_f32_e32 v110, v110
	v_exp_f32_e32 v111, v111
	v_pk_add_f32 v[108:109], v[108:109], 1.0 op_sel_hi:[1,0]
	s_nop 0
	v_rcp_f32_e32 v113, v108
	v_rcp_f32_e32 v114, v109
	v_pk_add_f32 v[108:109], v[110:111], 1.0 op_sel_hi:[1,0]
	v_pk_mul_f32 v[104:105], v[104:105], v[112:113] op_sel_hi:[1,0]
	s_nop 0
	v_exp_f32_e32 v104, v104
	v_exp_f32_e32 v105, v105
	v_pk_mul_f32 v[106:107], v[106:107], v[112:113] op_sel_hi:[1,0]
	v_pk_mul_f32 v[100:101], v[100:101], v[112:113] op_sel_hi:[1,0]
	v_exp_f32_e32 v106, v106
	v_exp_f32_e32 v107, v107
	v_pk_mul_f32 v[96:97], v[96:97], v[112:113] op_sel_hi:[1,0]
	v_exp_f32_e32 v100, v100
	v_exp_f32_e32 v101, v101
	v_pk_mul_f32 v[102:103], v[102:103], v[112:113] op_sel_hi:[1,0]
	v_exp_f32_e32 v96, v96
	v_exp_f32_e32 v97, v97
	v_pk_mul_f32 v[98:99], v[98:99], v[112:113] op_sel_hi:[1,0]
	v_pk_add_f32 v[104:105], v[104:105], 1.0 op_sel_hi:[1,0]
	v_exp_f32_e32 v102, v102
	v_exp_f32_e32 v103, v103
	v_exp_f32_e32 v98, v98
	v_exp_f32_e32 v99, v99
	v_rcp_f32_e32 v108, v108
	v_rcp_f32_e32 v109, v109
	v_rcp_f32_e32 v110, v104
	v_rcp_f32_e32 v111, v105
	v_pk_add_f32 v[104:105], v[106:107], 1.0 op_sel_hi:[1,0]
	v_pk_add_f32 v[100:101], v[100:101], 1.0 op_sel_hi:[1,0]
	v_rcp_f32_e32 v107, v104
	v_rcp_f32_e32 v115, v105
	v_cvt_pk_bf16_f32 v104, v113, v114
	v_cvt_pk_bf16_f32 v105, v108, v109
	v_mad_i64_i32 v[108:109], s[2:3], v184, s41, v[120:121]
	v_lshl_add_u64 v[108:109], v[108:109], 0, v[122:123]
	v_pk_add_f32 v[96:97], v[96:97], 1.0 op_sel_hi:[1,0]
	v_cvt_pk_bf16_f32 v106, v110, v111
	v_cvt_pk_bf16_f32 v107, v107, v115
	global_store_dwordx4 v[108:109], v[104:107], off
	s_nop 1
	v_rcp_f32_e32 v104, v100
	v_rcp_f32_e32 v105, v101
	v_pk_add_f32 v[100:101], v[102:103], 1.0 op_sel_hi:[1,0]
	v_rcp_f32_e32 v102, v96
	v_rcp_f32_e32 v103, v97
	v_pk_add_f32 v[96:97], v[98:99], 1.0 op_sel_hi:[1,0]
	v_rcp_f32_e32 v100, v100
	v_rcp_f32_e32 v99, v96
	v_cvt_pk_bf16_f32 v96, v104, v105
	v_rcp_f32_e32 v101, v101
	v_rcp_f32_e32 v106, v97
	v_cvt_pk_bf16_f32 v97, v100, v101
	v_cvt_pk_bf16_f32 v98, v102, v103
	v_cvt_pk_bf16_f32 v99, v99, v106
	global_store_dwordx4 v[108:109], v[96:99], off offset:256
	s_nop 1
	v_mul_f32_e32 v96, 0xbfb8aa3b, v136
	v_pk_mul_f32 v[92:93], v[92:93], v[96:97] op_sel_hi:[1,0]
	v_pk_mul_f32 v[94:95], v[94:95], v[96:97] op_sel_hi:[1,0]
	v_exp_f32_e32 v92, v92
	v_exp_f32_e32 v93, v93
	v_exp_f32_e32 v94, v94
	v_exp_f32_e32 v95, v95
	v_pk_add_f32 v[92:93], v[92:93], 1.0 op_sel_hi:[1,0]
	s_nop 0
	v_rcp_f32_e32 v97, v92
	v_rcp_f32_e32 v98, v93
	v_pk_add_f32 v[92:93], v[94:95], 1.0 op_sel_hi:[1,0]
	v_pk_mul_f32 v[88:89], v[88:89], v[96:97] op_sel_hi:[1,0]
	s_nop 0
	v_exp_f32_e32 v88, v88
	v_exp_f32_e32 v89, v89
	v_pk_mul_f32 v[90:91], v[90:91], v[96:97] op_sel_hi:[1,0]
	v_pk_mul_f32 v[84:85], v[84:85], v[96:97] op_sel_hi:[1,0]
	v_exp_f32_e32 v90, v90
	v_exp_f32_e32 v91, v91
	v_pk_mul_f32 v[80:81], v[80:81], v[96:97] op_sel_hi:[1,0]
	v_exp_f32_e32 v84, v84
	v_exp_f32_e32 v85, v85
	v_pk_mul_f32 v[86:87], v[86:87], v[96:97] op_sel_hi:[1,0]
	v_exp_f32_e32 v80, v80
	v_exp_f32_e32 v81, v81
	v_pk_mul_f32 v[82:83], v[82:83], v[96:97] op_sel_hi:[1,0]
	v_pk_add_f32 v[88:89], v[88:89], 1.0 op_sel_hi:[1,0]
	v_exp_f32_e32 v86, v86
	v_exp_f32_e32 v87, v87
	v_exp_f32_e32 v82, v82
	v_exp_f32_e32 v83, v83
	v_rcp_f32_e32 v92, v92
	v_rcp_f32_e32 v93, v93
	v_rcp_f32_e32 v94, v88
	v_rcp_f32_e32 v95, v89
	v_pk_add_f32 v[88:89], v[90:91], 1.0 op_sel_hi:[1,0]
	v_pk_add_f32 v[84:85], v[84:85], 1.0 op_sel_hi:[1,0]
	v_rcp_f32_e32 v91, v88
	v_rcp_f32_e32 v99, v89
	v_cvt_pk_bf16_f32 v88, v97, v98
	v_cvt_pk_bf16_f32 v89, v92, v93
	v_mad_i64_i32 v[92:93], s[2:3], v182, s41, v[120:121]
	v_lshl_add_u64 v[92:93], v[92:93], 0, v[122:123]
	v_pk_add_f32 v[80:81], v[80:81], 1.0 op_sel_hi:[1,0]
	v_cvt_pk_bf16_f32 v90, v94, v95
	v_cvt_pk_bf16_f32 v91, v91, v99
	global_store_dwordx4 v[92:93], v[88:91], off
	s_nop 1
	v_rcp_f32_e32 v88, v84
	v_rcp_f32_e32 v89, v85
	v_pk_add_f32 v[84:85], v[86:87], 1.0 op_sel_hi:[1,0]
	v_rcp_f32_e32 v86, v80
	v_rcp_f32_e32 v87, v81
; __device__ __forceinline__ unsigned cvt_pk_bf16(float lo, float hi) { unsigned r; asm volatile("v_cvt_pk_bf16_f32 %0, %1, %2" : "=v"(r) : "v"(lo), "v"(hi)); return r; }
;     template <bool GATE> __device__ __forceinline__ void body(const f32x4 (&acc)[2][2][4][2], const Unit& u, int wr, int wc, int fr, int fq) const {
;     ...
;                 const int row = row0 + ai * HALF + m * 16; const float r = rs[ai][m], nrl = r * -1.44269504089f;
; #pragma unroll
;                 for (int bj = 0; bj < 2; ++bj) {
;                     unsigned pk[4];
; #pragma unroll
;                     for (int q = 0; q < 4; ++q) {
;                         const f32x4 va = acc[ai][bj][m][q >> 1]; const int e0 = 2 * (q & 1);
;                         const f32x2 v = (f32x2){va[e0], va[e0 + 1]};
;                         f32x2 o;
;                         if (GATE) { const f32x2 t = v * nrl; f32x2 ex; ex.x = __builtin_amdgcn_exp2f(t.x); ex.y = __builtin_amdgcn_exp2f(t.y);
;                             const f32x2 d = ex + 1.0f; o.x = __builtin_amdgcn_rcpf(d.x); o.y = __builtin_amdgcn_rcpf(d.y); }
;                         else o = v * r;
;                         pk[q] = cvt_pk_bf16(o.x, o.y);
;                     }
;                     u32x4 w; w.x = pk[0]; w.y = pk[1]; w.z = pk[2]; w.w = pk[3];
;                     *(u32x4*)(P + (size_t)row * PITCH + col0 + bj * HALF) = w;
	v_pk_add_f32 v[80:81], v[82:83], 1.0 op_sel_hi:[1,0]
	v_rcp_f32_e32 v84, v84
	v_rcp_f32_e32 v83, v80
	v_cvt_pk_bf16_f32 v80, v88, v89
	v_rcp_f32_e32 v85, v85
	v_rcp_f32_e32 v90, v81
	v_cvt_pk_bf16_f32 v81, v84, v85
	v_cvt_pk_bf16_f32 v82, v86, v87
	v_cvt_pk_bf16_f32 v83, v83, v90
	global_store_dwordx4 v[92:93], v[80:83], off offset:256
	s_nop 1
	v_mul_f32_e32 v80, 0xbfb8aa3b, v137
	v_pk_mul_f32 v[76:77], v[76:77], v[80:81] op_sel_hi:[1,0]
	v_pk_mul_f32 v[78:79], v[78:79], v[80:81] op_sel_hi:[1,0]
	v_exp_f32_e32 v76, v76
	v_exp_f32_e32 v77, v77
	v_exp_f32_e32 v78, v78
	v_exp_f32_e32 v79, v79
	v_pk_add_f32 v[76:77], v[76:77], 1.0 op_sel_hi:[1,0]
	s_nop 0
	v_rcp_f32_e32 v81, v76
	v_rcp_f32_e32 v82, v77
	v_pk_add_f32 v[76:77], v[78:79], 1.0 op_sel_hi:[1,0]
	v_pk_mul_f32 v[72:73], v[72:73], v[80:81] op_sel_hi:[1,0]
	s_nop 0
	v_exp_f32_e32 v72, v72
	v_exp_f32_e32 v73, v73
	v_pk_mul_f32 v[74:75], v[74:75], v[80:81] op_sel_hi:[1,0]
	v_pk_mul_f32 v[68:69], v[68:69], v[80:81] op_sel_hi:[1,0]
	v_exp_f32_e32 v74, v74
	v_exp_f32_e32 v75, v75
	v_pk_mul_f32 v[64:65], v[64:65], v[80:81] op_sel_hi:[1,0]
	v_exp_f32_e32 v68, v68
	v_exp_f32_e32 v69, v69
	v_pk_mul_f32 v[70:71], v[70:71], v[80:81] op_sel_hi:[1,0]
	v_exp_f32_e32 v64, v64
	v_exp_f32_e32 v65, v65
	v_pk_mul_f32 v[66:67], v[66:67], v[80:81] op_sel_hi:[1,0]
	v_pk_add_f32 v[72:73], v[72:73], 1.0 op_sel_hi:[1,0]
	v_exp_f32_e32 v70, v70
	v_exp_f32_e32 v71, v71
	v_exp_f32_e32 v66, v66
	v_exp_f32_e32 v67, v67
	v_rcp_f32_e32 v76, v76
	v_rcp_f32_e32 v77, v77
	v_rcp_f32_e32 v78, v72
	v_rcp_f32_e32 v79, v73
	v_pk_add_f32 v[72:73], v[74:75], 1.0 op_sel_hi:[1,0]
	v_pk_add_f32 v[68:69], v[68:69], 1.0 op_sel_hi:[1,0]
	v_rcp_f32_e32 v75, v72
	v_rcp_f32_e32 v83, v73
	v_cvt_pk_bf16_f32 v72, v81, v82
	v_cvt_pk_bf16_f32 v73, v76, v77
	v_mad_i64_i32 v[76:77], s[2:3], v180, s41, v[120:121]
	v_lshl_add_u64 v[76:77], v[76:77], 0, v[122:123]
	v_pk_add_f32 v[64:65], v[64:65], 1.0 op_sel_hi:[1,0]
	v_cvt_pk_bf16_f32 v74, v78, v79
	v_cvt_pk_bf16_f32 v75, v75, v83
	global_store_dwordx4 v[76:77], v[72:75], off
	s_nop 1
	v_rcp_f32_e32 v72, v68
	v_rcp_f32_e32 v73, v69
	v_pk_add_f32 v[68:69], v[70:71], 1.0 op_sel_hi:[1,0]
	v_rcp_f32_e32 v70, v64
	v_rcp_f32_e32 v71, v65
	v_pk_add_f32 v[64:65], v[66:67], 1.0 op_sel_hi:[1,0]
	v_rcp_f32_e32 v68, v68
	v_rcp_f32_e32 v67, v64
	v_cvt_pk_bf16_f32 v64, v72, v73
	v_rcp_f32_e32 v69, v69
	v_rcp_f32_e32 v74, v65
	v_cvt_pk_bf16_f32 v65, v68, v69
	v_cvt_pk_bf16_f32 v66, v70, v71
	v_cvt_pk_bf16_f32 v67, v67, v74
	global_store_dwordx4 v[76:77], v[64:67], off offset:256
	s_nop 1
	v_mul_f32_e32 v64, 0xbfb8aa3b, v138
	v_pk_mul_f32 v[60:61], v[60:61], v[64:65] op_sel_hi:[1,0]
	v_pk_mul_f32 v[62:63], v[62:63], v[64:65] op_sel_hi:[1,0]
	v_exp_f32_e32 v60, v60
	v_exp_f32_e32 v61, v61
	v_exp_f32_e32 v62, v62
	v_exp_f32_e32 v63, v63
	v_pk_add_f32 v[60:61], v[60:61], 1.0 op_sel_hi:[1,0]
	s_nop 0
	v_rcp_f32_e32 v65, v60
	v_rcp_f32_e32 v66, v61
	v_pk_add_f32 v[60:61], v[62:63], 1.0 op_sel_hi:[1,0]
	v_pk_mul_f32 v[56:57], v[56:57], v[64:65] op_sel_hi:[1,0]
	s_nop 0
	v_exp_f32_e32 v56, v56
	v_exp_f32_e32 v57, v57
	v_pk_mul_f32 v[58:59], v[58:59], v[64:65] op_sel_hi:[1,0]
	v_pk_mul_f32 v[52:53], v[52:53], v[64:65] op_sel_hi:[1,0]
	v_exp_f32_e32 v58, v58
	v_exp_f32_e32 v59, v59
	v_pk_mul_f32 v[48:49], v[48:49], v[64:65] op_sel_hi:[1,0]
	v_exp_f32_e32 v52, v52
	v_exp_f32_e32 v53, v53
	v_pk_mul_f32 v[54:55], v[54:55], v[64:65] op_sel_hi:[1,0]
	v_exp_f32_e32 v48, v48
	v_exp_f32_e32 v49, v49
	v_pk_mul_f32 v[50:51], v[50:51], v[64:65] op_sel_hi:[1,0]
	v_pk_add_f32 v[56:57], v[56:57], 1.0 op_sel_hi:[1,0]
	v_exp_f32_e32 v54, v54
	v_exp_f32_e32 v55, v55
	v_exp_f32_e32 v50, v50
	v_exp_f32_e32 v51, v51
	v_rcp_f32_e32 v60, v60
	v_rcp_f32_e32 v61, v61
	v_rcp_f32_e32 v62, v56
	v_rcp_f32_e32 v63, v57
	v_pk_add_f32 v[56:57], v[58:59], 1.0 op_sel_hi:[1,0]
	v_pk_add_f32 v[52:53], v[52:53], 1.0 op_sel_hi:[1,0]
	v_rcp_f32_e32 v59, v56
	v_rcp_f32_e32 v67, v57
	v_cvt_pk_bf16_f32 v56, v65, v66
	v_cvt_pk_bf16_f32 v57, v60, v61
	v_mad_i64_i32 v[60:61], s[2:3], v178, s41, v[120:121]
	v_lshl_add_u64 v[60:61], v[60:61], 0, v[122:123]
	v_pk_add_f32 v[48:49], v[48:49], 1.0 op_sel_hi:[1,0]
	v_cvt_pk_bf16_f32 v58, v62, v63
	v_cvt_pk_bf16_f32 v59, v59, v67
	global_store_dwordx4 v[60:61], v[56:59], off
	s_nop 1
	v_rcp_f32_e32 v56, v52
	v_rcp_f32_e32 v57, v53
	v_pk_add_f32 v[52:53], v[54:55], 1.0 op_sel_hi:[1,0]
	v_rcp_f32_e32 v54, v48
	v_rcp_f32_e32 v55, v49
	v_pk_add_f32 v[48:49], v[50:51], 1.0 op_sel_hi:[1,0]
	v_rcp_f32_e32 v52, v52
	v_rcp_f32_e32 v51, v48
	v_cvt_pk_bf16_f32 v48, v56, v57
	v_rcp_f32_e32 v53, v53
	v_rcp_f32_e32 v58, v49
	v_cvt_pk_bf16_f32 v49, v52, v53
	v_cvt_pk_bf16_f32 v50, v54, v55
	v_cvt_pk_bf16_f32 v51, v51, v58
	global_store_dwordx4 v[60:61], v[48:51], off offset:256
	s_nop 1
	v_mul_f32_e32 v48, 0xbfb8aa3b, v130
	v_pk_mul_f32 v[44:45], v[44:45], v[48:49] op_sel_hi:[1,0]
	v_pk_mul_f32 v[46:47], v[46:47], v[48:49] op_sel_hi:[1,0]
	v_exp_f32_e32 v44, v44
	v_exp_f32_e32 v45, v45
	v_exp_f32_e32 v46, v46
	v_exp_f32_e32 v47, v47
	v_pk_add_f32 v[44:45], v[44:45], 1.0 op_sel_hi:[1,0]
	s_nop 0
	v_rcp_f32_e32 v49, v44
	v_rcp_f32_e32 v50, v45
	v_pk_add_f32 v[44:45], v[46:47], 1.0 op_sel_hi:[1,0]
	v_pk_mul_f32 v[40:41], v[40:41], v[48:49] op_sel_hi:[1,0]
	s_nop 0
	v_exp_f32_e32 v40, v40
	v_exp_f32_e32 v41, v41
	v_pk_mul_f32 v[42:43], v[42:43], v[48:49] op_sel_hi:[1,0]
	v_pk_mul_f32 v[36:37], v[36:37], v[48:49] op_sel_hi:[1,0]
	v_exp_f32_e32 v42, v42
	v_exp_f32_e32 v43, v43
	v_pk_mul_f32 v[32:33], v[32:33], v[48:49] op_sel_hi:[1,0]
	v_exp_f32_e32 v36, v36
	v_exp_f32_e32 v37, v37
	v_pk_mul_f32 v[38:39], v[38:39], v[48:49] op_sel_hi:[1,0]
; __device__ __forceinline__ unsigned cvt_pk_bf16(float lo, float hi) { unsigned r; asm volatile("v_cvt_pk_bf16_f32 %0, %1, %2" : "=v"(r) : "v"(lo), "v"(hi)); return r; }
;     template <bool GATE> __device__ __forceinline__ void body(const f32x4 (&acc)[2][2][4][2], const Unit& u, int wr, int wc, int fr, int fq) const {
;     ...
;                 const int row = row0 + ai * HALF + m * 16; const float r = rs[ai][m], nrl = r * -1.44269504089f;
; #pragma unroll
;                 for (int bj = 0; bj < 2; ++bj) {
;                     unsigned pk[4];
; #pragma unroll
;                     for (int q = 0; q < 4; ++q) {
;                         const f32x4 va = acc[ai][bj][m][q >> 1]; const int e0 = 2 * (q & 1);
;                         const f32x2 v = (f32x2){va[e0], va[e0 + 1]};
;                         f32x2 o;
;                         if (GATE) { const f32x2 t = v * nrl; f32x2 ex; ex.x = __builtin_amdgcn_exp2f(t.x); ex.y = __builtin_amdgcn_exp2f(t.y);
;                             const f32x2 d = ex + 1.0f; o.x = __builtin_amdgcn_rcpf(d.x); o.y = __builtin_amdgcn_rcpf(d.y); }
;                         else o = v * r;
;                         pk[q] = cvt_pk_bf16(o.x, o.y);
;                     }
;                     u32x4 w; w.x = pk[0]; w.y = pk[1]; w.z = pk[2]; w.w = pk[3];
;                     *(u32x4*)(P + (size_t)row * PITCH + col0 + bj * HALF) = w;
	v_exp_f32_e32 v32, v32
	v_exp_f32_e32 v33, v33
	v_pk_mul_f32 v[34:35], v[34:35], v[48:49] op_sel_hi:[1,0]
	v_pk_add_f32 v[40:41], v[40:41], 1.0 op_sel_hi:[1,0]
	v_exp_f32_e32 v38, v38
	v_exp_f32_e32 v39, v39
	v_exp_f32_e32 v34, v34
	v_exp_f32_e32 v35, v35
	v_rcp_f32_e32 v44, v44
	v_rcp_f32_e32 v45, v45
	v_rcp_f32_e32 v46, v40
	v_rcp_f32_e32 v47, v41
	v_pk_add_f32 v[40:41], v[42:43], 1.0 op_sel_hi:[1,0]
	v_pk_add_f32 v[36:37], v[36:37], 1.0 op_sel_hi:[1,0]
	v_rcp_f32_e32 v43, v40
	v_rcp_f32_e32 v51, v41
	v_cvt_pk_bf16_f32 v40, v49, v50
	v_cvt_pk_bf16_f32 v41, v44, v45
	v_mad_i64_i32 v[44:45], s[2:3], v176, s41, v[120:121]
	v_lshl_add_u64 v[44:45], v[44:45], 0, v[122:123]
	v_pk_add_f32 v[32:33], v[32:33], 1.0 op_sel_hi:[1,0]
	v_cvt_pk_bf16_f32 v42, v46, v47
	v_cvt_pk_bf16_f32 v43, v43, v51
	global_store_dwordx4 v[44:45], v[40:43], off
	s_nop 1
	v_rcp_f32_e32 v40, v36
	v_rcp_f32_e32 v41, v37
	v_pk_add_f32 v[36:37], v[38:39], 1.0 op_sel_hi:[1,0]
	v_rcp_f32_e32 v38, v32
	v_rcp_f32_e32 v39, v33
	v_pk_add_f32 v[32:33], v[34:35], 1.0 op_sel_hi:[1,0]
	v_rcp_f32_e32 v36, v36
	v_rcp_f32_e32 v35, v32
	v_cvt_pk_bf16_f32 v32, v40, v41
	v_rcp_f32_e32 v37, v37
	v_rcp_f32_e32 v42, v33
	v_cvt_pk_bf16_f32 v33, v36, v37
	v_cvt_pk_bf16_f32 v34, v38, v39
	v_cvt_pk_bf16_f32 v35, v35, v42
	global_store_dwordx4 v[44:45], v[32:35], off offset:256
	s_nop 1
	v_mul_f32_e32 v32, 0xbfb8aa3b, v129
	v_pk_mul_f32 v[28:29], v[28:29], v[32:33] op_sel_hi:[1,0]
	v_pk_mul_f32 v[30:31], v[30:31], v[32:33] op_sel_hi:[1,0]
	v_exp_f32_e32 v28, v28
	v_exp_f32_e32 v29, v29
	v_exp_f32_e32 v30, v30
	v_exp_f32_e32 v31, v31
	v_pk_add_f32 v[28:29], v[28:29], 1.0 op_sel_hi:[1,0]
	s_nop 0
	v_rcp_f32_e32 v33, v28
	v_rcp_f32_e32 v34, v29
	v_pk_add_f32 v[28:29], v[30:31], 1.0 op_sel_hi:[1,0]
	v_pk_mul_f32 v[24:25], v[24:25], v[32:33] op_sel_hi:[1,0]
	s_nop 0
	v_exp_f32_e32 v24, v24
	v_exp_f32_e32 v25, v25
	v_pk_mul_f32 v[26:27], v[26:27], v[32:33] op_sel_hi:[1,0]
	v_pk_mul_f32 v[20:21], v[20:21], v[32:33] op_sel_hi:[1,0]
	v_exp_f32_e32 v26, v26
	v_exp_f32_e32 v27, v27
	v_pk_mul_f32 v[16:17], v[16:17], v[32:33] op_sel_hi:[1,0]
	v_exp_f32_e32 v20, v20
	v_exp_f32_e32 v21, v21
	v_pk_mul_f32 v[22:23], v[22:23], v[32:33] op_sel_hi:[1,0]
	v_exp_f32_e32 v16, v16
	v_exp_f32_e32 v17, v17
	v_pk_mul_f32 v[18:19], v[18:19], v[32:33] op_sel_hi:[1,0]
	v_pk_add_f32 v[24:25], v[24:25], 1.0 op_sel_hi:[1,0]
	v_exp_f32_e32 v22, v22
	v_exp_f32_e32 v23, v23
	v_exp_f32_e32 v18, v18
	v_exp_f32_e32 v19, v19
	v_rcp_f32_e32 v28, v28
	v_rcp_f32_e32 v29, v29
	v_rcp_f32_e32 v30, v24
	v_rcp_f32_e32 v31, v25
	v_pk_add_f32 v[24:25], v[26:27], 1.0 op_sel_hi:[1,0]
	v_pk_add_f32 v[20:21], v[20:21], 1.0 op_sel_hi:[1,0]
	v_rcp_f32_e32 v27, v24
	v_rcp_f32_e32 v35, v25
	v_cvt_pk_bf16_f32 v24, v33, v34
	v_cvt_pk_bf16_f32 v25, v28, v29
	v_mad_i64_i32 v[28:29], s[2:3], v174, s41, v[120:121]
	v_lshl_add_u64 v[28:29], v[28:29], 0, v[122:123]
	v_pk_add_f32 v[16:17], v[16:17], 1.0 op_sel_hi:[1,0]
	v_cvt_pk_bf16_f32 v26, v30, v31
	v_cvt_pk_bf16_f32 v27, v27, v35
	global_store_dwordx4 v[28:29], v[24:27], off
	s_nop 1
	v_rcp_f32_e32 v24, v20
	v_rcp_f32_e32 v25, v21
	v_pk_add_f32 v[20:21], v[22:23], 1.0 op_sel_hi:[1,0]
	v_rcp_f32_e32 v22, v16
	v_rcp_f32_e32 v23, v17
	v_pk_add_f32 v[16:17], v[18:19], 1.0 op_sel_hi:[1,0]
	v_rcp_f32_e32 v20, v20
	v_rcp_f32_e32 v19, v16
	v_cvt_pk_bf16_f32 v16, v24, v25
	v_rcp_f32_e32 v21, v21
	v_rcp_f32_e32 v26, v17
	v_cvt_pk_bf16_f32 v17, v20, v21
	v_cvt_pk_bf16_f32 v18, v22, v23
	v_cvt_pk_bf16_f32 v19, v19, v26
	global_store_dwordx4 v[28:29], v[16:19], off offset:256
	s_nop 1
	v_mul_f32_e32 v16, 0xbfb8aa3b, v128
	v_pk_mul_f32 v[12:13], v[12:13], v[16:17] op_sel_hi:[1,0]
	v_pk_mul_f32 v[14:15], v[14:15], v[16:17] op_sel_hi:[1,0]
	v_exp_f32_e32 v12, v12
	v_exp_f32_e32 v13, v13
	v_exp_f32_e32 v14, v14
	v_exp_f32_e32 v15, v15
	v_pk_add_f32 v[12:13], v[12:13], 1.0 op_sel_hi:[1,0]
	s_nop 0
	v_rcp_f32_e32 v17, v12
	v_rcp_f32_e32 v18, v13
	v_pk_add_f32 v[12:13], v[14:15], 1.0 op_sel_hi:[1,0]
	v_pk_mul_f32 v[8:9], v[8:9], v[16:17] op_sel_hi:[1,0]
	s_nop 0
	v_exp_f32_e32 v8, v8
	v_exp_f32_e32 v9, v9
	v_pk_mul_f32 v[10:11], v[10:11], v[16:17] op_sel_hi:[1,0]
	v_pk_mul_f32 v[4:5], v[4:5], v[16:17] op_sel_hi:[1,0]
	v_exp_f32_e32 v10, v10
	v_exp_f32_e32 v11, v11
	v_pk_mul_f32 v[0:1], v[0:1], v[16:17] op_sel_hi:[1,0]
	v_exp_f32_e32 v4, v4
	v_exp_f32_e32 v5, v5
	v_pk_mul_f32 v[6:7], v[6:7], v[16:17] op_sel_hi:[1,0]
	v_exp_f32_e32 v0, v0
	v_exp_f32_e32 v1, v1
	v_pk_mul_f32 v[2:3], v[2:3], v[16:17] op_sel_hi:[1,0]
	v_pk_add_f32 v[8:9], v[8:9], 1.0 op_sel_hi:[1,0]
	v_exp_f32_e32 v6, v6
	v_exp_f32_e32 v7, v7
	v_exp_f32_e32 v2, v2
	v_exp_f32_e32 v3, v3
	v_rcp_f32_e32 v12, v12
	v_rcp_f32_e32 v13, v13
	v_rcp_f32_e32 v14, v8
	v_rcp_f32_e32 v15, v9
	v_pk_add_f32 v[8:9], v[10:11], 1.0 op_sel_hi:[1,0]
	v_pk_add_f32 v[4:5], v[4:5], 1.0 op_sel_hi:[1,0]
	v_rcp_f32_e32 v11, v8
	v_rcp_f32_e32 v19, v9
	v_cvt_pk_bf16_f32 v8, v17, v18
	v_cvt_pk_bf16_f32 v9, v12, v13
	v_mad_i64_i32 v[12:13], s[2:3], v170, s41, v[120:121]
	v_lshl_add_u64 v[12:13], v[12:13], 0, v[122:123]
	v_pk_add_f32 v[0:1], v[0:1], 1.0 op_sel_hi:[1,0]
	v_cvt_pk_bf16_f32 v10, v14, v15
	v_cvt_pk_bf16_f32 v11, v11, v19
	global_store_dwordx4 v[12:13], v[8:11], off
	s_nop 1
	v_rcp_f32_e32 v8, v4
	v_rcp_f32_e32 v9, v5
	v_pk_add_f32 v[4:5], v[6:7], 1.0 op_sel_hi:[1,0]
	v_rcp_f32_e32 v6, v0
	v_rcp_f32_e32 v7, v1
	v_pk_add_f32 v[0:1], v[2:3], 1.0 op_sel_hi:[1,0]
	v_rcp_f32_e32 v4, v4
	v_rcp_f32_e32 v5, v5
	v_rcp_f32_e32 v0, v0
	v_rcp_f32_e32 v1, v1
	v_cvt_pk_bf16_f32 v148, v8, v9
	v_cvt_pk_bf16_f32 v149, v4, v5
	v_cvt_pk_bf16_f32 v150, v6, v7
	v_cvt_pk_bf16_f32 v151, v0, v1

; __device__ __forceinline__ unsigned cvt_pk_bf16(float lo, float hi) { unsigned r; asm volatile("v_cvt_pk_bf16_f32 %0, %1, %2" : "=v"(r) : "v"(lo), "v"(hi)); return r; }
; __device__ __forceinline__ float bf_lo(unsigned w) { return __uint_as_float(w << 16); }
; __device__ __forceinline__ float bf_hi(unsigned w) { return __uint_as_float(w & 0xffff0000u); }
;     __device__ __forceinline__ void operator()(const f32x4 (&acc)[2][2][4][2], const Unit& u, int wr, int wc, int fr, int fq) const {
;     ...
;             for (int mm = 0; mm < RB; ++mm) { const size_t off = (size_t)(row0 + ai * HALF + (mh + mm) * 16) * D_MODEL + col0;
; #pragma unroll
;                 for (int bj = 0; bj < 2; ++bj) {
;                     if (BASE_F32) { bf[mm][bj][0] = *(const f32x4*)(basef + off + bj * HALF); bf[mm][bj][1] = *(const f32x4*)(basef + off + bj * HALF + 4); }
;                     else bb[mm][bj] = *(const u32x4*)(xb + off + bj * HALF);
;                 } }
;             asm volatile("" ::: "memory");
; #pragma unroll
;             for (int mm = 0; mm < RB; ++mm) {
;                 const int m = mh + mm;
;                 const int row = row0 + ai * HALF + m * 16; const size_t off = (size_t)row * D_MODEL + col0; float s = 0.f;
; #pragma unroll
;                 for (int bj = 0; bj < 2; ++bj) {
;                     f32x4 b0, b1;
;                     if (BASE_F32) { b0 = bf[mm][bj][0]; b1 = bf[mm][bj][1]; }
;                     else { const u32x4 w = bb[mm][bj]; b0 = (f32x4){bf_lo(w.x), bf_hi(w.x), bf_lo(w.y), bf_hi(w.y)}; b1 = (f32x4){bf_lo(w.z), bf_hi(w.z), bf_lo(w.w), bf_hi(w.w)}; }
;                     const f32x4 o0 = b0 + acc[ai][bj][m][0] * alpha, o1 = b1 + acc[ai][bj][m][1] * alpha;
;                     if (OUT_F32) { *(f32x4*)(out + off + bj * HALF) = o0; *(f32x4*)(out + off + bj * HALF + 4) = o1; }
;                     else { u32x4 w; w.x = cvt_pk_bf16(o0[0], o0[1]); w.y = cvt_pk_bf16(o0[2], o0[3]); w.z = cvt_pk_bf16(o1[0], o1[1]); w.w = cvt_pk_bf16(o1[2], o1[3]); *(u32x4*)(xb + off + bj * HALF) = w; }
;                     s += ((o0[0] * o0[0] + o0[1] * o0[1]) + (o0[2] * o0[2] + o0[3] * o0[3])) + ((o1[0] * o1[0] + o1[1] * o1[1]) + (o1[2] * o1[2] + o1[3] * o1[3]));
;                 }
;                 if (ssp) { s += __shfl_xor(s, 16); s += __shfl_xor(s, 32); if (fq == 0) ssp[(size_t)row * 16 + u.pn * 4 + wc] = s; }
.LBB0_826:
	v_lshl_or_b32 v166, s12, 8, v186
	v_lshl_add_u32 v168, s45, 8, v184
	v_ashrrev_i32_e32 v167, 31, v166
	v_readlane_b32 s2, v235, 38
	v_lshlrev_b64 v[194:195], 1, v[166:167]
	v_readlane_b32 s3, v235, 39
	v_ashrrev_i32_e32 v169, 31, v168
	v_lshlrev_b64 v[192:193], 11, v[168:169]
	v_lshl_add_u64 v[170:171], s[2:3], 0, v[194:195]
	v_lshl_add_u64 v[128:129], v[170:171], 0, v[192:193]
	global_load_dwordx4 v[198:201], v[128:129], off
	global_load_dwordx4 v[202:205], v[128:129], off offset:256
	v_or_b32_e32 v180, 16, v168
	v_or_b32_e32 v176, 32, v168
	v_or_b32_e32 v172, 48, v168
	v_ashrrev_i32_e32 v181, 31, v180
	v_ashrrev_i32_e32 v177, 31, v176
	v_ashrrev_i32_e32 v173, 31, v172
	v_lshlrev_b64 v[182:183], 11, v[180:181]
	v_lshlrev_b64 v[178:179], 11, v[176:177]
	v_lshlrev_b64 v[174:175], 11, v[172:173]
	v_lshl_add_u64 v[128:129], v[170:171], 0, v[182:183]
	v_lshl_add_u64 v[130:131], v[170:171], 0, v[178:179]
	v_lshl_add_u64 v[206:207], v[170:171], 0, v[174:175]
	global_load_dwordx4 v[148:151], v[128:129], off
	global_load_dwordx4 v[144:147], v[128:129], off offset:256
	global_load_dwordx4 v[140:143], v[130:131], off
	global_load_dwordx4 v[136:139], v[130:131], off offset:256
	global_load_dwordx4 v[132:135], v[206:207], off
	s_nop 0
	global_load_dwordx4 v[128:131], v[206:207], off offset:256
	v_and_b32_e32 v206, 64, v191
	v_xor_b32_e32 v197, 16, v191
	v_add_u32_e32 v206, 64, v206
	v_xor_b32_e32 v207, 32, v191
	v_cmp_lt_i32_e32 vcc, v197, v206
	s_lshl_b32 s8, s12, 2
	s_ashr_i32 s9, s8, 31
	v_cndmask_b32_e32 v197, v191, v197, vcc
	v_cmp_lt_i32_e32 vcc, v207, v206
	s_waitcnt vmcnt(0)
	v_lshlrev_b32_e32 v208, 16, v200
	v_cndmask_b32_e32 v214, v191, v207, vcc
	v_lshl_add_u64 v[206:207], s[2:3], 0, v[192:193]
	v_lshl_add_u64 v[194:195], v[206:207], 0, v[194:195]
	v_lshlrev_b32_e32 v206, 16, v198
	v_and_b32_e32 v207, 0xffff0000, v198
	v_lshlrev_b32_e32 v198, 16, v199
	v_and_b32_e32 v199, 0xffff0000, v199
	v_and_b32_e32 v209, 0xffff0000, v200
	v_lshlrev_b32_e32 v200, 16, v201
	v_and_b32_e32 v201, 0xffff0000, v201
	v_lshlrev_b32_e32 v210, 16, v202
	v_and_b32_e32 v211, 0xffff0000, v202
	v_lshlrev_b32_e32 v202, 16, v203
	v_and_b32_e32 v203, 0xffff0000, v203
	v_lshlrev_b32_e32 v212, 16, v204
	v_and_b32_e32 v213, 0xffff0000, v204
	v_lshlrev_b32_e32 v204, 16, v205
	v_and_b32_e32 v205, 0xffff0000, v205
	v_pk_add_f32 v[126:127], v[126:127], v[198:199]
	v_pk_add_f32 v[124:125], v[124:125], v[206:207]
	v_pk_add_f32 v[122:123], v[122:123], v[200:201]
	v_pk_add_f32 v[120:121], v[120:121], v[208:209]
	v_pk_add_f32 v[118:119], v[118:119], v[202:203]
	v_pk_add_f32 v[116:117], v[116:117], v[210:211]
	v_pk_add_f32 v[198:199], v[114:115], v[204:205]
	v_pk_add_f32 v[200:201], v[112:113], v[212:213]
	v_lshlrev_b32_e32 v192, 2, v197
	v_cvt_pk_bf16_f32 v112, v124, v125
	v_cvt_pk_bf16_f32 v113, v126, v127
	v_mul_f32_e32 v114, v125, v125
	v_mul_f32_e32 v115, v127, v127
	v_mul_f32_e32 v125, v121, v121
	v_mul_f32_e32 v127, v123, v123
	v_mul_f32_e32 v193, v117, v117
	v_mul_f32_e32 v197, v119, v119
	v_mul_f32_e32 v202, v201, v201
	v_mul_f32_e32 v203, v199, v199
	v_fmac_f32_e32 v114, v124, v124
	v_fmac_f32_e32 v115, v126, v126
	v_fmac_f32_e32 v125, v120, v120
	v_fmac_f32_e32 v127, v122, v122
	v_fmac_f32_e32 v193, v116, v116
	v_fmac_f32_e32 v197, v118, v118
	v_fmac_f32_e32 v202, v200, v200
	v_fmac_f32_e32 v203, v198, v198
	v_add_f32_e32 v114, v114, v115
	v_add_f32_e32 v115, v125, v127
	v_add_f32_e32 v124, v193, v197
	v_add_f32_e32 v125, v202, v203
	v_add_f32_e32 v114, v114, v115
	v_add_f32_e32 v115, v124, v125
	v_add_f32_e32 v124, v114, v115
	v_mov_b32_e32 v236, v124
	v_mov_b32_e32 v237, v124
	s_nop 1
	v_permlane16_swap_b32_e32 v236, v237
	v_cndmask_b32_e64 v125, v237, v236, s[98:99]
	v_cvt_pk_bf16_f32 v114, v120, v121
	v_cvt_pk_bf16_f32 v115, v122, v123
	global_store_dwordx4 v[194:195], v[112:115], off
	v_cvt_pk_bf16_f32 v116, v116, v117
	v_cvt_pk_bf16_f32 v117, v118, v119
	v_cvt_pk_bf16_f32 v118, v200, v201
	v_cvt_pk_bf16_f32 v119, v198, v199
	global_store_dwordx4 v[194:195], v[116:119], off offset:256
	s_waitcnt lgkmcnt(0)
	v_add_f32_e32 v113, v124, v125
	v_lshlrev_b32_e32 v112, 2, v214
	v_mov_b32_e32 v236, v113
	v_mov_b32_e32 v237, v113
	s_nop 1
	v_permlane32_swap_b32_e32 v236, v237
	v_cndmask_b32_e64 v114, v237, v236, s[100:101]
	s_and_saveexec_b64 s[2:3], s[4:5]
	s_cbranch_execz .LBB0_828
	v_lshlrev_b64 v[116:117], 6, v[168:169]
	v_lshl_add_u64 v[116:117], s[10:11], 0, v[116:117]
	v_lshl_add_u64 v[116:117], s[8:9], 2, v[116:117]
	s_lshl_b32 s12, s36, 2
	v_lshl_add_u64 v[116:117], v[116:117], 0, s[12:13]
	s_waitcnt lgkmcnt(0)
	v_add_f32_e32 v113, v113, v114
	global_store_dword v[116:117], v113, off
; __device__ __forceinline__ unsigned cvt_pk_bf16(float lo, float hi) { unsigned r; asm volatile("v_cvt_pk_bf16_f32 %0, %1, %2" : "=v"(r) : "v"(lo), "v"(hi)); return r; }
; __device__ __forceinline__ float bf_lo(unsigned w) { return __uint_as_float(w << 16); }
; __device__ __forceinline__ float bf_hi(unsigned w) { return __uint_as_float(w & 0xffff0000u); }
;     __device__ __forceinline__ void operator()(const f32x4 (&acc)[2][2][4][2], const Unit& u, int wr, int wc, int fr, int fq) const {
;     ...
;             for (int mm = 0; mm < RB; ++mm) {
;                 const int m = mh + mm;
;                 const int row = row0 + ai * HALF + m * 16; const size_t off = (size_t)row * D_MODEL + col0; float s = 0.f;
; #pragma unroll
;                 for (int bj = 0; bj < 2; ++bj) {
;                     f32x4 b0, b1;
;                     if (BASE_F32) { b0 = bf[mm][bj][0]; b1 = bf[mm][bj][1]; }
;                     else { const u32x4 w = bb[mm][bj]; b0 = (f32x4){bf_lo(w.x), bf_hi(w.x), bf_lo(w.y), bf_hi(w.y)}; b1 = (f32x4){bf_lo(w.z), bf_hi(w.z), bf_lo(w.w), bf_hi(w.w)}; }
;                     const f32x4 o0 = b0 + acc[ai][bj][m][0] * alpha, o1 = b1 + acc[ai][bj][m][1] * alpha;
;                     if (OUT_F32) { *(f32x4*)(out + off + bj * HALF) = o0; *(f32x4*)(out + off + bj * HALF + 4) = o1; }
;                     else { u32x4 w; w.x = cvt_pk_bf16(o0[0], o0[1]); w.y = cvt_pk_bf16(o0[2], o0[3]); w.z = cvt_pk_bf16(o1[0], o1[1]); w.w = cvt_pk_bf16(o1[2], o1[3]); *(u32x4*)(xb + off + bj * HALF) = w; }
;                     s += ((o0[0] * o0[0] + o0[1] * o0[1]) + (o0[2] * o0[2] + o0[3] * o0[3])) + ((o1[0] * o1[0] + o1[1] * o1[1]) + (o1[2] * o1[2] + o1[3] * o1[3]));
;                 }
;                 if (ssp) { s += __shfl_xor(s, 16); s += __shfl_xor(s, 32); if (fq == 0) ssp[(size_t)row * 16 + u.pn * 4 + wc] = s; }
.LBB0_828:
	s_or_b64 exec, exec, s[2:3]
	s_waitcnt lgkmcnt(0)
	v_lshlrev_b32_e32 v114, 16, v148
	v_and_b32_e32 v115, 0xffff0000, v148
	v_lshlrev_b32_e32 v116, 16, v149
	v_and_b32_e32 v117, 0xffff0000, v149
	v_lshlrev_b32_e32 v120, 16, v151
	v_and_b32_e32 v121, 0xffff0000, v151
	v_pk_add_f32 v[110:111], v[110:111], v[116:117]
	v_pk_add_f32 v[108:109], v[108:109], v[114:115]
	v_pk_add_f32 v[114:115], v[106:107], v[120:121]
	v_lshlrev_b32_e32 v120, 16, v145
	v_and_b32_e32 v121, 0xffff0000, v145
	v_lshlrev_b32_e32 v122, 16, v146
	v_and_b32_e32 v123, 0xffff0000, v146
	v_lshlrev_b32_e32 v118, 16, v150
	v_and_b32_e32 v119, 0xffff0000, v150
	v_pk_add_f32 v[102:103], v[102:103], v[120:121]
	v_pk_add_f32 v[120:121], v[96:97], v[122:123]
	v_mul_f32_e32 v96, v109, v109
	v_mul_f32_e32 v97, v111, v111
	v_pk_add_f32 v[116:117], v[104:105], v[118:119]
	v_lshlrev_b32_e32 v118, 16, v144
	v_and_b32_e32 v119, 0xffff0000, v144
	v_lshlrev_b32_e32 v124, 16, v147
	v_and_b32_e32 v125, 0xffff0000, v147
	v_fmac_f32_e32 v96, v108, v108
	v_fmac_f32_e32 v97, v110, v110
	v_pk_add_f32 v[100:101], v[100:101], v[118:119]
	v_pk_add_f32 v[118:119], v[98:99], v[124:125]
	v_add_f32_e32 v96, v96, v97
	v_mul_f32_e32 v97, v117, v117
	v_mul_f32_e32 v98, v115, v115
	v_fmac_f32_e32 v97, v116, v116
	v_fmac_f32_e32 v98, v114, v114
	v_add_f32_e32 v97, v97, v98
	v_add_f32_e32 v96, v96, v97
	v_mul_f32_e32 v97, v101, v101
	v_mul_f32_e32 v98, v103, v103
	v_fmac_f32_e32 v97, v100, v100
	v_fmac_f32_e32 v98, v102, v102
	v_add_f32_e32 v97, v97, v98
	v_mul_f32_e32 v98, v121, v121
	v_mul_f32_e32 v99, v119, v119
	v_fmac_f32_e32 v98, v120, v120
	v_fmac_f32_e32 v99, v118, v118
	v_add_f32_e32 v98, v98, v99
	v_add_f32_e32 v97, v97, v98
	v_add_f32_e32 v99, v96, v97
	v_cvt_pk_bf16_f32 v104, v108, v109
	v_cvt_pk_bf16_f32 v105, v110, v111
	v_mov_b32_e32 v236, v99
	v_mov_b32_e32 v237, v99
	s_nop 1
	v_permlane16_swap_b32_e32 v236, v237
	v_cndmask_b32_e64 v110, v237, v236, s[98:99]
	v_readlane_b32 s2, v235, 38
	v_readlane_b32 s3, v235, 39
	v_cvt_pk_bf16_f32 v106, v116, v117
	v_cvt_pk_bf16_f32 v107, v114, v115
	s_nop 1
	v_lshl_add_u64 v[96:97], s[2:3], 0, v[182:183]
	v_lshl_add_u64 v[108:109], v[166:167], 1, v[96:97]
	s_waitcnt lgkmcnt(0)
	v_add_f32_e32 v96, v99, v110
	v_mov_b32_e32 v236, v96
	v_mov_b32_e32 v237, v96
	s_nop 1
	v_permlane32_swap_b32_e32 v236, v237
	v_cndmask_b32_e64 v97, v237, v236, s[100:101]
	global_store_dwordx4 v[108:109], v[104:107], off
	v_cvt_pk_bf16_f32 v98, v100, v101
	v_cvt_pk_bf16_f32 v99, v102, v103
	v_cvt_pk_bf16_f32 v100, v120, v121
	v_cvt_pk_bf16_f32 v101, v118, v119
	global_store_dwordx4 v[108:109], v[98:101], off offset:256
	s_and_saveexec_b64 s[2:3], s[4:5]
	s_cbranch_execz .LBB0_830
	v_lshlrev_b64 v[98:99], 6, v[180:181]
	v_lshl_add_u64 v[98:99], s[10:11], 0, v[98:99]
	v_lshl_add_u64 v[98:99], s[8:9], 2, v[98:99]
	s_lshl_b32 s12, s36, 2
	v_lshl_add_u64 v[98:99], v[98:99], 0, s[12:13]
	s_waitcnt lgkmcnt(0)
	v_add_f32_e32 v96, v96, v97
	global_store_dword v[98:99], v96, off
.LBB0_830:
	s_or_b64 exec, exec, s[2:3]
	v_lshlrev_b32_e32 v96, 16, v140
	s_waitcnt lgkmcnt(0)
	v_and_b32_e32 v97, 0xffff0000, v140
	v_lshlrev_b32_e32 v98, 16, v141
	v_and_b32_e32 v99, 0xffff0000, v141
	v_lshlrev_b32_e32 v102, 16, v143
	v_and_b32_e32 v103, 0xffff0000, v143
	v_pk_add_f32 v[94:95], v[94:95], v[98:99]
	v_pk_add_f32 v[92:93], v[92:93], v[96:97]
	v_pk_add_f32 v[96:97], v[90:91], v[102:103]
	v_lshlrev_b32_e32 v102, 16, v137
	v_and_b32_e32 v103, 0xffff0000, v137
	v_lshlrev_b32_e32 v104, 16, v138
	v_and_b32_e32 v105, 0xffff0000, v138
	v_lshlrev_b32_e32 v100, 16, v142
	v_and_b32_e32 v101, 0xffff0000, v142
	v_pk_add_f32 v[86:87], v[86:87], v[102:103]
	v_pk_add_f32 v[102:103], v[80:81], v[104:105]
	v_mul_f32_e32 v80, v93, v93
	v_mul_f32_e32 v81, v95, v95
	v_pk_add_f32 v[98:99], v[88:89], v[100:101]
	v_lshlrev_b32_e32 v100, 16, v136
	v_and_b32_e32 v101, 0xffff0000, v136
	v_lshlrev_b32_e32 v106, 16, v139
	v_and_b32_e32 v107, 0xffff0000, v139
	v_fmac_f32_e32 v80, v92, v92
	v_fmac_f32_e32 v81, v94, v94
	v_pk_add_f32 v[84:85], v[84:85], v[100:101]
	v_pk_add_f32 v[100:101], v[82:83], v[106:107]
	v_add_f32_e32 v80, v80, v81
	v_mul_f32_e32 v81, v99, v99
	v_mul_f32_e32 v82, v97, v97
	v_fmac_f32_e32 v81, v98, v98
	v_fmac_f32_e32 v82, v96, v96
	v_add_f32_e32 v81, v81, v82
	v_add_f32_e32 v80, v80, v81
	v_mul_f32_e32 v81, v85, v85
	v_mul_f32_e32 v82, v87, v87
	v_fmac_f32_e32 v81, v84, v84
	v_fmac_f32_e32 v82, v86, v86
	v_add_f32_e32 v81, v81, v82
	v_mul_f32_e32 v82, v103, v103
	v_mul_f32_e32 v83, v101, v101
	v_fmac_f32_e32 v82, v102, v102
	v_fmac_f32_e32 v83, v100, v100
	v_add_f32_e32 v82, v82, v83
	v_add_f32_e32 v81, v81, v82
	v_add_f32_e32 v83, v80, v81
	v_cvt_pk_bf16_f32 v88, v92, v93
	v_cvt_pk_bf16_f32 v89, v94, v95
	v_mov_b32_e32 v236, v83
	v_mov_b32_e32 v237, v83
	s_nop 1
	v_permlane16_swap_b32_e32 v236, v237
	v_cndmask_b32_e64 v94, v237, v236, s[98:99]
	v_readlane_b32 s2, v235, 38
	v_readlane_b32 s3, v235, 39
	v_cvt_pk_bf16_f32 v90, v98, v99
	v_cvt_pk_bf16_f32 v91, v96, v97
	s_nop 1
	v_lshl_add_u64 v[80:81], s[2:3], 0, v[178:179]
	v_lshl_add_u64 v[92:93], v[166:167], 1, v[80:81]
	s_waitcnt lgkmcnt(0)
	v_add_f32_e32 v80, v83, v94
	v_mov_b32_e32 v236, v80
	v_mov_b32_e32 v237, v80
	s_nop 1
	v_permlane32_swap_b32_e32 v236, v237
	v_cndmask_b32_e64 v81, v237, v236, s[100:101]
	global_store_dwordx4 v[92:93], v[88:91], off
	v_cvt_pk_bf16_f32 v82, v84, v85
	v_cvt_pk_bf16_f32 v83, v86, v87
	v_cvt_pk_bf16_f32 v84, v102, v103
	v_cvt_pk_bf16_f32 v85, v100, v101
	global_store_dwordx4 v[92:93], v[82:85], off offset:256
	s_and_saveexec_b64 s[2:3], s[4:5]
	s_cbranch_execz .LBB0_832
	v_lshlrev_b64 v[82:83], 6, v[176:177]
	v_lshl_add_u64 v[82:83], s[10:11], 0, v[82:83]
	v_lshl_add_u64 v[82:83], s[8:9], 2, v[82:83]
	s_lshl_b32 s12, s36, 2
	v_lshl_add_u64 v[82:83], v[82:83], 0, s[12:13]
	s_waitcnt lgkmcnt(0)
	v_add_f32_e32 v80, v80, v81
	global_store_dword v[82:83], v80, off
; __device__ __forceinline__ unsigned cvt_pk_bf16(float lo, float hi) { unsigned r; asm volatile("v_cvt_pk_bf16_f32 %0, %1, %2" : "=v"(r) : "v"(lo), "v"(hi)); return r; }
; __device__ __forceinline__ float bf_lo(unsigned w) { return __uint_as_float(w << 16); }
; __device__ __forceinline__ float bf_hi(unsigned w) { return __uint_as_float(w & 0xffff0000u); }
;     __device__ __forceinline__ void operator()(const f32x4 (&acc)[2][2][4][2], const Unit& u, int wr, int wc, int fr, int fq) const {
;     ...
;             for (int mm = 0; mm < RB; ++mm) { const size_t off = (size_t)(row0 + ai * HALF + (mh + mm) * 16) * D_MODEL + col0;
; #pragma unroll
;                 for (int bj = 0; bj < 2; ++bj) {
;                     if (BASE_F32) { bf[mm][bj][0] = *(const f32x4*)(basef + off + bj * HALF); bf[mm][bj][1] = *(const f32x4*)(basef + off + bj * HALF + 4); }
;                     else bb[mm][bj] = *(const u32x4*)(xb + off + bj * HALF);
;                 } }
;             asm volatile("" ::: "memory");
; #pragma unroll
;             for (int mm = 0; mm < RB; ++mm) {
;                 const int m = mh + mm;
;                 const int row = row0 + ai * HALF + m * 16; const size_t off = (size_t)row * D_MODEL + col0; float s = 0.f;
; #pragma unroll
;                 for (int bj = 0; bj < 2; ++bj) {
;                     f32x4 b0, b1;
;                     if (BASE_F32) { b0 = bf[mm][bj][0]; b1 = bf[mm][bj][1]; }
;                     else { const u32x4 w = bb[mm][bj]; b0 = (f32x4){bf_lo(w.x), bf_hi(w.x), bf_lo(w.y), bf_hi(w.y)}; b1 = (f32x4){bf_lo(w.z), bf_hi(w.z), bf_lo(w.w), bf_hi(w.w)}; }
;                     const f32x4 o0 = b0 + acc[ai][bj][m][0] * alpha, o1 = b1 + acc[ai][bj][m][1] * alpha;
;                     if (OUT_F32) { *(f32x4*)(out + off + bj * HALF) = o0; *(f32x4*)(out + off + bj * HALF + 4) = o1; }
;                     else { u32x4 w; w.x = cvt_pk_bf16(o0[0], o0[1]); w.y = cvt_pk_bf16(o0[2], o0[3]); w.z = cvt_pk_bf16(o1[0], o1[1]); w.w = cvt_pk_bf16(o1[2], o1[3]); *(u32x4*)(xb + off + bj * HALF) = w; }
;                     s += ((o0[0] * o0[0] + o0[1] * o0[1]) + (o0[2] * o0[2] + o0[3] * o0[3])) + ((o1[0] * o1[0] + o1[1] * o1[1]) + (o1[2] * o1[2] + o1[3] * o1[3]));
;                 }
;                 if (ssp) { s += __shfl_xor(s, 16); s += __shfl_xor(s, 32); if (fq == 0) ssp[(size_t)row * 16 + u.pn * 4 + wc] = s; }
.LBB0_832:
	s_or_b64 exec, exec, s[2:3]
	v_lshlrev_b32_e32 v80, 16, v132
	s_waitcnt lgkmcnt(0)
	v_and_b32_e32 v81, 0xffff0000, v132
	v_lshlrev_b32_e32 v82, 16, v133
	v_and_b32_e32 v83, 0xffff0000, v133
	v_lshlrev_b32_e32 v86, 16, v135
	v_and_b32_e32 v87, 0xffff0000, v135
	v_pk_add_f32 v[78:79], v[78:79], v[82:83]
	v_pk_add_f32 v[76:77], v[76:77], v[80:81]
	v_pk_add_f32 v[80:81], v[74:75], v[86:87]
	v_lshlrev_b32_e32 v86, 16, v129
	v_and_b32_e32 v87, 0xffff0000, v129
	v_lshlrev_b32_e32 v88, 16, v130
	v_and_b32_e32 v89, 0xffff0000, v130
	v_lshlrev_b32_e32 v84, 16, v134
	v_and_b32_e32 v85, 0xffff0000, v134
	v_pk_add_f32 v[70:71], v[70:71], v[86:87]
	v_pk_add_f32 v[86:87], v[64:65], v[88:89]
	v_mul_f32_e32 v64, v77, v77
	v_mul_f32_e32 v65, v79, v79
	v_pk_add_f32 v[82:83], v[72:73], v[84:85]
	v_lshlrev_b32_e32 v84, 16, v128
	v_and_b32_e32 v85, 0xffff0000, v128
	v_lshlrev_b32_e32 v90, 16, v131
	v_and_b32_e32 v91, 0xffff0000, v131
	v_fmac_f32_e32 v64, v76, v76
	v_fmac_f32_e32 v65, v78, v78
	v_pk_add_f32 v[68:69], v[68:69], v[84:85]
	v_pk_add_f32 v[84:85], v[66:67], v[90:91]
	v_add_f32_e32 v64, v64, v65
	v_mul_f32_e32 v65, v83, v83
	v_mul_f32_e32 v66, v81, v81
	v_fmac_f32_e32 v65, v82, v82
	v_fmac_f32_e32 v66, v80, v80
	v_add_f32_e32 v65, v65, v66
	v_add_f32_e32 v64, v64, v65
	v_mul_f32_e32 v65, v69, v69
	v_mul_f32_e32 v66, v71, v71
	v_fmac_f32_e32 v65, v68, v68
	v_fmac_f32_e32 v66, v70, v70
	v_add_f32_e32 v65, v65, v66
	v_mul_f32_e32 v66, v87, v87
	v_mul_f32_e32 v67, v85, v85
	v_fmac_f32_e32 v66, v86, v86
	v_fmac_f32_e32 v67, v84, v84
	v_add_f32_e32 v66, v66, v67
	v_add_f32_e32 v65, v65, v66
	v_add_f32_e32 v67, v64, v65
	v_cvt_pk_bf16_f32 v72, v76, v77
	v_cvt_pk_bf16_f32 v73, v78, v79
	v_mov_b32_e32 v236, v67
	v_mov_b32_e32 v237, v67
	s_nop 1
	v_permlane16_swap_b32_e32 v236, v237
	v_cndmask_b32_e64 v78, v237, v236, s[98:99]
	v_readlane_b32 s2, v235, 38
	v_readlane_b32 s3, v235, 39
	v_cvt_pk_bf16_f32 v74, v82, v83
	v_cvt_pk_bf16_f32 v75, v80, v81
	s_nop 1
	v_lshl_add_u64 v[64:65], s[2:3], 0, v[174:175]
	v_lshl_add_u64 v[76:77], v[166:167], 1, v[64:65]
	s_waitcnt lgkmcnt(0)
	v_add_f32_e32 v64, v67, v78
	v_mov_b32_e32 v236, v64
	v_mov_b32_e32 v237, v64
	s_nop 1
	v_permlane32_swap_b32_e32 v236, v237
	v_cndmask_b32_e64 v65, v237, v236, s[100:101]
	global_store_dwordx4 v[76:77], v[72:75], off
	v_cvt_pk_bf16_f32 v66, v68, v69
	v_cvt_pk_bf16_f32 v67, v70, v71
	v_cvt_pk_bf16_f32 v68, v86, v87
	v_cvt_pk_bf16_f32 v69, v84, v85
	global_store_dwordx4 v[76:77], v[66:69], off offset:256
	s_and_saveexec_b64 s[2:3], s[4:5]
	s_cbranch_execz .LBB0_834
	v_lshlrev_b64 v[66:67], 6, v[172:173]
	v_lshl_add_u64 v[66:67], s[10:11], 0, v[66:67]
	v_lshl_add_u64 v[66:67], s[8:9], 2, v[66:67]
	s_lshl_b32 s12, s36, 2
	v_lshl_add_u64 v[66:67], v[66:67], 0, s[12:13]
	s_waitcnt lgkmcnt(0)
	v_add_f32_e32 v64, v64, v65
	global_store_dword v[66:67], v64, off
.LBB0_834:
	s_or_b64 exec, exec, s[2:3]
	v_add_u32_e32 v100, 0x80, v168
	v_ashrrev_i32_e32 v101, 31, v100
	v_lshlrev_b64 v[110:111], 11, v[100:101]
	s_waitcnt lgkmcnt(0)
	v_lshl_add_u64 v[64:65], v[170:171], 0, v[110:111]
	global_load_dwordx4 v[102:105], v[64:65], off
	global_load_dwordx4 v[106:109], v[64:65], off offset:256
	v_add_u32_e32 v96, 0x90, v168
	v_add_u32_e32 v92, 0xa0, v168
	v_add_u32_e32 v88, 0xb0, v168
	v_ashrrev_i32_e32 v97, 31, v96
	v_ashrrev_i32_e32 v93, 31, v92
	v_ashrrev_i32_e32 v89, 31, v88
	v_lshlrev_b64 v[98:99], 11, v[96:97]
	v_lshlrev_b64 v[94:95], 11, v[92:93]
	v_lshlrev_b64 v[90:91], 11, v[88:89]
	v_lshl_add_u64 v[64:65], v[170:171], 0, v[98:99]
	v_lshl_add_u64 v[66:67], v[170:171], 0, v[94:95]
	v_lshl_add_u64 v[114:115], v[170:171], 0, v[90:91]
	global_load_dwordx4 v[84:87], v[64:65], off
	global_load_dwordx4 v[80:83], v[64:65], off offset:256
	global_load_dwordx4 v[76:79], v[66:67], off
	global_load_dwordx4 v[72:75], v[66:67], off offset:256
	global_load_dwordx4 v[68:71], v[114:115], off
	s_nop 0
	global_load_dwordx4 v[64:67], v[114:115], off offset:256
	v_readlane_b32 s2, v235, 38
	v_readlane_b32 s3, v235, 39
	s_waitcnt vmcnt(7)
	v_lshlrev_b32_e32 v114, 16, v102
	v_and_b32_e32 v115, 0xffff0000, v102
	v_lshlrev_b32_e32 v102, 16, v103
	v_and_b32_e32 v103, 0xffff0000, v103
	v_lshlrev_b32_e32 v116, 16, v104
	v_and_b32_e32 v117, 0xffff0000, v104
	v_lshlrev_b32_e32 v104, 16, v105
	v_and_b32_e32 v105, 0xffff0000, v105
	s_waitcnt vmcnt(6)
	v_lshlrev_b32_e32 v118, 16, v106
	v_and_b32_e32 v119, 0xffff0000, v106
	v_lshlrev_b32_e32 v106, 16, v107
	v_and_b32_e32 v107, 0xffff0000, v107
	v_lshlrev_b32_e32 v120, 16, v108
	v_and_b32_e32 v121, 0xffff0000, v108
	v_lshlrev_b32_e32 v108, 16, v109
	v_and_b32_e32 v109, 0xffff0000, v109
	v_pk_add_f32 v[62:63], v[62:63], v[102:103]
	v_pk_add_f32 v[60:61], v[60:61], v[114:115]
	v_pk_add_f32 v[58:59], v[58:59], v[104:105]
	v_pk_add_f32 v[56:57], v[56:57], v[116:117]
	v_pk_add_f32 v[54:55], v[54:55], v[106:107]
	v_pk_add_f32 v[52:53], v[52:53], v[118:119]
	v_pk_add_f32 v[102:103], v[50:51], v[108:109]
	v_pk_add_f32 v[104:105], v[48:49], v[120:121]
	v_cvt_pk_bf16_f32 v48, v60, v61
	v_cvt_pk_bf16_f32 v49, v62, v63
	v_cvt_pk_bf16_f32 v50, v56, v57
	v_cvt_pk_bf16_f32 v51, v58, v59
	v_mul_f32_e32 v61, v61, v61
	v_mul_f32_e32 v63, v63, v63
	v_mul_f32_e32 v57, v57, v57
	v_mul_f32_e32 v59, v59, v59
	v_mul_f32_e32 v106, v53, v53
	v_mul_f32_e32 v107, v55, v55
	v_mul_f32_e32 v108, v105, v105
	v_mul_f32_e32 v109, v103, v103
	v_fmac_f32_e32 v61, v60, v60
	v_fmac_f32_e32 v63, v62, v62
	v_fmac_f32_e32 v57, v56, v56
	v_fmac_f32_e32 v59, v58, v58
	v_fmac_f32_e32 v106, v52, v52
	v_fmac_f32_e32 v107, v54, v54
	v_fmac_f32_e32 v108, v104, v104
	v_fmac_f32_e32 v109, v102, v102
	v_add_f32_e32 v56, v61, v63
	v_add_f32_e32 v57, v57, v59
	v_add_f32_e32 v58, v106, v107
	v_add_f32_e32 v59, v108, v109
	v_add_f32_e32 v56, v56, v57
	v_add_f32_e32 v57, v58, v59
	v_add_f32_e32 v58, v56, v57
	v_mov_b32_e32 v236, v58
	v_mov_b32_e32 v237, v58
	s_nop 1
	v_permlane16_swap_b32_e32 v236, v237
	v_cndmask_b32_e64 v59, v237, v236, s[98:99]
	v_lshl_add_u64 v[56:57], s[2:3], 0, v[110:111]
	v_lshl_add_u64 v[56:57], v[166:167], 1, v[56:57]
	global_store_dwordx4 v[56:57], v[48:51], off
	s_waitcnt lgkmcnt(0)
	s_nop 0
	v_add_f32_e32 v48, v58, v59
	v_mov_b32_e32 v236, v48
	v_mov_b32_e32 v237, v48
	s_nop 1
	v_permlane32_swap_b32_e32 v236, v237
	v_cndmask_b32_e64 v49, v237, v236, s[100:101]
	v_cvt_pk_bf16_f32 v50, v52, v53
	v_cvt_pk_bf16_f32 v51, v54, v55
	v_cvt_pk_bf16_f32 v52, v104, v105
	v_cvt_pk_bf16_f32 v53, v102, v103
	global_store_dwordx4 v[56:57], v[50:53], off offset:256
	s_and_saveexec_b64 s[2:3], s[4:5]
	s_cbranch_execz .LBB0_836
	v_lshlrev_b64 v[50:51], 6, v[100:101]
	v_lshl_add_u64 v[50:51], s[10:11], 0, v[50:51]
	v_lshl_add_u64 v[50:51], s[8:9], 2, v[50:51]
	s_lshl_b32 s12, s36, 2
	v_lshl_add_u64 v[50:51], v[50:51], 0, s[12:13]
	s_waitcnt lgkmcnt(0)
	v_add_f32_e32 v48, v48, v49
	global_store_dword v[50:51], v48, off
; __device__ __forceinline__ unsigned cvt_pk_bf16(float lo, float hi) { unsigned r; asm volatile("v_cvt_pk_bf16_f32 %0, %1, %2" : "=v"(r) : "v"(lo), "v"(hi)); return r; }
; __device__ __forceinline__ float bf_lo(unsigned w) { return __uint_as_float(w << 16); }
; __device__ __forceinline__ float bf_hi(unsigned w) { return __uint_as_float(w & 0xffff0000u); }
;     __device__ __forceinline__ void operator()(const f32x4 (&acc)[2][2][4][2], const Unit& u, int wr, int wc, int fr, int fq) const {
;     ...
;             for (int mm = 0; mm < RB; ++mm) {
;                 const int m = mh + mm;
;                 const int row = row0 + ai * HALF + m * 16; const size_t off = (size_t)row * D_MODEL + col0; float s = 0.f;
; #pragma unroll
;                 for (int bj = 0; bj < 2; ++bj) {
;                     f32x4 b0, b1;
;                     if (BASE_F32) { b0 = bf[mm][bj][0]; b1 = bf[mm][bj][1]; }
;                     else { const u32x4 w = bb[mm][bj]; b0 = (f32x4){bf_lo(w.x), bf_hi(w.x), bf_lo(w.y), bf_hi(w.y)}; b1 = (f32x4){bf_lo(w.z), bf_hi(w.z), bf_lo(w.w), bf_hi(w.w)}; }
;                     const f32x4 o0 = b0 + acc[ai][bj][m][0] * alpha, o1 = b1 + acc[ai][bj][m][1] * alpha;
;                     if (OUT_F32) { *(f32x4*)(out + off + bj * HALF) = o0; *(f32x4*)(out + off + bj * HALF + 4) = o1; }
;                     else { u32x4 w; w.x = cvt_pk_bf16(o0[0], o0[1]); w.y = cvt_pk_bf16(o0[2], o0[3]); w.z = cvt_pk_bf16(o1[0], o1[1]); w.w = cvt_pk_bf16(o1[2], o1[3]); *(u32x4*)(xb + off + bj * HALF) = w; }
;                     s += ((o0[0] * o0[0] + o0[1] * o0[1]) + (o0[2] * o0[2] + o0[3] * o0[3])) + ((o1[0] * o1[0] + o1[1] * o1[1]) + (o1[2] * o1[2] + o1[3] * o1[3]));
;                 }
;                 if (ssp) { s += __shfl_xor(s, 16); s += __shfl_xor(s, 32); if (fq == 0) ssp[(size_t)row * 16 + u.pn * 4 + wc] = s; }
.LBB0_836:
	s_or_b64 exec, exec, s[2:3]
	s_waitcnt vmcnt(7)
	v_lshlrev_b32_e32 v48, 16, v84
	s_waitcnt lgkmcnt(0)
	v_and_b32_e32 v49, 0xffff0000, v84
	v_lshlrev_b32_e32 v50, 16, v85
	v_and_b32_e32 v51, 0xffff0000, v85
	v_lshlrev_b32_e32 v54, 16, v87
	v_and_b32_e32 v55, 0xffff0000, v87
	v_pk_add_f32 v[46:47], v[46:47], v[50:51]
	v_pk_add_f32 v[44:45], v[44:45], v[48:49]
	v_pk_add_f32 v[48:49], v[42:43], v[54:55]
	s_waitcnt vmcnt(6)
	v_lshlrev_b32_e32 v54, 16, v81
	v_and_b32_e32 v55, 0xffff0000, v81
	v_lshlrev_b32_e32 v56, 16, v82
	v_and_b32_e32 v57, 0xffff0000, v82
	v_lshlrev_b32_e32 v52, 16, v86
	v_and_b32_e32 v53, 0xffff0000, v86
	v_pk_add_f32 v[38:39], v[38:39], v[54:55]
	v_pk_add_f32 v[54:55], v[32:33], v[56:57]
	v_mul_f32_e32 v32, v45, v45
	v_mul_f32_e32 v33, v47, v47
	v_pk_add_f32 v[50:51], v[40:41], v[52:53]
	v_lshlrev_b32_e32 v52, 16, v80
	v_and_b32_e32 v53, 0xffff0000, v80
	v_lshlrev_b32_e32 v58, 16, v83
	v_and_b32_e32 v59, 0xffff0000, v83
	v_fmac_f32_e32 v32, v44, v44
	v_fmac_f32_e32 v33, v46, v46
	v_pk_add_f32 v[36:37], v[36:37], v[52:53]
	v_pk_add_f32 v[52:53], v[34:35], v[58:59]
	v_add_f32_e32 v32, v32, v33
	v_mul_f32_e32 v33, v51, v51
	v_mul_f32_e32 v34, v49, v49
	v_fmac_f32_e32 v33, v50, v50
	v_fmac_f32_e32 v34, v48, v48
	v_add_f32_e32 v33, v33, v34
	v_add_f32_e32 v32, v32, v33
	v_mul_f32_e32 v33, v37, v37
	v_mul_f32_e32 v34, v39, v39
	v_fmac_f32_e32 v33, v36, v36
	v_fmac_f32_e32 v34, v38, v38
	v_add_f32_e32 v33, v33, v34
	v_mul_f32_e32 v34, v55, v55
	v_mul_f32_e32 v35, v53, v53
	v_fmac_f32_e32 v34, v54, v54
	v_fmac_f32_e32 v35, v52, v52
	v_add_f32_e32 v34, v34, v35
	v_add_f32_e32 v33, v33, v34
	v_add_f32_e32 v35, v32, v33
	v_cvt_pk_bf16_f32 v40, v44, v45
	v_cvt_pk_bf16_f32 v41, v46, v47
	v_mov_b32_e32 v236, v35
	v_mov_b32_e32 v237, v35
	s_nop 1
	v_permlane16_swap_b32_e32 v236, v237
	v_cndmask_b32_e64 v46, v237, v236, s[98:99]
	v_readlane_b32 s2, v235, 38
	v_readlane_b32 s3, v235, 39
	v_cvt_pk_bf16_f32 v42, v50, v51
	v_cvt_pk_bf16_f32 v43, v48, v49
	s_nop 1
	v_lshl_add_u64 v[32:33], s[2:3], 0, v[98:99]
	v_lshl_add_u64 v[44:45], v[166:167], 1, v[32:33]
	s_waitcnt lgkmcnt(0)
	v_add_f32_e32 v32, v35, v46
	v_mov_b32_e32 v236, v32
	v_mov_b32_e32 v237, v32
	s_nop 1
	v_permlane32_swap_b32_e32 v236, v237
	v_cndmask_b32_e64 v33, v237, v236, s[100:101]
	global_store_dwordx4 v[44:45], v[40:43], off
	v_cvt_pk_bf16_f32 v34, v36, v37
	v_cvt_pk_bf16_f32 v35, v38, v39
	v_cvt_pk_bf16_f32 v36, v54, v55
	v_cvt_pk_bf16_f32 v37, v52, v53
	global_store_dwordx4 v[44:45], v[34:37], off offset:256
	s_and_saveexec_b64 s[2:3], s[4:5]
	s_cbranch_execz .LBB0_838
	v_lshlrev_b64 v[34:35], 6, v[96:97]
	v_lshl_add_u64 v[34:35], s[10:11], 0, v[34:35]
	v_lshl_add_u64 v[34:35], s[8:9], 2, v[34:35]
	s_lshl_b32 s12, s36, 2
	v_lshl_add_u64 v[34:35], v[34:35], 0, s[12:13]
	s_waitcnt lgkmcnt(0)
	v_add_f32_e32 v32, v32, v33
	global_store_dword v[34:35], v32, off
; __device__ __forceinline__ unsigned cvt_pk_bf16(float lo, float hi) { unsigned r; asm volatile("v_cvt_pk_bf16_f32 %0, %1, %2" : "=v"(r) : "v"(lo), "v"(hi)); return r; }
; __device__ __forceinline__ float bf_lo(unsigned w) { return __uint_as_float(w << 16); }
; __device__ __forceinline__ float bf_hi(unsigned w) { return __uint_as_float(w & 0xffff0000u); }
;     __device__ __forceinline__ void operator()(const f32x4 (&acc)[2][2][4][2], const Unit& u, int wr, int wc, int fr, int fq) const {
;     ...
;             for (int mm = 0; mm < RB; ++mm) {
;                 const int m = mh + mm;
;                 const int row = row0 + ai * HALF + m * 16; const size_t off = (size_t)row * D_MODEL + col0; float s = 0.f;
; #pragma unroll
;                 for (int bj = 0; bj < 2; ++bj) {
;                     f32x4 b0, b1;
;                     if (BASE_F32) { b0 = bf[mm][bj][0]; b1 = bf[mm][bj][1]; }
;                     else { const u32x4 w = bb[mm][bj]; b0 = (f32x4){bf_lo(w.x), bf_hi(w.x), bf_lo(w.y), bf_hi(w.y)}; b1 = (f32x4){bf_lo(w.z), bf_hi(w.z), bf_lo(w.w), bf_hi(w.w)}; }
;                     const f32x4 o0 = b0 + acc[ai][bj][m][0] * alpha, o1 = b1 + acc[ai][bj][m][1] * alpha;
;                     if (OUT_F32) { *(f32x4*)(out + off + bj * HALF) = o0; *(f32x4*)(out + off + bj * HALF + 4) = o1; }
;                     else { u32x4 w; w.x = cvt_pk_bf16(o0[0], o0[1]); w.y = cvt_pk_bf16(o0[2], o0[3]); w.z = cvt_pk_bf16(o1[0], o1[1]); w.w = cvt_pk_bf16(o1[2], o1[3]); *(u32x4*)(xb + off + bj * HALF) = w; }
;                     s += ((o0[0] * o0[0] + o0[1] * o0[1]) + (o0[2] * o0[2] + o0[3] * o0[3])) + ((o1[0] * o1[0] + o1[1] * o1[1]) + (o1[2] * o1[2] + o1[3] * o1[3]));
;                 }
;                 if (ssp) { s += __shfl_xor(s, 16); s += __shfl_xor(s, 32); if (fq == 0) ssp[(size_t)row * 16 + u.pn * 4 + wc] = s; }
;             }
.LBB0_838:
	s_or_b64 exec, exec, s[2:3]
	s_waitcnt vmcnt(7)
	v_lshlrev_b32_e32 v32, 16, v76
	s_waitcnt lgkmcnt(0)
	v_and_b32_e32 v33, 0xffff0000, v76
	v_lshlrev_b32_e32 v34, 16, v77
	v_and_b32_e32 v35, 0xffff0000, v77
	v_lshlrev_b32_e32 v38, 16, v79
	v_and_b32_e32 v39, 0xffff0000, v79
	v_pk_add_f32 v[30:31], v[30:31], v[34:35]
	v_pk_add_f32 v[28:29], v[28:29], v[32:33]
	v_pk_add_f32 v[32:33], v[26:27], v[38:39]
	s_waitcnt vmcnt(6)
	v_lshlrev_b32_e32 v38, 16, v73
	v_and_b32_e32 v39, 0xffff0000, v73
	v_lshlrev_b32_e32 v40, 16, v74
	v_and_b32_e32 v41, 0xffff0000, v74
	v_lshlrev_b32_e32 v36, 16, v78
	v_and_b32_e32 v37, 0xffff0000, v78
	v_pk_add_f32 v[22:23], v[22:23], v[38:39]
	v_pk_add_f32 v[38:39], v[16:17], v[40:41]
	v_mul_f32_e32 v16, v29, v29
	v_mul_f32_e32 v17, v31, v31
	v_pk_add_f32 v[34:35], v[24:25], v[36:37]
	v_lshlrev_b32_e32 v36, 16, v72
	v_and_b32_e32 v37, 0xffff0000, v72
	v_lshlrev_b32_e32 v42, 16, v75
	v_and_b32_e32 v43, 0xffff0000, v75
	v_fmac_f32_e32 v16, v28, v28
	v_fmac_f32_e32 v17, v30, v30
	v_pk_add_f32 v[20:21], v[20:21], v[36:37]
	v_pk_add_f32 v[36:37], v[18:19], v[42:43]
	v_add_f32_e32 v16, v16, v17
	v_mul_f32_e32 v17, v35, v35
	v_mul_f32_e32 v18, v33, v33
	v_fmac_f32_e32 v17, v34, v34
	v_fmac_f32_e32 v18, v32, v32
	v_add_f32_e32 v17, v17, v18
	v_add_f32_e32 v16, v16, v17
	v_mul_f32_e32 v17, v21, v21
	v_mul_f32_e32 v18, v23, v23
	v_fmac_f32_e32 v17, v20, v20
	v_fmac_f32_e32 v18, v22, v22
	v_add_f32_e32 v17, v17, v18
	v_mul_f32_e32 v18, v39, v39
	v_mul_f32_e32 v19, v37, v37
	v_fmac_f32_e32 v18, v38, v38
	v_fmac_f32_e32 v19, v36, v36
	v_add_f32_e32 v18, v18, v19
	v_add_f32_e32 v17, v17, v18
	v_add_f32_e32 v19, v16, v17
	v_cvt_pk_bf16_f32 v24, v28, v29
	v_cvt_pk_bf16_f32 v25, v30, v31
	v_mov_b32_e32 v236, v19
	v_mov_b32_e32 v237, v19
	s_nop 1
	v_permlane16_swap_b32_e32 v236, v237
	v_cndmask_b32_e64 v30, v237, v236, s[98:99]
	v_readlane_b32 s2, v235, 38
	v_readlane_b32 s3, v235, 39
	v_cvt_pk_bf16_f32 v26, v34, v35
	v_cvt_pk_bf16_f32 v27, v32, v33
	s_nop 1
	v_lshl_add_u64 v[16:17], s[2:3], 0, v[94:95]
	v_lshl_add_u64 v[28:29], v[166:167], 1, v[16:17]
	s_waitcnt lgkmcnt(0)
	v_add_f32_e32 v16, v19, v30
	v_mov_b32_e32 v236, v16
	v_mov_b32_e32 v237, v16
	s_nop 1
	v_permlane32_swap_b32_e32 v236, v237
	v_cndmask_b32_e64 v17, v237, v236, s[100:101]
	global_store_dwordx4 v[28:29], v[24:27], off
	v_cvt_pk_bf16_f32 v18, v20, v21
	v_cvt_pk_bf16_f32 v19, v22, v23
	v_cvt_pk_bf16_f32 v20, v38, v39
	v_cvt_pk_bf16_f32 v21, v36, v37
	global_store_dwordx4 v[28:29], v[18:21], off offset:256
	s_and_saveexec_b64 s[2:3], s[4:5]
	s_cbranch_execz .LBB0_840
	v_lshlrev_b64 v[18:19], 6, v[92:93]
	v_lshl_add_u64 v[18:19], s[10:11], 0, v[18:19]
	v_lshl_add_u64 v[18:19], s[8:9], 2, v[18:19]
	s_lshl_b32 s12, s36, 2
	v_lshl_add_u64 v[18:19], v[18:19], 0, s[12:13]
	s_waitcnt lgkmcnt(0)
	v_add_f32_e32 v16, v16, v17
	global_store_dword v[18:19], v16, off
.LBB0_840:
	s_or_b64 exec, exec, s[2:3]
	s_waitcnt vmcnt(7)
	v_lshlrev_b32_e32 v16, 16, v68
	s_waitcnt lgkmcnt(0)
	v_and_b32_e32 v17, 0xffff0000, v68
	v_lshlrev_b32_e32 v18, 16, v69
	v_and_b32_e32 v19, 0xffff0000, v69
	v_lshlrev_b32_e32 v22, 16, v71
	v_and_b32_e32 v23, 0xffff0000, v71
	v_pk_add_f32 v[14:15], v[14:15], v[18:19]
	v_pk_add_f32 v[12:13], v[12:13], v[16:17]
	v_pk_add_f32 v[16:17], v[10:11], v[22:23]
	s_waitcnt vmcnt(6)
	v_lshlrev_b32_e32 v22, 16, v65
	v_and_b32_e32 v23, 0xffff0000, v65
	v_lshlrev_b32_e32 v24, 16, v66
	v_and_b32_e32 v25, 0xffff0000, v66
	v_lshlrev_b32_e32 v20, 16, v70
	v_and_b32_e32 v21, 0xffff0000, v70
	v_pk_add_f32 v[6:7], v[6:7], v[22:23]
	v_pk_add_f32 v[22:23], v[0:1], v[24:25]
	v_mul_f32_e32 v0, v13, v13
	v_mul_f32_e32 v1, v15, v15
	v_pk_add_f32 v[18:19], v[8:9], v[20:21]
	v_lshlrev_b32_e32 v20, 16, v64
	v_and_b32_e32 v21, 0xffff0000, v64
	v_lshlrev_b32_e32 v26, 16, v67
	v_and_b32_e32 v27, 0xffff0000, v67
	v_fmac_f32_e32 v0, v12, v12
	v_fmac_f32_e32 v1, v14, v14
	v_pk_add_f32 v[4:5], v[4:5], v[20:21]
	v_pk_add_f32 v[20:21], v[2:3], v[26:27]
	v_add_f32_e32 v0, v0, v1
	v_mul_f32_e32 v1, v19, v19
	v_mul_f32_e32 v2, v17, v17
	v_fmac_f32_e32 v1, v18, v18
	v_fmac_f32_e32 v2, v16, v16
	v_add_f32_e32 v1, v1, v2
	v_add_f32_e32 v0, v0, v1
	v_mul_f32_e32 v1, v5, v5
	v_mul_f32_e32 v2, v7, v7
	v_fmac_f32_e32 v1, v4, v4
	v_fmac_f32_e32 v2, v6, v6
	v_add_f32_e32 v1, v1, v2
	v_mul_f32_e32 v2, v23, v23
	v_mul_f32_e32 v3, v21, v21
	v_fmac_f32_e32 v2, v22, v22
	v_fmac_f32_e32 v3, v20, v20
	v_add_f32_e32 v2, v2, v3
	v_add_f32_e32 v1, v1, v2
	v_add_f32_e32 v3, v0, v1
	v_cvt_pk_bf16_f32 v8, v12, v13
	v_cvt_pk_bf16_f32 v9, v14, v15
	v_mov_b32_e32 v236, v3
	v_mov_b32_e32 v237, v3
	s_nop 1
	v_permlane16_swap_b32_e32 v236, v237
	v_cndmask_b32_e64 v14, v237, v236, s[98:99]
	v_readlane_b32 s2, v235, 38
	v_readlane_b32 s3, v235, 39
	v_cvt_pk_bf16_f32 v10, v18, v19
	v_cvt_pk_bf16_f32 v11, v16, v17
	s_nop 1
	v_lshl_add_u64 v[0:1], s[2:3], 0, v[90:91]
	v_lshl_add_u64 v[12:13], v[166:167], 1, v[0:1]
	s_waitcnt lgkmcnt(0)
	v_add_f32_e32 v0, v3, v14
	v_mov_b32_e32 v236, v0
	v_mov_b32_e32 v237, v0
	s_nop 1
	v_permlane32_swap_b32_e32 v236, v237
	v_cndmask_b32_e64 v1, v237, v236, s[100:101]
	global_store_dwordx4 v[12:13], v[8:11], off
	v_cvt_pk_bf16_f32 v2, v4, v5
	v_cvt_pk_bf16_f32 v3, v6, v7
	v_cvt_pk_bf16_f32 v4, v22, v23
	v_cvt_pk_bf16_f32 v5, v20, v21
	global_store_dwordx4 v[12:13], v[2:5], off offset:256
	s_and_saveexec_b64 s[2:3], s[4:5]
	s_cbranch_execz .LBB0_842
	v_lshlrev_b64 v[2:3], 6, v[88:89]
	v_lshl_add_u64 v[2:3], s[10:11], 0, v[2:3]
	v_lshl_add_u64 v[2:3], s[8:9], 2, v[2:3]
	s_lshl_b32 s12, s36, 2
	v_lshl_add_u64 v[2:3], v[2:3], 0, s[12:13]
	s_waitcnt lgkmcnt(0)
	v_add_f32_e32 v0, v0, v1
	global_store_dword v[2:3], v0, off

; template <int NP> __device__ __forceinline__ void load_rs(const float* ssp, int row0, int fq, float (&rs)[2][4]) {
;     ...
;             for (int m = 0; m < 4; ++m) p[ai][m] = *(const f32x4*)(ssp + (size_t)(row0 + ai * HALF + m * 16) * 16 + 4 * fq);
; #pragma unroll
;         for (int ai = 0; ai < 2; ++ai)
; #pragma unroll
;             for (int m = 0; m < 4; ++m) { float s = (p[ai][m][0] + p[ai][m][1]) + (p[ai][m][2] + p[ai][m][3]); s += __shfl_xor(s, 16); s += __shfl_xor(s, 32); rs[ai][m] = s; }
;     __device__ __forceinline__ void operator()(const f32x4 (&acc)[2][2][4][2], const Unit& u, int wr, int wc, int fr, int fq) const {
;     ...
;                     const f32x4 ga = acc[ai][0][m][q >> 1], ua = acc[ai][1][m][q >> 1]; const int e0 = 2 * (q & 1);
;                     const f32x2 g = (f32x2){ga[e0], ga[e0 + 1]}, up = (f32x2){ua[e0], ua[e0 + 1]};
;                     const f32x2 t = g * nrl; f32x2 ex; ex.x = __builtin_amdgcn_exp2f(t.x); ex.y = __builtin_amdgcn_exp2f(t.y);
;                     const f32x2 d = ex + 1.0f; f32x2 rc; rc.x = __builtin_amdgcn_rcpf(d.x); rc.y = __builtin_amdgcn_rcpf(d.y);
;                     const f32x2 o = (g * up) * (rc * r2);
.LBB0_932:
	s_lshl_b32 s2, s41, 8
	s_add_i32 s2, s2, s29
	v_or_b32_e32 v146, s2, v150
	v_ashrrev_i32_e32 v147, 31, v146
	v_or_b32_e32 v160, 16, v146
	v_lshlrev_b64 v[148:149], 6, v[146:147]
	v_ashrrev_i32_e32 v161, 31, v160
	v_or_b32_e32 v168, 32, v146
	v_or_b32_e32 v170, 48, v146
	v_add_u32_e32 v146, 0x80, v146
	v_lshlrev_b64 v[160:161], 6, v[160:161]
	v_ashrrev_i32_e32 v169, 31, v168
	v_ashrrev_i32_e32 v171, 31, v170
	v_ashrrev_i32_e32 v147, 31, v146
	v_lshl_add_u64 v[148:149], v[138:139], 0, v[148:149]
	v_lshl_add_u64 v[164:165], v[138:139], 0, v[160:161]
	v_lshlrev_b64 v[168:169], 6, v[168:169]
	v_lshlrev_b64 v[170:171], 6, v[170:171]
	v_lshlrev_b64 v[176:177], 6, v[146:147]
	global_load_dwordx4 v[160:163], v[148:149], off
	s_nop 0
	global_load_dwordx4 v[164:167], v[164:165], off
	v_lshl_add_u64 v[168:169], v[138:139], 0, v[168:169]
	v_lshl_add_u64 v[172:173], v[138:139], 0, v[170:171]
	v_lshl_add_u64 v[176:177], v[138:139], 0, v[176:177]
	global_load_dwordx4 v[168:171], v[168:169], off
	s_nop 0
	global_load_dwordx4 v[172:175], v[172:173], off
	v_add_co_u32_e32 v148, vcc, s26, v148
	global_load_dwordx4 v[176:179], v[176:177], off
	s_nop 0
	v_addc_co_u32_e32 v149, vcc, 0, v149, vcc
	global_load_dwordx4 v[180:183], v[148:149], off offset:1024
	global_load_dwordx4 v[184:187], v[148:149], off offset:2048
	global_load_dwordx4 v[190:193], v[148:149], off offset:3072
	v_and_b32_e32 v147, 64, v156
	v_xor_b32_e32 v136, 16, v156
	v_add_u32_e32 v147, 64, v147
	v_xor_b32_e32 v149, 32, v156
	v_cmp_lt_i32_e32 vcc, v136, v147
	v_pk_mul_f32 v[120:121], v[124:125], v[120:121]
	v_pk_mul_f32 v[122:123], v[126:127], v[122:123]
	v_cndmask_b32_e32 v136, v156, v136, vcc
	v_cmp_lt_i32_e32 vcc, v149, v147
	v_lshlrev_b32_e32 v136, 2, v136
	v_pk_mul_f32 v[112:113], v[116:117], v[112:113]
	v_cndmask_b32_e32 v147, v156, v149, vcc
	v_lshlrev_b32_e32 v147, 2, v147
	v_pk_mul_f32 v[114:115], v[118:119], v[114:115]
	v_pk_mul_f32 v[104:105], v[108:109], v[104:105]
	s_ashr_i32 s3, s2, 13
	s_mul_hi_i32 s11, s3, 0x4400000
	s_mul_i32 s3, s3, 0x4400000
	v_readlane_b32 s16, v235, 44
	v_lshl_or_b32 v148, s42, 7, v152
	v_readlane_b32 s17, v235, 45
	v_pk_mul_f32 v[106:107], v[110:111], v[106:107]
	v_pk_mul_f32 v[96:97], v[100:101], v[96:97]
	v_pk_mul_f32 v[98:99], v[102:103], v[98:99]
	v_pk_mul_f32 v[88:89], v[92:93], v[88:89]
	v_pk_mul_f32 v[90:91], v[94:95], v[90:91]
	v_pk_mul_f32 v[80:81], v[84:85], v[80:81]
	v_pk_mul_f32 v[82:83], v[86:87], v[82:83]
	v_pk_mul_f32 v[72:73], v[76:77], v[72:73]
	v_pk_mul_f32 v[74:75], v[78:79], v[74:75]
	v_pk_mul_f32 v[64:65], v[68:69], v[64:65]
	v_pk_mul_f32 v[66:67], v[70:71], v[66:67]
	v_pk_mul_f32 v[56:57], v[60:61], v[56:57]
	v_pk_mul_f32 v[58:59], v[62:63], v[58:59]
	v_pk_mul_f32 v[48:49], v[52:53], v[48:49]
	v_pk_mul_f32 v[50:51], v[54:55], v[50:51]
	v_pk_mul_f32 v[40:41], v[44:45], v[40:41]
	v_pk_mul_f32 v[42:43], v[46:47], v[42:43]
	v_pk_mul_f32 v[32:33], v[36:37], v[32:33]
	v_pk_mul_f32 v[34:35], v[38:39], v[34:35]
	v_pk_mul_f32 v[24:25], v[28:29], v[24:25]
	v_pk_mul_f32 v[26:27], v[30:31], v[26:27]
	v_pk_mul_f32 v[16:17], v[20:21], v[16:17]
	v_pk_mul_f32 v[18:19], v[22:23], v[18:19]
	v_pk_mul_f32 v[8:9], v[12:13], v[8:9]
	v_pk_mul_f32 v[10:11], v[14:15], v[10:11]
	v_pk_mul_f32 v[0:1], v[4:5], v[0:1]
	v_pk_mul_f32 v[2:3], v[6:7], v[2:3]
	s_waitcnt vmcnt(0)
	v_mov_b32_e32 v194, v161
	v_mov_b32_e32 v195, v162
	v_mov_b32_e32 v161, v163
	v_pk_add_f32 v[160:161], v[194:195], v[160:161]
	v_mov_b32_e32 v162, v165
	v_mov_b32_e32 v163, v166
	v_mov_b32_e32 v165, v167
	v_mov_b32_e32 v166, v169
	v_mov_b32_e32 v167, v170
	v_mov_b32_e32 v169, v171
	v_mov_b32_e32 v170, v173
	v_mov_b32_e32 v171, v174
	v_mov_b32_e32 v173, v175
	v_mov_b32_e32 v174, v177
	v_mov_b32_e32 v175, v178
	v_mov_b32_e32 v177, v179
	v_add_f32_e32 v149, v160, v161
	v_pk_add_f32 v[160:161], v[162:163], v[164:165]
	v_pk_add_f32 v[162:163], v[166:167], v[168:169]
	v_pk_add_f32 v[166:167], v[174:175], v[176:177]
	v_add_f32_e32 v160, v160, v161
	v_add_f32_e32 v161, v162, v163
	v_mov_b32_e32 v236, v149
	v_mov_b32_e32 v237, v149
	s_nop 1
	v_permlane16_swap_b32_e32 v236, v237
	v_cndmask_b32_e64 v159, v237, v236, s[98:99]
	v_add_f32_e32 v163, v166, v167
	v_mov_b32_e32 v236, v160
	v_mov_b32_e32 v237, v160
	s_nop 1
	v_permlane16_swap_b32_e32 v236, v237
	v_cndmask_b32_e64 v166, v237, v236, s[98:99]
	v_mov_b32_e32 v236, v161
	v_mov_b32_e32 v237, v161
	s_nop 1
	v_permlane16_swap_b32_e32 v236, v237
	v_cndmask_b32_e64 v167, v237, v236, s[98:99]
	v_mov_b32_e32 v178, v181
	s_waitcnt lgkmcnt(2)
	v_add_f32_e32 v149, v149, v159
	v_mov_b32_e32 v236, v149
	v_mov_b32_e32 v237, v149
	s_nop 1
	v_permlane32_swap_b32_e32 v236, v237
	v_cndmask_b32_e64 v159, v237, v236, s[100:101]
	s_waitcnt lgkmcnt(2)
	v_add_f32_e32 v160, v160, v166
	s_waitcnt lgkmcnt(1)
	v_add_f32_e32 v161, v161, v167
	v_mov_b32_e32 v236, v160
	v_mov_b32_e32 v237, v160
	s_nop 1
	v_permlane32_swap_b32_e32 v236, v237
	v_cndmask_b32_e64 v166, v237, v236, s[100:101]
	v_mov_b32_e32 v236, v161
	v_mov_b32_e32 v237, v161
	s_nop 1
	v_permlane32_swap_b32_e32 v236, v237
	v_cndmask_b32_e64 v167, v237, v236, s[100:101]
	v_mov_b32_e32 v179, v182
	v_mov_b32_e32 v181, v183
	v_mov_b32_e32 v182, v185
	v_mov_b32_e32 v183, v186
	v_mov_b32_e32 v185, v187
	v_mov_b32_e32 v186, v191
	v_mov_b32_e32 v187, v192
	v_mov_b32_e32 v191, v193
	v_pk_add_f32 v[164:165], v[170:171], v[172:173]
	v_pk_add_f32 v[168:169], v[178:179], v[180:181]
	v_pk_add_f32 v[170:171], v[182:183], v[184:185]
	s_waitcnt lgkmcnt(2)
	v_add_f32_e32 v149, v149, v159
	s_waitcnt lgkmcnt(1)
	v_add_f32_e32 v159, v160, v166
	s_waitcnt lgkmcnt(0)
; __device__ __forceinline__ unsigned cvt_pk_bf16(float lo, float hi) { unsigned r; asm volatile("v_cvt_pk_bf16_f32 %0, %1, %2" : "=v"(r) : "v"(lo), "v"(hi)); return r; }
; template <int NP> __device__ __forceinline__ void load_rs(const float* ssp, int row0, int fq, float (&rs)[2][4]) {
;     ...
;             for (int m = 0; m < 4; ++m) { float s = (p[ai][m][0] + p[ai][m][1]) + (p[ai][m][2] + p[ai][m][3]); s += __shfl_xor(s, 16); s += __shfl_xor(s, 32); rs[ai][m] = s; }
;     }
; #pragma unroll
;     for (int ai = 0; ai < 2; ++ai)
; #pragma unroll
;         for (int m = 0; m < 4; ++m) rs[ai][m] = __builtin_amdgcn_rsqf(rs[ai][m] * (1.0f / D_MODEL) + RMS_EPS);
;     __device__ __forceinline__ void operator()(const f32x4 (&acc)[2][2][4][2], const Unit& u, int wr, int wc, int fr, int fq) const {
;     ...
;                 const int row = row0 + ai * HALF + m * 16; const float r = rs[ai][m];
;                 const float nrl = r * -1.44269504089f, r2 = r * r;
;                 unsigned pk[4];
; #pragma unroll
;                 for (int q = 0; q < 4; ++q) {
;                     const f32x4 ga = acc[ai][0][m][q >> 1], ua = acc[ai][1][m][q >> 1]; const int e0 = 2 * (q & 1);
;                     const f32x2 g = (f32x2){ga[e0], ga[e0 + 1]}, up = (f32x2){ua[e0], ua[e0 + 1]};
;                     const f32x2 t = g * nrl; f32x2 ex; ex.x = __builtin_amdgcn_exp2f(t.x); ex.y = __builtin_amdgcn_exp2f(t.y);
;                     const f32x2 d = ex + 1.0f; f32x2 rc; rc.x = __builtin_amdgcn_rcpf(d.x); rc.y = __builtin_amdgcn_rcpf(d.y);
;                     const f32x2 o = (g * up) * (rc * r2);
;                     pk[q] = cvt_pk_bf16(o.x, o.y);
;                 }
;                 u32x4 w; w.x = pk[0]; w.y = pk[1]; w.z = pk[2]; w.w = pk[3];
;                 *(u32x4*)(U + (size_t)(row >> 13) * U_SLAB + (size_t)(row & (SEQ - 1)) * U_PITCH + col0) = w;
	v_add_f32_e32 v166, v161, v167
	v_pk_add_f32 v[160:161], v[186:187], v[190:191]
	v_add_f32_e32 v162, v164, v165
	v_add_f32_e32 v164, v168, v169
	v_add_f32_e32 v165, v170, v171
	v_add_f32_e32 v160, v160, v161
	v_mov_b32_e32 v236, v162
	v_mov_b32_e32 v237, v162
	s_nop 1
	v_permlane16_swap_b32_e32 v236, v237
	v_cndmask_b32_e64 v168, v237, v236, s[98:99]
	v_mov_b32_e32 v236, v163
	v_mov_b32_e32 v237, v163
	s_nop 1
	v_permlane16_swap_b32_e32 v236, v237
	v_cndmask_b32_e64 v169, v237, v236, s[98:99]
	v_mov_b32_e32 v236, v164
	v_mov_b32_e32 v237, v164
	s_nop 1
	v_permlane16_swap_b32_e32 v236, v237
	v_cndmask_b32_e64 v170, v237, v236, s[98:99]
	v_mov_b32_e32 v236, v165
	v_mov_b32_e32 v237, v165
	s_nop 1
	v_permlane16_swap_b32_e32 v236, v237
	v_cndmask_b32_e64 v171, v237, v236, s[98:99]
	v_mov_b32_e32 v236, v160
	v_mov_b32_e32 v237, v160
	s_nop 1
	v_permlane16_swap_b32_e32 v236, v237
	v_cndmask_b32_e64 v136, v237, v236, s[98:99]
	s_waitcnt lgkmcnt(4)
	v_add_f32_e32 v162, v162, v168
	s_waitcnt lgkmcnt(3)
	v_add_f32_e32 v163, v163, v169
	s_waitcnt lgkmcnt(2)
	v_add_f32_e32 v161, v164, v170
	s_waitcnt lgkmcnt(1)
	v_add_f32_e32 v165, v165, v171
	s_waitcnt lgkmcnt(0)
	v_add_f32_e32 v136, v160, v136
	v_mov_b32_e32 v236, v162
	v_mov_b32_e32 v237, v162
	s_nop 1
	v_permlane32_swap_b32_e32 v236, v237
	v_cndmask_b32_e64 v168, v237, v236, s[100:101]
	v_mov_b32_e32 v236, v163
	v_mov_b32_e32 v237, v163
	s_nop 1
	v_permlane32_swap_b32_e32 v236, v237
	v_cndmask_b32_e64 v169, v237, v236, s[100:101]
	v_mov_b32_e32 v236, v161
	v_mov_b32_e32 v237, v161
	s_nop 1
	v_permlane32_swap_b32_e32 v236, v237
	v_cndmask_b32_e64 v164, v237, v236, s[100:101]
	v_mov_b32_e32 v236, v165
	v_mov_b32_e32 v237, v165
	s_nop 1
	v_permlane32_swap_b32_e32 v236, v237
	v_cndmask_b32_e64 v167, v237, v236, s[100:101]
	v_mov_b32_e32 v236, v136
	v_mov_b32_e32 v237, v136
	s_nop 1
	v_permlane32_swap_b32_e32 v236, v237
	v_cndmask_b32_e64 v147, v237, v236, s[100:101]
	s_waitcnt lgkmcnt(4)
	v_add_f32_e32 v160, v162, v168
	s_waitcnt lgkmcnt(3)
	v_add_f32_e32 v162, v163, v169
	s_waitcnt lgkmcnt(2)
	v_add_f32_e32 v161, v161, v164
	s_waitcnt lgkmcnt(1)
	v_add_f32_e32 v163, v165, v167
	s_waitcnt lgkmcnt(0)
	v_add_f32_e32 v136, v136, v147
	v_fmamk_f32 v147, v149, 0x3a800000, v157
	v_rsq_f32_e32 v164, v147
	v_fmamk_f32 v147, v159, 0x3a800000, v157
	v_rsq_f32_e32 v165, v147
	v_fmamk_f32 v147, v166, 0x3a800000, v157
	v_rsq_f32_e32 v166, v147
	v_fmamk_f32 v147, v160, 0x3a800000, v157
	v_rsq_f32_e32 v167, v147
	v_fmamk_f32 v147, v162, 0x3a800000, v157
	v_rsq_f32_e32 v168, v147
	v_fmamk_f32 v147, v161, 0x3a800000, v157
	v_rsq_f32_e32 v160, v147
	v_fmamk_f32 v147, v163, 0x3a800000, v157
	v_fmamk_f32 v136, v136, 0x3a800000, v157
	v_rsq_f32_e32 v159, v147
	v_rsq_f32_e32 v147, v136
	v_mul_f32_e32 v136, 0xbfb8aa3b, v164
	v_pk_mul_f32 v[162:163], v[124:125], v[136:137] op_sel_hi:[1,0]
	v_pk_mul_f32 v[124:125], v[126:127], v[136:137] op_sel_hi:[1,0]
	v_exp_f32_e32 v162, v162
	v_exp_f32_e32 v163, v163
	v_exp_f32_e32 v124, v124
	v_exp_f32_e32 v125, v125
	v_mul_f32_e32 v164, v164, v164
	v_pk_add_f32 v[162:163], v[162:163], 1.0 op_sel_hi:[1,0]
	v_bitop3_b32 v161, s2, v158, v150 bitop3:0xc8
	v_rcp_f32_e32 v162, v162
	v_rcp_f32_e32 v163, v163
	v_pk_add_f32 v[124:125], v[124:125], 1.0 op_sel_hi:[1,0]
	s_add_u32 s2, s16, s3
	v_rcp_f32_e32 v124, v124
	v_rcp_f32_e32 v125, v125
	v_pk_mul_f32 v[126:127], v[164:165], v[162:163] op_sel_hi:[0,1]
	v_pk_mul_f32 v[120:121], v[120:121], v[126:127]
	v_pk_mul_f32 v[126:127], v[116:117], v[136:137] op_sel_hi:[1,0]
	v_pk_mul_f32 v[124:125], v[164:165], v[124:125] op_sel_hi:[0,1]
	v_exp_f32_e32 v126, v126
	v_exp_f32_e32 v127, v127
	v_pk_mul_f32 v[122:123], v[122:123], v[124:125]
	v_pk_mul_f32 v[124:125], v[118:119], v[136:137] op_sel_hi:[1,0]
	v_cvt_pk_bf16_f32 v120, v120, v121
	v_cvt_pk_bf16_f32 v121, v122, v123
	v_pk_add_f32 v[122:123], v[126:127], 1.0 op_sel_hi:[1,0]
	v_exp_f32_e32 v124, v124
	v_exp_f32_e32 v125, v125
	v_rcp_f32_e32 v122, v122
	v_rcp_f32_e32 v123, v123
	v_ashrrev_i32_e32 v149, 31, v148
	v_pk_add_f32 v[116:117], v[124:125], 1.0 op_sel_hi:[1,0]
	s_addc_u32 s3, s17, s11
	v_rcp_f32_e32 v116, v116
	v_rcp_f32_e32 v117, v117
	v_pk_mul_f32 v[118:119], v[164:165], v[122:123] op_sel_hi:[0,1]
	v_pk_mul_f32 v[112:113], v[112:113], v[118:119]
	s_nop 0
	v_cvt_pk_bf16_f32 v122, v112, v113
	v_pk_mul_f32 v[112:113], v[164:165], v[116:117] op_sel_hi:[0,1]
	v_mul_f32_e32 v116, 0xbfb8aa3b, v165
	v_pk_mul_f32 v[118:119], v[108:109], v[116:117] op_sel_hi:[1,0]
	v_pk_mul_f32 v[108:109], v[110:111], v[116:117] op_sel_hi:[1,0]
	v_exp_f32_e32 v118, v118
	v_exp_f32_e32 v119, v119
	v_exp_f32_e32 v108, v108
	v_exp_f32_e32 v109, v109
	v_pk_mul_f32 v[112:113], v[114:115], v[112:113]
	v_pk_add_f32 v[118:119], v[118:119], 1.0 op_sel_hi:[1,0]
	v_cvt_pk_bf16_f32 v123, v112, v113
	v_mul_u32_u24_e32 v112, 0xb40, v161
	v_lshlrev_b32_e32 v136, 1, v112
	v_rcp_f32_e32 v118, v118
	v_rcp_f32_e32 v119, v119
	v_lshl_add_u64 v[114:115], s[2:3], 0, v[136:137]
	v_lshlrev_b64 v[112:113], 1, v[148:149]
	v_pk_add_f32 v[108:109], v[108:109], 1.0 op_sel_hi:[1,0]
	v_lshl_add_u64 v[114:115], v[114:115], 0, v[112:113]
	v_rcp_f32_e32 v108, v108
	v_rcp_f32_e32 v109, v109
	global_store_dwordx4 v[114:115], v[120:123], off
	s_nop 1
	v_mul_f32_e32 v120, v165, v165
	v_pk_mul_f32 v[110:111], v[120:121], v[118:119] op_sel_hi:[0,1]
	v_pk_mul_f32 v[104:105], v[104:105], v[110:111]
	v_pk_mul_f32 v[110:111], v[100:101], v[116:117] op_sel_hi:[1,0]
	v_pk_mul_f32 v[108:109], v[120:121], v[108:109] op_sel_hi:[0,1]
	v_exp_f32_e32 v110, v110
	v_exp_f32_e32 v111, v111
	v_pk_mul_f32 v[106:107], v[106:107], v[108:109]
; __device__ __forceinline__ unsigned cvt_pk_bf16(float lo, float hi) { unsigned r; asm volatile("v_cvt_pk_bf16_f32 %0, %1, %2" : "=v"(r) : "v"(lo), "v"(hi)); return r; }
;     __device__ __forceinline__ void operator()(const f32x4 (&acc)[2][2][4][2], const Unit& u, int wr, int wc, int fr, int fq) const {
;     ...
;                 const int row = row0 + ai * HALF + m * 16; const float r = rs[ai][m];
;                 const float nrl = r * -1.44269504089f, r2 = r * r;
;                 unsigned pk[4];
; #pragma unroll
;                 for (int q = 0; q < 4; ++q) {
;                     const f32x4 ga = acc[ai][0][m][q >> 1], ua = acc[ai][1][m][q >> 1]; const int e0 = 2 * (q & 1);
;                     const f32x2 g = (f32x2){ga[e0], ga[e0 + 1]}, up = (f32x2){ua[e0], ua[e0 + 1]};
;                     const f32x2 t = g * nrl; f32x2 ex; ex.x = __builtin_amdgcn_exp2f(t.x); ex.y = __builtin_amdgcn_exp2f(t.y);
;                     const f32x2 d = ex + 1.0f; f32x2 rc; rc.x = __builtin_amdgcn_rcpf(d.x); rc.y = __builtin_amdgcn_rcpf(d.y);
;                     const f32x2 o = (g * up) * (rc * r2);
;                     pk[q] = cvt_pk_bf16(o.x, o.y);
;                 }
;                 u32x4 w; w.x = pk[0]; w.y = pk[1]; w.z = pk[2]; w.w = pk[3];
;                 *(u32x4*)(U + (size_t)(row >> 13) * U_SLAB + (size_t)(row & (SEQ - 1)) * U_PITCH + col0) = w;
	v_pk_mul_f32 v[108:109], v[102:103], v[116:117] op_sel_hi:[1,0]
	v_cvt_pk_bf16_f32 v104, v104, v105
	v_cvt_pk_bf16_f32 v105, v106, v107
	v_pk_add_f32 v[106:107], v[110:111], 1.0 op_sel_hi:[1,0]
	v_exp_f32_e32 v108, v108
	v_exp_f32_e32 v109, v109
	v_rcp_f32_e32 v106, v106
	v_rcp_f32_e32 v107, v107
	v_pk_add_f32 v[100:101], v[108:109], 1.0 op_sel_hi:[1,0]
	s_nop 0
	v_rcp_f32_e32 v100, v100
	v_rcp_f32_e32 v101, v101
	v_pk_mul_f32 v[102:103], v[120:121], v[106:107] op_sel_hi:[0,1]
	v_pk_mul_f32 v[96:97], v[96:97], v[102:103]
	s_nop 0
	v_cvt_pk_bf16_f32 v106, v96, v97
	v_pk_mul_f32 v[96:97], v[120:121], v[100:101] op_sel_hi:[0,1]
	v_pk_mul_f32 v[96:97], v[98:99], v[96:97]
	v_add_co_u32_e32 v100, vcc, s28, v114
	v_cvt_pk_bf16_f32 v107, v96, v97
	v_mul_f32_e32 v96, 0xbfb8aa3b, v166
	v_pk_mul_f32 v[98:99], v[92:93], v[96:97] op_sel_hi:[1,0]
	v_pk_mul_f32 v[92:93], v[94:95], v[96:97] op_sel_hi:[1,0]
	v_exp_f32_e32 v98, v98
	v_exp_f32_e32 v99, v99
	v_exp_f32_e32 v92, v92
	v_exp_f32_e32 v93, v93
	v_addc_co_u32_e32 v101, vcc, 0, v115, vcc
	v_pk_add_f32 v[98:99], v[98:99], 1.0 op_sel_hi:[1,0]
	v_pk_add_f32 v[92:93], v[92:93], 1.0 op_sel_hi:[1,0]
	v_rcp_f32_e32 v98, v98
	v_rcp_f32_e32 v99, v99
	v_rcp_f32_e32 v92, v92
	v_rcp_f32_e32 v93, v93
	global_store_dwordx4 v[100:101], v[104:107], off offset:2048
	v_mul_f32_e32 v100, v166, v166
	v_pk_mul_f32 v[94:95], v[100:101], v[98:99] op_sel_hi:[0,1]
	v_pk_mul_f32 v[88:89], v[88:89], v[94:95]
	v_pk_mul_f32 v[94:95], v[84:85], v[96:97] op_sel_hi:[1,0]
	v_pk_mul_f32 v[92:93], v[100:101], v[92:93] op_sel_hi:[0,1]
	v_exp_f32_e32 v94, v94
	v_exp_f32_e32 v95, v95
	v_pk_mul_f32 v[90:91], v[90:91], v[92:93]
	v_pk_mul_f32 v[92:93], v[86:87], v[96:97] op_sel_hi:[1,0]
	v_cvt_pk_bf16_f32 v88, v88, v89
	v_cvt_pk_bf16_f32 v89, v90, v91
	v_pk_add_f32 v[90:91], v[94:95], 1.0 op_sel_hi:[1,0]
	v_exp_f32_e32 v92, v92
	v_exp_f32_e32 v93, v93
	v_rcp_f32_e32 v90, v90
	v_rcp_f32_e32 v91, v91
	v_pk_add_f32 v[84:85], v[92:93], 1.0 op_sel_hi:[1,0]
	s_nop 0
	v_rcp_f32_e32 v84, v84
	v_rcp_f32_e32 v85, v85
	v_pk_mul_f32 v[86:87], v[100:101], v[90:91] op_sel_hi:[0,1]
	v_pk_mul_f32 v[80:81], v[80:81], v[86:87]
	s_nop 0
	v_cvt_pk_bf16_f32 v90, v80, v81
	v_pk_mul_f32 v[80:81], v[100:101], v[84:85] op_sel_hi:[0,1]
	v_pk_mul_f32 v[80:81], v[82:83], v[80:81]
	v_add_co_u32_e32 v84, vcc, s38, v114
	v_cvt_pk_bf16_f32 v91, v80, v81
	v_mul_f32_e32 v80, 0xbfb8aa3b, v167
	v_pk_mul_f32 v[82:83], v[76:77], v[80:81] op_sel_hi:[1,0]
	v_pk_mul_f32 v[76:77], v[78:79], v[80:81] op_sel_hi:[1,0]
	v_exp_f32_e32 v82, v82
	v_exp_f32_e32 v83, v83
	v_exp_f32_e32 v76, v76
	v_exp_f32_e32 v77, v77
	v_addc_co_u32_e32 v85, vcc, 0, v115, vcc
	v_pk_add_f32 v[82:83], v[82:83], 1.0 op_sel_hi:[1,0]
	v_pk_add_f32 v[76:77], v[76:77], 1.0 op_sel_hi:[1,0]
	v_rcp_f32_e32 v82, v82
	v_rcp_f32_e32 v83, v83
	v_rcp_f32_e32 v76, v76
	v_rcp_f32_e32 v77, v77
	global_store_dwordx4 v[84:85], v[88:91], off
	v_mul_f32_e32 v84, v167, v167
	v_pk_mul_f32 v[78:79], v[84:85], v[82:83] op_sel_hi:[0,1]
	v_pk_mul_f32 v[72:73], v[72:73], v[78:79]
	v_pk_mul_f32 v[78:79], v[68:69], v[80:81] op_sel_hi:[1,0]
	v_pk_mul_f32 v[76:77], v[84:85], v[76:77] op_sel_hi:[0,1]
	v_exp_f32_e32 v78, v78
	v_exp_f32_e32 v79, v79
	v_pk_mul_f32 v[74:75], v[74:75], v[76:77]
	v_pk_mul_f32 v[76:77], v[70:71], v[80:81] op_sel_hi:[1,0]
	v_cvt_pk_bf16_f32 v72, v72, v73
	v_cvt_pk_bf16_f32 v73, v74, v75
	v_pk_add_f32 v[74:75], v[78:79], 1.0 op_sel_hi:[1,0]
	v_exp_f32_e32 v76, v76
	v_exp_f32_e32 v77, v77
	v_rcp_f32_e32 v74, v74
	v_rcp_f32_e32 v75, v75
	v_pk_add_f32 v[68:69], v[76:77], 1.0 op_sel_hi:[1,0]
	s_nop 0
	v_rcp_f32_e32 v68, v68
	v_rcp_f32_e32 v69, v69
	v_pk_mul_f32 v[70:71], v[84:85], v[74:75] op_sel_hi:[0,1]
	v_pk_mul_f32 v[64:65], v[64:65], v[70:71]
	s_nop 0
	v_cvt_pk_bf16_f32 v74, v64, v65
	v_pk_mul_f32 v[64:65], v[84:85], v[68:69] op_sel_hi:[0,1]
	v_pk_mul_f32 v[64:65], v[66:67], v[64:65]
	v_and_b32_e32 v69, 0x1fcf, v146
	v_cvt_pk_bf16_f32 v75, v64, v65
	v_add_co_u32_e32 v64, vcc, s39, v114
	v_mul_f32_e32 v68, v168, v168
	s_nop 0
	v_addc_co_u32_e32 v65, vcc, 0, v115, vcc
	global_store_dwordx4 v[64:65], v[72:75], off offset:2048
	v_mul_f32_e32 v64, 0xbfb8aa3b, v168
	v_pk_mul_f32 v[66:67], v[60:61], v[64:65] op_sel_hi:[1,0]
	v_ashrrev_i32_e32 v65, 13, v146
	v_exp_f32_e32 v66, v66
	v_exp_f32_e32 v67, v67
	v_pk_mul_f32 v[60:61], v[62:63], v[64:65] op_sel_hi:[1,0]
	v_pk_add_f32 v[66:67], v[66:67], 1.0 op_sel_hi:[1,0]
	v_exp_f32_e32 v60, v60
	v_exp_f32_e32 v61, v61
	v_rcp_f32_e32 v66, v66
	v_rcp_f32_e32 v67, v67
	v_pk_add_f32 v[60:61], v[60:61], 1.0 op_sel_hi:[1,0]
	s_nop 0
	v_rcp_f32_e32 v60, v60
	v_rcp_f32_e32 v61, v61
	v_pk_mul_f32 v[62:63], v[68:69], v[66:67] op_sel_hi:[0,1]
	v_pk_mul_f32 v[56:57], v[56:57], v[62:63]
	v_pk_mul_f32 v[62:63], v[52:53], v[64:65] op_sel_hi:[1,0]
	v_pk_mul_f32 v[60:61], v[68:69], v[60:61] op_sel_hi:[0,1]
	v_exp_f32_e32 v62, v62
	v_exp_f32_e32 v63, v63
	v_pk_mul_f32 v[58:59], v[58:59], v[60:61]
	v_pk_mul_f32 v[60:61], v[54:55], v[64:65] op_sel_hi:[1,0]
	v_cvt_pk_bf16_f32 v56, v56, v57
	v_cvt_pk_bf16_f32 v57, v58, v59
	v_pk_add_f32 v[58:59], v[62:63], 1.0 op_sel_hi:[1,0]
	v_exp_f32_e32 v60, v60
	v_exp_f32_e32 v61, v61
	v_rcp_f32_e32 v58, v58
	v_rcp_f32_e32 v59, v59
	v_pk_add_f32 v[52:53], v[60:61], 1.0 op_sel_hi:[1,0]
	s_nop 0
	v_rcp_f32_e32 v52, v52
	v_rcp_f32_e32 v53, v53
	v_pk_mul_f32 v[54:55], v[68:69], v[58:59] op_sel_hi:[0,1]
	v_pk_mul_f32 v[48:49], v[48:49], v[54:55]
; __device__ __forceinline__ unsigned cvt_pk_bf16(float lo, float hi) { unsigned r; asm volatile("v_cvt_pk_bf16_f32 %0, %1, %2" : "=v"(r) : "v"(lo), "v"(hi)); return r; }
; #define PG8_BAR __builtin_amdgcn_s_barrier()
;     __device__ __forceinline__ void operator()(const f32x4 (&acc)[2][2][4][2], const Unit& u, int wr, int wc, int fr, int fq) const {
;     ...
;                 const int row = row0 + ai * HALF + m * 16; const float r = rs[ai][m];
;                 const float nrl = r * -1.44269504089f, r2 = r * r;
;                 unsigned pk[4];
; #pragma unroll
;                 for (int q = 0; q < 4; ++q) {
;                     const f32x4 ga = acc[ai][0][m][q >> 1], ua = acc[ai][1][m][q >> 1]; const int e0 = 2 * (q & 1);
;                     const f32x2 g = (f32x2){ga[e0], ga[e0 + 1]}, up = (f32x2){ua[e0], ua[e0 + 1]};
;                     const f32x2 t = g * nrl; f32x2 ex; ex.x = __builtin_amdgcn_exp2f(t.x); ex.y = __builtin_amdgcn_exp2f(t.y);
;                     const f32x2 d = ex + 1.0f; f32x2 rc; rc.x = __builtin_amdgcn_rcpf(d.x); rc.y = __builtin_amdgcn_rcpf(d.y);
;                     const f32x2 o = (g * up) * (rc * r2);
;                     pk[q] = cvt_pk_bf16(o.x, o.y);
;                 }
;                 u32x4 w; w.x = pk[0]; w.y = pk[1]; w.z = pk[2]; w.w = pk[3];
;                 *(u32x4*)(U + (size_t)(row >> 13) * U_SLAB + (size_t)(row & (SEQ - 1)) * U_PITCH + col0) = w;
; template <class Epi>
; __device__ __forceinline__ void gemm_phase(LAS unsigned char* lds, const Gemm g, const StaticOrder& S, const Epi& E) {
;     ...
;         if (!has_next) break;
; #pragma unroll
;         for (int a = 0; a < 2; ++a)
; #pragma unroll
;             for (int b = 0; b < 2; ++b)
; #pragma unroll
;                 for (int m = 0; m < 4; ++m)
; #pragma unroll
;                     for (int n = 0; n < 2; ++n) acc[a][b][m][n] = (f32x4){0.f, 0.f, 0.f, 0.f};
;         cur = nxt; cA = nA; cB = nB; ++ui;
;         if (wr == 1) PG8_BAR;
	v_mul_f32_e32 v54, v160, v160
	v_cvt_pk_bf16_f32 v58, v48, v49
	v_pk_mul_f32 v[48:49], v[68:69], v[52:53] op_sel_hi:[0,1]
	v_pk_mul_f32 v[48:49], v[50:51], v[48:49]
	v_mul_u32_u24_e32 v50, 0xb40, v69
	v_lshlrev_b32_e32 v136, 1, v50
	v_mul_f32_e32 v50, 0xbfb8aa3b, v160
	v_pk_mul_f32 v[52:53], v[44:45], v[50:51] op_sel_hi:[1,0]
	v_pk_mul_f32 v[44:45], v[46:47], v[50:51] op_sel_hi:[1,0]
	v_exp_f32_e32 v52, v52
	v_exp_f32_e32 v53, v53
	v_exp_f32_e32 v44, v44
	v_exp_f32_e32 v45, v45
	v_cvt_pk_bf16_f32 v59, v48, v49
	v_pk_add_f32 v[52:53], v[52:53], 1.0 op_sel_hi:[1,0]
	v_mov_b64_e32 v[48:49], s[16:17]
	v_rcp_f32_e32 v52, v52
	v_rcp_f32_e32 v53, v53
	v_pk_add_f32 v[44:45], v[44:45], 1.0 op_sel_hi:[1,0]
	v_mad_i64_i32 v[48:49], s[2:3], v65, s37, v[48:49]
	v_rcp_f32_e32 v44, v44
	v_rcp_f32_e32 v45, v45
	v_pk_mul_f32 v[46:47], v[54:55], v[52:53] op_sel_hi:[0,1]
	v_pk_mul_f32 v[40:41], v[40:41], v[46:47]
	v_pk_mul_f32 v[46:47], v[36:37], v[50:51] op_sel_hi:[1,0]
	v_pk_mul_f32 v[44:45], v[54:55], v[44:45] op_sel_hi:[0,1]
	v_exp_f32_e32 v46, v46
	v_exp_f32_e32 v47, v47
	v_pk_mul_f32 v[42:43], v[42:43], v[44:45]
	v_pk_mul_f32 v[44:45], v[38:39], v[50:51] op_sel_hi:[1,0]
	v_lshl_add_u64 v[48:49], v[48:49], 0, v[136:137]
	v_exp_f32_e32 v44, v44
	v_exp_f32_e32 v45, v45
	v_lshl_add_u64 v[48:49], v[48:49], 0, v[112:113]
	global_store_dwordx4 v[48:49], v[56:59], off
	v_cvt_pk_bf16_f32 v40, v40, v41
	v_cvt_pk_bf16_f32 v41, v42, v43
	v_pk_add_f32 v[42:43], v[46:47], 1.0 op_sel_hi:[1,0]
	v_pk_add_f32 v[36:37], v[44:45], 1.0 op_sel_hi:[1,0]
	v_rcp_f32_e32 v42, v42
	v_rcp_f32_e32 v43, v43
	v_rcp_f32_e32 v36, v36
	v_rcp_f32_e32 v37, v37
	s_mov_b64 s[2:3], -1
	v_pk_mul_f32 v[38:39], v[54:55], v[42:43] op_sel_hi:[0,1]
	v_pk_mul_f32 v[32:33], v[32:33], v[38:39]
	s_nop 0
	v_cvt_pk_bf16_f32 v42, v32, v33
	v_pk_mul_f32 v[32:33], v[54:55], v[36:37] op_sel_hi:[0,1]
	v_pk_mul_f32 v[32:33], v[34:35], v[32:33]
	v_add_co_u32_e32 v36, vcc, s28, v48
	v_cvt_pk_bf16_f32 v43, v32, v33
	v_mul_f32_e32 v32, 0xbfb8aa3b, v159
	v_pk_mul_f32 v[34:35], v[28:29], v[32:33] op_sel_hi:[1,0]
	v_pk_mul_f32 v[28:29], v[30:31], v[32:33] op_sel_hi:[1,0]
	v_exp_f32_e32 v34, v34
	v_exp_f32_e32 v35, v35
	v_exp_f32_e32 v28, v28
	v_exp_f32_e32 v29, v29
	v_addc_co_u32_e32 v37, vcc, 0, v49, vcc
	v_pk_add_f32 v[34:35], v[34:35], 1.0 op_sel_hi:[1,0]
	v_pk_add_f32 v[28:29], v[28:29], 1.0 op_sel_hi:[1,0]
	v_rcp_f32_e32 v34, v34
	v_rcp_f32_e32 v35, v35
	v_rcp_f32_e32 v28, v28
	v_rcp_f32_e32 v29, v29
	global_store_dwordx4 v[36:37], v[40:43], off offset:2048
	v_mul_f32_e32 v36, v159, v159
	v_pk_mul_f32 v[30:31], v[36:37], v[34:35] op_sel_hi:[0,1]
	v_pk_mul_f32 v[24:25], v[24:25], v[30:31]
	v_pk_mul_f32 v[30:31], v[20:21], v[32:33] op_sel_hi:[1,0]
	v_pk_mul_f32 v[28:29], v[36:37], v[28:29] op_sel_hi:[0,1]
	v_exp_f32_e32 v30, v30
	v_exp_f32_e32 v31, v31
	v_pk_mul_f32 v[26:27], v[26:27], v[28:29]
	v_pk_mul_f32 v[28:29], v[22:23], v[32:33] op_sel_hi:[1,0]
	v_cvt_pk_bf16_f32 v24, v24, v25
	v_cvt_pk_bf16_f32 v25, v26, v27
	v_pk_add_f32 v[26:27], v[30:31], 1.0 op_sel_hi:[1,0]
	v_exp_f32_e32 v28, v28
	v_exp_f32_e32 v29, v29
	v_rcp_f32_e32 v26, v26
	v_rcp_f32_e32 v27, v27
	v_pk_add_f32 v[20:21], v[28:29], 1.0 op_sel_hi:[1,0]
	s_nop 0
	v_rcp_f32_e32 v20, v20
	v_rcp_f32_e32 v21, v21
	v_pk_mul_f32 v[22:23], v[36:37], v[26:27] op_sel_hi:[0,1]
	v_pk_mul_f32 v[16:17], v[16:17], v[22:23]
	s_nop 0
	v_cvt_pk_bf16_f32 v26, v16, v17
	v_pk_mul_f32 v[16:17], v[36:37], v[20:21] op_sel_hi:[0,1]
	v_pk_mul_f32 v[16:17], v[18:19], v[16:17]
	v_add_co_u32_e32 v20, vcc, s38, v48
	v_cvt_pk_bf16_f32 v27, v16, v17
	v_mul_f32_e32 v16, 0xbfb8aa3b, v147
	v_pk_mul_f32 v[18:19], v[12:13], v[16:17] op_sel_hi:[1,0]
	v_pk_mul_f32 v[12:13], v[14:15], v[16:17] op_sel_hi:[1,0]
	v_exp_f32_e32 v18, v18
	v_exp_f32_e32 v19, v19
	v_exp_f32_e32 v12, v12
	v_exp_f32_e32 v13, v13
	v_addc_co_u32_e32 v21, vcc, 0, v49, vcc
	v_pk_add_f32 v[18:19], v[18:19], 1.0 op_sel_hi:[1,0]
	v_pk_add_f32 v[12:13], v[12:13], 1.0 op_sel_hi:[1,0]
	v_rcp_f32_e32 v18, v18
	v_rcp_f32_e32 v19, v19
	v_rcp_f32_e32 v12, v12
	v_rcp_f32_e32 v13, v13
	global_store_dwordx4 v[20:21], v[24:27], off
	v_mul_f32_e32 v20, v147, v147
	v_pk_mul_f32 v[14:15], v[20:21], v[18:19] op_sel_hi:[0,1]
	v_pk_mul_f32 v[8:9], v[8:9], v[14:15]
	v_pk_mul_f32 v[14:15], v[4:5], v[16:17] op_sel_hi:[1,0]
	v_pk_mul_f32 v[12:13], v[20:21], v[12:13] op_sel_hi:[0,1]
	v_exp_f32_e32 v14, v14
	v_exp_f32_e32 v15, v15
	v_pk_mul_f32 v[10:11], v[10:11], v[12:13]
	v_pk_mul_f32 v[12:13], v[6:7], v[16:17] op_sel_hi:[1,0]
	v_cvt_pk_bf16_f32 v8, v8, v9
	v_cvt_pk_bf16_f32 v9, v10, v11
	v_pk_add_f32 v[10:11], v[14:15], 1.0 op_sel_hi:[1,0]
	v_exp_f32_e32 v12, v12
	v_exp_f32_e32 v13, v13
	v_rcp_f32_e32 v10, v10
	v_rcp_f32_e32 v11, v11
	v_pk_add_f32 v[4:5], v[12:13], 1.0 op_sel_hi:[1,0]
	s_nop 0
	v_rcp_f32_e32 v4, v4
	v_rcp_f32_e32 v5, v5
	v_pk_mul_f32 v[6:7], v[20:21], v[10:11] op_sel_hi:[0,1]
	v_pk_mul_f32 v[0:1], v[0:1], v[6:7]
	s_nop 0
	v_cvt_pk_bf16_f32 v10, v0, v1
	v_pk_mul_f32 v[0:1], v[20:21], v[4:5] op_sel_hi:[0,1]
	v_pk_mul_f32 v[0:1], v[2:3], v[0:1]
	s_nop 0
	v_cvt_pk_bf16_f32 v11, v0, v1
	v_add_co_u32_e32 v0, vcc, 0x43000, v48
	s_nop 1
	v_addc_co_u32_e32 v1, vcc, 0, v49, vcc
	s_andn2_b64 vcc, exec, s[4:5]
	global_store_dwordx4 v[0:1], v[8:11], off offset:2048
	s_cbranch_vccnz .LBB0_925
	s_andn2_b64 vcc, exec, s[0:1]
	s_cbranch_vccnz .LBB0_924
	s_barrier
	s_branch .LBB0_924

; __device__ __forceinline__ unsigned cvt_pk_bf16(float lo, float hi) { unsigned r; asm volatile("v_cvt_pk_bf16_f32 %0, %1, %2" : "=v"(r) : "v"(lo), "v"(hi)); return r; }
; __device__ __forceinline__ float bf_lo(unsigned w) { return __uint_as_float(w << 16); }
;     __device__ __forceinline__ void operator()(const f32x4 (&acc)[2][2][4][2], const Unit& u, int wr, int wc, int fr, int fq) const {
;     ...
;             f32x4 bf[BASE_F32 ? RB : 1][2][2]; u32x4 bb[BASE_F32 ? 1 : RB][2];
; #pragma unroll
;             for (int mm = 0; mm < RB; ++mm) { const size_t off = (size_t)(row0 + ai * HALF + (mh + mm) * 16) * D_MODEL + col0;
; #pragma unroll
;                 for (int bj = 0; bj < 2; ++bj) {
;                     if (BASE_F32) { bf[mm][bj][0] = *(const f32x4*)(basef + off + bj * HALF); bf[mm][bj][1] = *(const f32x4*)(basef + off + bj * HALF + 4); }
;                     else bb[mm][bj] = *(const u32x4*)(xb + off + bj * HALF);
;                 } }
;             asm volatile("" ::: "memory");
; #pragma unroll
;             for (int mm = 0; mm < RB; ++mm) {
;                 const int m = mh + mm;
;                 const int row = row0 + ai * HALF + m * 16; const size_t off = (size_t)row * D_MODEL + col0; float s = 0.f;
; #pragma unroll
;                 for (int bj = 0; bj < 2; ++bj) {
;                     f32x4 b0, b1;
;                     if (BASE_F32) { b0 = bf[mm][bj][0]; b1 = bf[mm][bj][1]; }
;                     else { const u32x4 w = bb[mm][bj]; b0 = (f32x4){bf_lo(w.x), bf_hi(w.x), bf_lo(w.y), bf_hi(w.y)}; b1 = (f32x4){bf_lo(w.z), bf_hi(w.z), bf_lo(w.w), bf_hi(w.w)}; }
;                     const f32x4 o0 = b0 + acc[ai][bj][m][0] * alpha, o1 = b1 + acc[ai][bj][m][1] * alpha;
;                     if (OUT_F32) { *(f32x4*)(out + off + bj * HALF) = o0; *(f32x4*)(out + off + bj * HALF + 4) = o1; }
;                     else { u32x4 w; w.x = cvt_pk_bf16(o0[0], o0[1]); w.y = cvt_pk_bf16(o0[2], o0[3]); w.z = cvt_pk_bf16(o1[0], o1[1]); w.w = cvt_pk_bf16(o1[2], o1[3]); *(u32x4*)(xb + off + bj * HALF) = w; }
;                     s += ((o0[0] * o0[0] + o0[1] * o0[1]) + (o0[2] * o0[2] + o0[3] * o0[3])) + ((o1[0] * o1[0] + o1[1] * o1[1]) + (o1[2] * o1[2] + o1[3] * o1[3]));
;                 }
;                 if (ssp) { s += __shfl_xor(s, 16); s += __shfl_xor(s, 32); if (fq == 0) ssp[(size_t)row * 16 + u.pn * 4 + wc] = s; }
;             }
.LBB0_1037:
	v_lshl_or_b32 v166, s10, 8, v186
	v_lshl_add_u32 v168, s41, 8, v184
	v_ashrrev_i32_e32 v167, 31, v166
	v_readlane_b32 s2, v235, 38
	v_lshlrev_b64 v[202:203], 1, v[166:167]
	v_readlane_b32 s3, v235, 39
	v_ashrrev_i32_e32 v169, 31, v168
	v_or_b32_e32 v180, 16, v168
	v_or_b32_e32 v176, 32, v168
	v_lshl_add_u64 v[170:171], s[2:3], 0, v[202:203]
	v_lshlrev_b64 v[204:205], 11, v[168:169]
	v_or_b32_e32 v172, 48, v168
	v_ashrrev_i32_e32 v181, 31, v180
	v_ashrrev_i32_e32 v177, 31, v176
	v_lshl_add_u64 v[128:129], v[170:171], 0, v[204:205]
	v_ashrrev_i32_e32 v173, 31, v172
	v_lshlrev_b64 v[182:183], 11, v[180:181]
	v_lshlrev_b64 v[178:179], 11, v[176:177]
	global_load_dwordx4 v[192:195], v[128:129], off
	global_load_dwordx4 v[198:201], v[128:129], off offset:256
	v_lshlrev_b64 v[174:175], 11, v[172:173]
	v_lshl_add_u64 v[128:129], v[170:171], 0, v[182:183]
	v_lshl_add_u64 v[130:131], v[170:171], 0, v[178:179]
	v_lshl_add_u64 v[206:207], v[170:171], 0, v[174:175]
	global_load_dwordx4 v[148:151], v[128:129], off
	global_load_dwordx4 v[144:147], v[128:129], off offset:256
	global_load_dwordx4 v[140:143], v[130:131], off
	global_load_dwordx4 v[136:139], v[130:131], off offset:256
	global_load_dwordx4 v[132:135], v[206:207], off
	s_nop 0
	global_load_dwordx4 v[128:131], v[206:207], off offset:256
	v_readlane_b32 s22, v235, 42
	v_readlane_b32 s23, v235, 43
	v_lshl_add_u64 v[204:205], s[2:3], 0, v[204:205]
	s_lshl_b32 s20, s10, 2
	v_cndmask_b32_e64 v197, 0, 1, s[22:23]
	v_lshl_add_u64 v[202:203], v[204:205], 0, v[202:203]
	s_ashr_i32 s21, s20, 31
	v_cmp_ne_u32_e64 s[8:9], 1, v197
	s_andn2_b64 vcc, exec, s[22:23]
	s_waitcnt vmcnt(0)
	v_lshlrev_b32_e32 v204, 16, v192
	v_and_b32_e32 v205, 0xffff0000, v192
	v_lshlrev_b32_e32 v192, 16, v193
	v_and_b32_e32 v193, 0xffff0000, v193
	v_lshlrev_b32_e32 v206, 16, v194
	v_and_b32_e32 v207, 0xffff0000, v194
	v_lshlrev_b32_e32 v194, 16, v195
	v_and_b32_e32 v195, 0xffff0000, v195
	v_lshlrev_b32_e32 v208, 16, v198
	v_and_b32_e32 v209, 0xffff0000, v198
	v_lshlrev_b32_e32 v198, 16, v199
	v_and_b32_e32 v199, 0xffff0000, v199
	v_lshlrev_b32_e32 v210, 16, v200
	v_and_b32_e32 v211, 0xffff0000, v200
	v_lshlrev_b32_e32 v200, 16, v201
	v_and_b32_e32 v201, 0xffff0000, v201
	v_pk_fma_f32 v[126:127], v[126:127], 0.5, v[192:193] op_sel_hi:[1,0,1]
	v_pk_fma_f32 v[124:125], v[124:125], 0.5, v[204:205] op_sel_hi:[1,0,1]
	v_pk_fma_f32 v[122:123], v[122:123], 0.5, v[194:195] op_sel_hi:[1,0,1]
	v_pk_fma_f32 v[120:121], v[120:121], 0.5, v[206:207] op_sel_hi:[1,0,1]
	v_pk_fma_f32 v[118:119], v[118:119], 0.5, v[198:199] op_sel_hi:[1,0,1]
	v_pk_fma_f32 v[116:117], v[116:117], 0.5, v[208:209] op_sel_hi:[1,0,1]
	v_pk_fma_f32 v[114:115], v[114:115], 0.5, v[200:201] op_sel_hi:[1,0,1]
	v_pk_fma_f32 v[112:113], v[112:113], 0.5, v[210:211] op_sel_hi:[1,0,1]
	v_cvt_pk_bf16_f32 v192, v124, v125
	v_cvt_pk_bf16_f32 v193, v126, v127
	v_cvt_pk_bf16_f32 v194, v120, v121
	v_cvt_pk_bf16_f32 v195, v122, v123
	global_store_dwordx4 v[202:203], v[192:195], off
	s_nop 1
	v_cvt_pk_bf16_f32 v192, v116, v117
	v_cvt_pk_bf16_f32 v193, v118, v119
	v_cvt_pk_bf16_f32 v194, v112, v113
	v_cvt_pk_bf16_f32 v195, v114, v115
	global_store_dwordx4 v[202:203], v[192:195], off offset:256
	s_cbranch_vccnz .LBB0_1041
	v_mul_f32_e32 v113, v113, v113
	v_mul_f32_e32 v125, v125, v125
	v_mul_f32_e32 v121, v121, v121
	v_mul_f32_e32 v117, v117, v117
	v_fmac_f32_e32 v113, v112, v112
	v_mul_f32_e32 v112, v115, v115
	v_fmac_f32_e32 v125, v124, v124
	v_mul_f32_e32 v124, v127, v127
	v_fmac_f32_e32 v121, v120, v120
	v_mul_f32_e32 v120, v123, v123
	v_fmac_f32_e32 v117, v116, v116
	v_mul_f32_e32 v116, v119, v119
	v_fmac_f32_e32 v112, v114, v114
	v_and_b32_e32 v114, 64, v191
	v_fmac_f32_e32 v124, v126, v126
	v_fmac_f32_e32 v120, v122, v122
	v_fmac_f32_e32 v116, v118, v118
	v_add_f32_e32 v112, v113, v112
	v_xor_b32_e32 v113, 16, v191
	v_add_u32_e32 v114, 64, v114
	v_add_f32_e32 v124, v125, v124
	v_add_f32_e32 v120, v121, v120
	v_add_f32_e32 v116, v117, v116
	v_cmp_lt_i32_e32 vcc, v113, v114
	v_add_f32_e32 v120, v124, v120
	v_add_f32_e32 v112, v116, v112
	v_cndmask_b32_e32 v113, v191, v113, vcc
	v_add_f32_e32 v112, v120, v112
	v_lshlrev_b32_e32 v113, 2, v113
	v_mov_b32_e32 v236, v112
	v_mov_b32_e32 v237, v112
	s_nop 1
	v_permlane16_swap_b32_e32 v236, v237
	v_cndmask_b32_e64 v113, v237, v236, s[98:99]
	s_waitcnt lgkmcnt(0)
	v_add_f32_e32 v112, v112, v113
	v_xor_b32_e32 v113, 32, v191
	v_cmp_lt_i32_e32 vcc, v113, v114
	s_nop 1
	v_cndmask_b32_e32 v113, v191, v113, vcc
	v_lshlrev_b32_e32 v113, 2, v113
	v_mov_b32_e32 v236, v112
	v_mov_b32_e32 v237, v112
	s_nop 1
	v_permlane32_swap_b32_e32 v236, v237
	v_cndmask_b32_e64 v113, v237, v236, s[100:101]
	s_and_saveexec_b64 s[2:3], s[4:5]
	s_cbranch_execz .LBB0_1040
	v_readlane_b32 s22, v235, 50
	v_lshlrev_b64 v[114:115], 6, v[168:169]
	v_readlane_b32 s23, v235, 51
	s_lshl_b32 s10, s29, 2
	s_waitcnt lgkmcnt(0)
	v_add_f32_e32 v112, v112, v113
	v_lshl_add_u64 v[114:115], s[22:23], 0, v[114:115]
	v_lshl_add_u64 v[114:115], s[20:21], 2, v[114:115]
	v_lshl_add_u64 v[114:115], v[114:115], 0, s[10:11]
	global_store_dword v[114:115], v112, off

; __device__ __forceinline__ unsigned cvt_pk_bf16(float lo, float hi) { unsigned r; asm volatile("v_cvt_pk_bf16_f32 %0, %1, %2" : "=v"(r) : "v"(lo), "v"(hi)); return r; }
; __device__ __forceinline__ float bf_lo(unsigned w) { return __uint_as_float(w << 16); }
; __device__ __forceinline__ float bf_hi(unsigned w) { return __uint_as_float(w & 0xffff0000u); }
;     __device__ __forceinline__ void operator()(const f32x4 (&acc)[2][2][4][2], const Unit& u, int wr, int wc, int fr, int fq) const {
;     ...
;             for (int mm = 0; mm < RB; ++mm) {
;                 const int m = mh + mm;
;                 const int row = row0 + ai * HALF + m * 16; const size_t off = (size_t)row * D_MODEL + col0; float s = 0.f;
; #pragma unroll
;                 for (int bj = 0; bj < 2; ++bj) {
;                     f32x4 b0, b1;
;                     if (BASE_F32) { b0 = bf[mm][bj][0]; b1 = bf[mm][bj][1]; }
;                     else { const u32x4 w = bb[mm][bj]; b0 = (f32x4){bf_lo(w.x), bf_hi(w.x), bf_lo(w.y), bf_hi(w.y)}; b1 = (f32x4){bf_lo(w.z), bf_hi(w.z), bf_lo(w.w), bf_hi(w.w)}; }
;                     const f32x4 o0 = b0 + acc[ai][bj][m][0] * alpha, o1 = b1 + acc[ai][bj][m][1] * alpha;
;                     if (OUT_F32) { *(f32x4*)(out + off + bj * HALF) = o0; *(f32x4*)(out + off + bj * HALF + 4) = o1; }
;                     else { u32x4 w; w.x = cvt_pk_bf16(o0[0], o0[1]); w.y = cvt_pk_bf16(o0[2], o0[3]); w.z = cvt_pk_bf16(o1[0], o1[1]); w.w = cvt_pk_bf16(o1[2], o1[3]); *(u32x4*)(xb + off + bj * HALF) = w; }
;                     s += ((o0[0] * o0[0] + o0[1] * o0[1]) + (o0[2] * o0[2] + o0[3] * o0[3])) + ((o1[0] * o1[0] + o1[1] * o1[1]) + (o1[2] * o1[2] + o1[3] * o1[3]));
;                 }
;                 if (ssp) { s += __shfl_xor(s, 16); s += __shfl_xor(s, 32); if (fq == 0) ssp[(size_t)row * 16 + u.pn * 4 + wc] = s; }
;             }
.LBB0_1041:
	v_readlane_b32 s2, v235, 38
	v_lshlrev_b32_e32 v116, 16, v150
	v_and_b32_e32 v117, 0xffff0000, v150
	v_readlane_b32 s3, v235, 39
	v_lshlrev_b32_e32 v112, 16, v148
	s_waitcnt lgkmcnt(0)
	v_and_b32_e32 v113, 0xffff0000, v148
	v_lshlrev_b32_e32 v114, 16, v149
	v_and_b32_e32 v115, 0xffff0000, v149
	v_lshlrev_b32_e32 v118, 16, v151
	v_and_b32_e32 v119, 0xffff0000, v151
	v_pk_fma_f32 v[104:105], v[104:105], 0.5, v[116:117] op_sel_hi:[1,0,1]
	v_lshl_add_u64 v[116:117], s[2:3], 0, v[182:183]
	v_pk_fma_f32 v[110:111], v[110:111], 0.5, v[114:115] op_sel_hi:[1,0,1]
	v_pk_fma_f32 v[108:109], v[108:109], 0.5, v[112:113] op_sel_hi:[1,0,1]
	v_pk_fma_f32 v[106:107], v[106:107], 0.5, v[118:119] op_sel_hi:[1,0,1]
	v_cvt_pk_bf16_f32 v112, v108, v109
	v_cvt_pk_bf16_f32 v113, v110, v111
	v_cvt_pk_bf16_f32 v114, v104, v105
	v_lshl_add_u64 v[116:117], v[166:167], 1, v[116:117]
	v_cvt_pk_bf16_f32 v115, v106, v107
	global_store_dwordx4 v[116:117], v[112:115], off
	v_lshlrev_b32_e32 v118, 16, v146
	v_and_b32_e32 v119, 0xffff0000, v146
	v_lshlrev_b32_e32 v112, 16, v144
	v_and_b32_e32 v113, 0xffff0000, v144
	v_lshlrev_b32_e32 v114, 16, v145
	v_and_b32_e32 v115, 0xffff0000, v145
	v_lshlrev_b32_e32 v120, 16, v147
	v_and_b32_e32 v121, 0xffff0000, v147
	v_pk_fma_f32 v[102:103], v[102:103], 0.5, v[114:115] op_sel_hi:[1,0,1]
	v_pk_fma_f32 v[100:101], v[100:101], 0.5, v[112:113] op_sel_hi:[1,0,1]
	v_pk_fma_f32 v[98:99], v[98:99], 0.5, v[120:121] op_sel_hi:[1,0,1]
	v_pk_fma_f32 v[96:97], v[96:97], 0.5, v[118:119] op_sel_hi:[1,0,1]
	s_and_b64 vcc, exec, s[8:9]
	v_cvt_pk_bf16_f32 v112, v100, v101
	v_cvt_pk_bf16_f32 v113, v102, v103
	v_cvt_pk_bf16_f32 v114, v96, v97
	v_cvt_pk_bf16_f32 v115, v98, v99
	global_store_dwordx4 v[116:117], v[112:115], off offset:256
	s_cbranch_vccnz .LBB0_1045
	v_mul_f32_e32 v97, v97, v97
	v_mul_f32_e32 v109, v109, v109
	v_mul_f32_e32 v105, v105, v105
	v_mul_f32_e32 v101, v101, v101
	v_fmac_f32_e32 v97, v96, v96
	v_mul_f32_e32 v96, v99, v99
	v_fmac_f32_e32 v109, v108, v108
	v_mul_f32_e32 v108, v111, v111
	v_fmac_f32_e32 v105, v104, v104
	v_mul_f32_e32 v104, v107, v107
	v_fmac_f32_e32 v101, v100, v100
	v_mul_f32_e32 v100, v103, v103
	v_fmac_f32_e32 v96, v98, v98
	v_and_b32_e32 v98, 64, v191
	v_fmac_f32_e32 v108, v110, v110
	v_fmac_f32_e32 v104, v106, v106
	v_fmac_f32_e32 v100, v102, v102
	v_add_f32_e32 v96, v97, v96
	v_xor_b32_e32 v97, 16, v191
	v_add_u32_e32 v98, 64, v98
	v_add_f32_e32 v108, v109, v108
	v_add_f32_e32 v104, v105, v104
	v_add_f32_e32 v100, v101, v100
	v_cmp_lt_i32_e32 vcc, v97, v98
	v_add_f32_e32 v104, v108, v104
	v_add_f32_e32 v96, v100, v96
	v_cndmask_b32_e32 v97, v191, v97, vcc
	v_add_f32_e32 v96, v104, v96
	v_lshlrev_b32_e32 v97, 2, v97
	v_mov_b32_e32 v236, v96
	v_mov_b32_e32 v237, v96
	s_nop 1
	v_permlane16_swap_b32_e32 v236, v237
	v_cndmask_b32_e64 v97, v237, v236, s[98:99]
	s_waitcnt lgkmcnt(0)
	v_add_f32_e32 v96, v96, v97
	v_xor_b32_e32 v97, 32, v191
	v_cmp_lt_i32_e32 vcc, v97, v98
	s_nop 1
	v_cndmask_b32_e32 v97, v191, v97, vcc
	v_lshlrev_b32_e32 v97, 2, v97
	v_mov_b32_e32 v236, v96
	v_mov_b32_e32 v237, v96
	s_nop 1
	v_permlane32_swap_b32_e32 v236, v237
	v_cndmask_b32_e64 v97, v237, v236, s[100:101]
	s_and_saveexec_b64 s[2:3], s[4:5]
	s_cbranch_execz .LBB0_1044
	v_readlane_b32 s22, v235, 50
	v_lshlrev_b64 v[98:99], 6, v[180:181]
	v_readlane_b32 s23, v235, 51
	s_lshl_b32 s10, s29, 2
	s_waitcnt lgkmcnt(0)
	v_add_f32_e32 v96, v96, v97
	v_lshl_add_u64 v[98:99], s[22:23], 0, v[98:99]
	v_lshl_add_u64 v[98:99], s[20:21], 2, v[98:99]
	v_lshl_add_u64 v[98:99], v[98:99], 0, s[10:11]
	global_store_dword v[98:99], v96, off

; __device__ __forceinline__ unsigned cvt_pk_bf16(float lo, float hi) { unsigned r; asm volatile("v_cvt_pk_bf16_f32 %0, %1, %2" : "=v"(r) : "v"(lo), "v"(hi)); return r; }
; __device__ __forceinline__ float bf_lo(unsigned w) { return __uint_as_float(w << 16); }
; __device__ __forceinline__ float bf_hi(unsigned w) { return __uint_as_float(w & 0xffff0000u); }
;     __device__ __forceinline__ void operator()(const f32x4 (&acc)[2][2][4][2], const Unit& u, int wr, int wc, int fr, int fq) const {
;     ...
;             for (int mm = 0; mm < RB; ++mm) {
;                 const int m = mh + mm;
;                 const int row = row0 + ai * HALF + m * 16; const size_t off = (size_t)row * D_MODEL + col0; float s = 0.f;
; #pragma unroll
;                 for (int bj = 0; bj < 2; ++bj) {
;                     f32x4 b0, b1;
;                     if (BASE_F32) { b0 = bf[mm][bj][0]; b1 = bf[mm][bj][1]; }
;                     else { const u32x4 w = bb[mm][bj]; b0 = (f32x4){bf_lo(w.x), bf_hi(w.x), bf_lo(w.y), bf_hi(w.y)}; b1 = (f32x4){bf_lo(w.z), bf_hi(w.z), bf_lo(w.w), bf_hi(w.w)}; }
;                     const f32x4 o0 = b0 + acc[ai][bj][m][0] * alpha, o1 = b1 + acc[ai][bj][m][1] * alpha;
;                     if (OUT_F32) { *(f32x4*)(out + off + bj * HALF) = o0; *(f32x4*)(out + off + bj * HALF + 4) = o1; }
;                     else { u32x4 w; w.x = cvt_pk_bf16(o0[0], o0[1]); w.y = cvt_pk_bf16(o0[2], o0[3]); w.z = cvt_pk_bf16(o1[0], o1[1]); w.w = cvt_pk_bf16(o1[2], o1[3]); *(u32x4*)(xb + off + bj * HALF) = w; }
;                     s += ((o0[0] * o0[0] + o0[1] * o0[1]) + (o0[2] * o0[2] + o0[3] * o0[3])) + ((o1[0] * o1[0] + o1[1] * o1[1]) + (o1[2] * o1[2] + o1[3] * o1[3]));
;                 }
;                 if (ssp) { s += __shfl_xor(s, 16); s += __shfl_xor(s, 32); if (fq == 0) ssp[(size_t)row * 16 + u.pn * 4 + wc] = s; }
;             }
.LBB0_1045:
	v_readlane_b32 s2, v235, 38
	v_lshlrev_b32_e32 v100, 16, v142
	v_and_b32_e32 v101, 0xffff0000, v142
	v_readlane_b32 s3, v235, 39
	v_lshlrev_b32_e32 v96, 16, v140
	s_waitcnt lgkmcnt(0)
	v_and_b32_e32 v97, 0xffff0000, v140
	v_lshlrev_b32_e32 v98, 16, v141
	v_and_b32_e32 v99, 0xffff0000, v141
	v_lshlrev_b32_e32 v102, 16, v143
	v_and_b32_e32 v103, 0xffff0000, v143
	v_pk_fma_f32 v[88:89], v[88:89], 0.5, v[100:101] op_sel_hi:[1,0,1]
	v_lshl_add_u64 v[100:101], s[2:3], 0, v[178:179]
	v_pk_fma_f32 v[94:95], v[94:95], 0.5, v[98:99] op_sel_hi:[1,0,1]
	v_pk_fma_f32 v[92:93], v[92:93], 0.5, v[96:97] op_sel_hi:[1,0,1]
	v_pk_fma_f32 v[90:91], v[90:91], 0.5, v[102:103] op_sel_hi:[1,0,1]
	v_cvt_pk_bf16_f32 v96, v92, v93
	v_cvt_pk_bf16_f32 v97, v94, v95
	v_cvt_pk_bf16_f32 v98, v88, v89
	v_lshl_add_u64 v[100:101], v[166:167], 1, v[100:101]
	v_cvt_pk_bf16_f32 v99, v90, v91
	global_store_dwordx4 v[100:101], v[96:99], off
	v_lshlrev_b32_e32 v102, 16, v138
	v_and_b32_e32 v103, 0xffff0000, v138
	v_lshlrev_b32_e32 v96, 16, v136
	v_and_b32_e32 v97, 0xffff0000, v136
	v_lshlrev_b32_e32 v98, 16, v137
	v_and_b32_e32 v99, 0xffff0000, v137
	v_lshlrev_b32_e32 v104, 16, v139
	v_and_b32_e32 v105, 0xffff0000, v139
	v_pk_fma_f32 v[86:87], v[86:87], 0.5, v[98:99] op_sel_hi:[1,0,1]
	v_pk_fma_f32 v[84:85], v[84:85], 0.5, v[96:97] op_sel_hi:[1,0,1]
	v_pk_fma_f32 v[82:83], v[82:83], 0.5, v[104:105] op_sel_hi:[1,0,1]
	v_pk_fma_f32 v[80:81], v[80:81], 0.5, v[102:103] op_sel_hi:[1,0,1]
	s_and_b64 vcc, exec, s[8:9]
	v_cvt_pk_bf16_f32 v96, v84, v85
	v_cvt_pk_bf16_f32 v97, v86, v87
	v_cvt_pk_bf16_f32 v98, v80, v81
	v_cvt_pk_bf16_f32 v99, v82, v83
	global_store_dwordx4 v[100:101], v[96:99], off offset:256
	s_cbranch_vccnz .LBB0_1049
	v_mul_f32_e32 v81, v81, v81
	v_mul_f32_e32 v93, v93, v93
	v_mul_f32_e32 v89, v89, v89
	v_mul_f32_e32 v85, v85, v85
	v_fmac_f32_e32 v81, v80, v80
	v_mul_f32_e32 v80, v83, v83
	v_fmac_f32_e32 v93, v92, v92
	v_mul_f32_e32 v92, v95, v95
	v_fmac_f32_e32 v89, v88, v88
	v_mul_f32_e32 v88, v91, v91
	v_fmac_f32_e32 v85, v84, v84
	v_mul_f32_e32 v84, v87, v87
	v_fmac_f32_e32 v80, v82, v82
	v_and_b32_e32 v82, 64, v191
	v_fmac_f32_e32 v92, v94, v94
	v_fmac_f32_e32 v88, v90, v90
	v_fmac_f32_e32 v84, v86, v86
	v_add_f32_e32 v80, v81, v80
	v_xor_b32_e32 v81, 16, v191
	v_add_u32_e32 v82, 64, v82
	v_add_f32_e32 v92, v93, v92
	v_add_f32_e32 v88, v89, v88
	v_add_f32_e32 v84, v85, v84
	v_cmp_lt_i32_e32 vcc, v81, v82
	v_add_f32_e32 v88, v92, v88
	v_add_f32_e32 v80, v84, v80
	v_cndmask_b32_e32 v81, v191, v81, vcc
	v_add_f32_e32 v80, v88, v80
	v_lshlrev_b32_e32 v81, 2, v81
	v_mov_b32_e32 v236, v80
	v_mov_b32_e32 v237, v80
	s_nop 1
	v_permlane16_swap_b32_e32 v236, v237
	v_cndmask_b32_e64 v81, v237, v236, s[98:99]
	s_waitcnt lgkmcnt(0)
	v_add_f32_e32 v80, v80, v81
	v_xor_b32_e32 v81, 32, v191
	v_cmp_lt_i32_e32 vcc, v81, v82
	s_nop 1
	v_cndmask_b32_e32 v81, v191, v81, vcc
	v_lshlrev_b32_e32 v81, 2, v81
	v_mov_b32_e32 v236, v80
	v_mov_b32_e32 v237, v80
	s_nop 1
	v_permlane32_swap_b32_e32 v236, v237
	v_cndmask_b32_e64 v81, v237, v236, s[100:101]
	s_and_saveexec_b64 s[2:3], s[4:5]
	s_cbranch_execz .LBB0_1048
	v_readlane_b32 s22, v235, 50
	v_lshlrev_b64 v[82:83], 6, v[176:177]
	v_readlane_b32 s23, v235, 51
	s_lshl_b32 s10, s29, 2
	s_waitcnt lgkmcnt(0)
	v_add_f32_e32 v80, v80, v81
	v_lshl_add_u64 v[82:83], s[22:23], 0, v[82:83]
	v_lshl_add_u64 v[82:83], s[20:21], 2, v[82:83]
	v_lshl_add_u64 v[82:83], v[82:83], 0, s[10:11]
	global_store_dword v[82:83], v80, off

; __device__ __forceinline__ unsigned cvt_pk_bf16(float lo, float hi) { unsigned r; asm volatile("v_cvt_pk_bf16_f32 %0, %1, %2" : "=v"(r) : "v"(lo), "v"(hi)); return r; }
; __device__ __forceinline__ float bf_lo(unsigned w) { return __uint_as_float(w << 16); }
; __device__ __forceinline__ float bf_hi(unsigned w) { return __uint_as_float(w & 0xffff0000u); }
;     __device__ __forceinline__ void operator()(const f32x4 (&acc)[2][2][4][2], const Unit& u, int wr, int wc, int fr, int fq) const {
;     ...
;             for (int mm = 0; mm < RB; ++mm) {
;                 const int m = mh + mm;
;                 const int row = row0 + ai * HALF + m * 16; const size_t off = (size_t)row * D_MODEL + col0; float s = 0.f;
; #pragma unroll
;                 for (int bj = 0; bj < 2; ++bj) {
;                     f32x4 b0, b1;
;                     if (BASE_F32) { b0 = bf[mm][bj][0]; b1 = bf[mm][bj][1]; }
;                     else { const u32x4 w = bb[mm][bj]; b0 = (f32x4){bf_lo(w.x), bf_hi(w.x), bf_lo(w.y), bf_hi(w.y)}; b1 = (f32x4){bf_lo(w.z), bf_hi(w.z), bf_lo(w.w), bf_hi(w.w)}; }
;                     const f32x4 o0 = b0 + acc[ai][bj][m][0] * alpha, o1 = b1 + acc[ai][bj][m][1] * alpha;
;                     if (OUT_F32) { *(f32x4*)(out + off + bj * HALF) = o0; *(f32x4*)(out + off + bj * HALF + 4) = o1; }
;                     else { u32x4 w; w.x = cvt_pk_bf16(o0[0], o0[1]); w.y = cvt_pk_bf16(o0[2], o0[3]); w.z = cvt_pk_bf16(o1[0], o1[1]); w.w = cvt_pk_bf16(o1[2], o1[3]); *(u32x4*)(xb + off + bj * HALF) = w; }
;                     s += ((o0[0] * o0[0] + o0[1] * o0[1]) + (o0[2] * o0[2] + o0[3] * o0[3])) + ((o1[0] * o1[0] + o1[1] * o1[1]) + (o1[2] * o1[2] + o1[3] * o1[3]));
;                 }
;                 if (ssp) { s += __shfl_xor(s, 16); s += __shfl_xor(s, 32); if (fq == 0) ssp[(size_t)row * 16 + u.pn * 4 + wc] = s; }
;             }
.LBB0_1049:
	v_readlane_b32 s2, v235, 38
	v_lshlrev_b32_e32 v84, 16, v134
	v_and_b32_e32 v85, 0xffff0000, v134
	v_readlane_b32 s3, v235, 39
	v_lshlrev_b32_e32 v80, 16, v132
	s_waitcnt lgkmcnt(0)
	v_and_b32_e32 v81, 0xffff0000, v132
	v_lshlrev_b32_e32 v82, 16, v133
	v_and_b32_e32 v83, 0xffff0000, v133
	v_lshlrev_b32_e32 v86, 16, v135
	v_and_b32_e32 v87, 0xffff0000, v135
	v_pk_fma_f32 v[72:73], v[72:73], 0.5, v[84:85] op_sel_hi:[1,0,1]
	v_lshl_add_u64 v[84:85], s[2:3], 0, v[174:175]
	v_pk_fma_f32 v[78:79], v[78:79], 0.5, v[82:83] op_sel_hi:[1,0,1]
	v_pk_fma_f32 v[76:77], v[76:77], 0.5, v[80:81] op_sel_hi:[1,0,1]
	v_pk_fma_f32 v[74:75], v[74:75], 0.5, v[86:87] op_sel_hi:[1,0,1]
	v_cvt_pk_bf16_f32 v80, v76, v77
	v_cvt_pk_bf16_f32 v81, v78, v79
	v_cvt_pk_bf16_f32 v82, v72, v73
	v_lshl_add_u64 v[84:85], v[166:167], 1, v[84:85]
	v_cvt_pk_bf16_f32 v83, v74, v75
	global_store_dwordx4 v[84:85], v[80:83], off
	v_lshlrev_b32_e32 v86, 16, v130
	v_and_b32_e32 v87, 0xffff0000, v130
	v_lshlrev_b32_e32 v80, 16, v128
	v_and_b32_e32 v81, 0xffff0000, v128
	v_lshlrev_b32_e32 v82, 16, v129
	v_and_b32_e32 v83, 0xffff0000, v129
	v_lshlrev_b32_e32 v88, 16, v131
	v_and_b32_e32 v89, 0xffff0000, v131
	v_pk_fma_f32 v[70:71], v[70:71], 0.5, v[82:83] op_sel_hi:[1,0,1]
	v_pk_fma_f32 v[68:69], v[68:69], 0.5, v[80:81] op_sel_hi:[1,0,1]
	v_pk_fma_f32 v[66:67], v[66:67], 0.5, v[88:89] op_sel_hi:[1,0,1]
	v_pk_fma_f32 v[64:65], v[64:65], 0.5, v[86:87] op_sel_hi:[1,0,1]
	s_and_b64 vcc, exec, s[8:9]
	v_cvt_pk_bf16_f32 v80, v68, v69
	v_cvt_pk_bf16_f32 v81, v70, v71
	v_cvt_pk_bf16_f32 v82, v64, v65
	v_cvt_pk_bf16_f32 v83, v66, v67
	global_store_dwordx4 v[84:85], v[80:83], off offset:256
	s_cbranch_vccnz .LBB0_1053
	v_mul_f32_e32 v65, v65, v65
	v_mul_f32_e32 v77, v77, v77
	v_mul_f32_e32 v73, v73, v73
	v_mul_f32_e32 v69, v69, v69
	v_fmac_f32_e32 v65, v64, v64
	v_mul_f32_e32 v64, v67, v67
	v_fmac_f32_e32 v77, v76, v76
	v_mul_f32_e32 v76, v79, v79
	v_fmac_f32_e32 v73, v72, v72
	v_mul_f32_e32 v72, v75, v75
	v_fmac_f32_e32 v69, v68, v68
	v_mul_f32_e32 v68, v71, v71
	v_fmac_f32_e32 v64, v66, v66
	v_and_b32_e32 v66, 64, v191
	v_fmac_f32_e32 v76, v78, v78
	v_fmac_f32_e32 v72, v74, v74
	v_fmac_f32_e32 v68, v70, v70
	v_add_f32_e32 v64, v65, v64
	v_xor_b32_e32 v65, 16, v191
	v_add_u32_e32 v66, 64, v66
	v_add_f32_e32 v76, v77, v76
	v_add_f32_e32 v72, v73, v72
	v_add_f32_e32 v68, v69, v68
	v_cmp_lt_i32_e32 vcc, v65, v66
	v_add_f32_e32 v72, v76, v72
	v_add_f32_e32 v64, v68, v64
	v_cndmask_b32_e32 v65, v191, v65, vcc
	v_add_f32_e32 v64, v72, v64
	v_lshlrev_b32_e32 v65, 2, v65
	v_mov_b32_e32 v236, v64
	v_mov_b32_e32 v237, v64
	s_nop 1
	v_permlane16_swap_b32_e32 v236, v237
	v_cndmask_b32_e64 v65, v237, v236, s[98:99]
	s_waitcnt lgkmcnt(0)
	v_add_f32_e32 v64, v64, v65
	v_xor_b32_e32 v65, 32, v191
	v_cmp_lt_i32_e32 vcc, v65, v66
	s_nop 1
	v_cndmask_b32_e32 v65, v191, v65, vcc
	v_lshlrev_b32_e32 v65, 2, v65
	v_mov_b32_e32 v236, v64
	v_mov_b32_e32 v237, v64
	s_nop 1
	v_permlane32_swap_b32_e32 v236, v237
	v_cndmask_b32_e64 v65, v237, v236, s[100:101]
	s_and_saveexec_b64 s[2:3], s[4:5]
	s_cbranch_execz .LBB0_1052
	v_readlane_b32 s22, v235, 50
	v_lshlrev_b64 v[66:67], 6, v[172:173]
	v_readlane_b32 s23, v235, 51
	s_lshl_b32 s10, s29, 2
	s_waitcnt lgkmcnt(0)
	v_add_f32_e32 v64, v64, v65
	v_lshl_add_u64 v[66:67], s[22:23], 0, v[66:67]
	v_lshl_add_u64 v[66:67], s[20:21], 2, v[66:67]
	v_lshl_add_u64 v[66:67], v[66:67], 0, s[10:11]
	global_store_dword v[66:67], v64, off

; __device__ __forceinline__ unsigned cvt_pk_bf16(float lo, float hi) { unsigned r; asm volatile("v_cvt_pk_bf16_f32 %0, %1, %2" : "=v"(r) : "v"(lo), "v"(hi)); return r; }
; __device__ __forceinline__ float bf_lo(unsigned w) { return __uint_as_float(w << 16); }
;     __device__ __forceinline__ void operator()(const f32x4 (&acc)[2][2][4][2], const Unit& u, int wr, int wc, int fr, int fq) const {
;     ...
;             f32x4 bf[BASE_F32 ? RB : 1][2][2]; u32x4 bb[BASE_F32 ? 1 : RB][2];
; #pragma unroll
;             for (int mm = 0; mm < RB; ++mm) { const size_t off = (size_t)(row0 + ai * HALF + (mh + mm) * 16) * D_MODEL + col0;
; #pragma unroll
;                 for (int bj = 0; bj < 2; ++bj) {
;                     if (BASE_F32) { bf[mm][bj][0] = *(const f32x4*)(basef + off + bj * HALF); bf[mm][bj][1] = *(const f32x4*)(basef + off + bj * HALF + 4); }
;                     else bb[mm][bj] = *(const u32x4*)(xb + off + bj * HALF);
;                 } }
;             asm volatile("" ::: "memory");
; #pragma unroll
;             for (int mm = 0; mm < RB; ++mm) {
;                 const int m = mh + mm;
;                 const int row = row0 + ai * HALF + m * 16; const size_t off = (size_t)row * D_MODEL + col0; float s = 0.f;
; #pragma unroll
;                 for (int bj = 0; bj < 2; ++bj) {
;                     f32x4 b0, b1;
;                     if (BASE_F32) { b0 = bf[mm][bj][0]; b1 = bf[mm][bj][1]; }
;                     else { const u32x4 w = bb[mm][bj]; b0 = (f32x4){bf_lo(w.x), bf_hi(w.x), bf_lo(w.y), bf_hi(w.y)}; b1 = (f32x4){bf_lo(w.z), bf_hi(w.z), bf_lo(w.w), bf_hi(w.w)}; }
;                     const f32x4 o0 = b0 + acc[ai][bj][m][0] * alpha, o1 = b1 + acc[ai][bj][m][1] * alpha;
;                     if (OUT_F32) { *(f32x4*)(out + off + bj * HALF) = o0; *(f32x4*)(out + off + bj * HALF + 4) = o1; }
;                     else { u32x4 w; w.x = cvt_pk_bf16(o0[0], o0[1]); w.y = cvt_pk_bf16(o0[2], o0[3]); w.z = cvt_pk_bf16(o1[0], o1[1]); w.w = cvt_pk_bf16(o1[2], o1[3]); *(u32x4*)(xb + off + bj * HALF) = w; }
;                     s += ((o0[0] * o0[0] + o0[1] * o0[1]) + (o0[2] * o0[2] + o0[3] * o0[3])) + ((o1[0] * o1[0] + o1[1] * o1[1]) + (o1[2] * o1[2] + o1[3] * o1[3]));
;                 }
;                 if (ssp) { s += __shfl_xor(s, 16); s += __shfl_xor(s, 32); if (fq == 0) ssp[(size_t)row * 16 + u.pn * 4 + wc] = s; }
;             }
.LBB0_1053:
	v_add_u32_e32 v100, 0x80, v168
	v_ashrrev_i32_e32 v101, 31, v100
	v_add_u32_e32 v96, 0x90, v168
	v_add_u32_e32 v92, 0xa0, v168
	v_lshlrev_b64 v[110:111], 11, v[100:101]
	v_add_u32_e32 v88, 0xb0, v168
	v_ashrrev_i32_e32 v97, 31, v96
	v_ashrrev_i32_e32 v93, 31, v92
	s_waitcnt lgkmcnt(0)
	v_lshl_add_u64 v[64:65], v[170:171], 0, v[110:111]
	v_ashrrev_i32_e32 v89, 31, v88
	v_lshlrev_b64 v[98:99], 11, v[96:97]
	v_lshlrev_b64 v[94:95], 11, v[92:93]
	global_load_dwordx4 v[102:105], v[64:65], off
	global_load_dwordx4 v[106:109], v[64:65], off offset:256
	v_lshlrev_b64 v[90:91], 11, v[88:89]
	v_lshl_add_u64 v[64:65], v[170:171], 0, v[98:99]
	v_lshl_add_u64 v[66:67], v[170:171], 0, v[94:95]
	v_lshl_add_u64 v[112:113], v[170:171], 0, v[90:91]
	global_load_dwordx4 v[84:87], v[64:65], off
	global_load_dwordx4 v[80:83], v[64:65], off offset:256
	global_load_dwordx4 v[76:79], v[66:67], off
	global_load_dwordx4 v[72:75], v[66:67], off offset:256
	global_load_dwordx4 v[68:71], v[112:113], off
	s_nop 0
	global_load_dwordx4 v[64:67], v[112:113], off offset:256
	v_readlane_b32 s2, v235, 38
	v_readlane_b32 s3, v235, 39
	s_and_b64 vcc, exec, s[8:9]
	s_waitcnt vmcnt(7)
	v_lshlrev_b32_e32 v112, 16, v102
	v_lshl_add_u64 v[110:111], s[2:3], 0, v[110:111]
	v_and_b32_e32 v113, 0xffff0000, v102
	v_lshlrev_b32_e32 v102, 16, v103
	v_and_b32_e32 v103, 0xffff0000, v103
	v_lshlrev_b32_e32 v114, 16, v104
	v_and_b32_e32 v115, 0xffff0000, v104
	v_lshlrev_b32_e32 v104, 16, v105
	v_and_b32_e32 v105, 0xffff0000, v105
	s_waitcnt vmcnt(6)
	v_lshlrev_b32_e32 v116, 16, v106
	v_and_b32_e32 v117, 0xffff0000, v106
	v_lshlrev_b32_e32 v106, 16, v107
	v_and_b32_e32 v107, 0xffff0000, v107
	v_lshlrev_b32_e32 v118, 16, v108
	v_and_b32_e32 v119, 0xffff0000, v108
	v_lshlrev_b32_e32 v108, 16, v109
	v_and_b32_e32 v109, 0xffff0000, v109
	v_lshl_add_u64 v[110:111], v[166:167], 1, v[110:111]
	v_pk_fma_f32 v[62:63], v[62:63], 0.5, v[102:103] op_sel_hi:[1,0,1]
	v_pk_fma_f32 v[60:61], v[60:61], 0.5, v[112:113] op_sel_hi:[1,0,1]
	v_pk_fma_f32 v[58:59], v[58:59], 0.5, v[104:105] op_sel_hi:[1,0,1]
	v_pk_fma_f32 v[56:57], v[56:57], 0.5, v[114:115] op_sel_hi:[1,0,1]
	v_pk_fma_f32 v[54:55], v[54:55], 0.5, v[106:107] op_sel_hi:[1,0,1]
	v_pk_fma_f32 v[52:53], v[52:53], 0.5, v[116:117] op_sel_hi:[1,0,1]
	v_pk_fma_f32 v[50:51], v[50:51], 0.5, v[108:109] op_sel_hi:[1,0,1]
	v_pk_fma_f32 v[48:49], v[48:49], 0.5, v[118:119] op_sel_hi:[1,0,1]
	v_cvt_pk_bf16_f32 v102, v60, v61
	v_cvt_pk_bf16_f32 v103, v62, v63
	v_cvt_pk_bf16_f32 v104, v56, v57
	v_cvt_pk_bf16_f32 v105, v58, v59
	global_store_dwordx4 v[110:111], v[102:105], off
	s_nop 1
	v_cvt_pk_bf16_f32 v102, v52, v53
	v_cvt_pk_bf16_f32 v103, v54, v55
	v_cvt_pk_bf16_f32 v104, v48, v49
	v_cvt_pk_bf16_f32 v105, v50, v51
	global_store_dwordx4 v[110:111], v[102:105], off offset:256
	s_cbranch_vccnz .LBB0_1057
	v_mul_f32_e32 v49, v49, v49
	v_mul_f32_e32 v61, v61, v61
	v_mul_f32_e32 v57, v57, v57
	v_mul_f32_e32 v53, v53, v53
	v_fmac_f32_e32 v49, v48, v48
	v_mul_f32_e32 v48, v51, v51
	v_fmac_f32_e32 v61, v60, v60
	v_mul_f32_e32 v60, v63, v63
	v_fmac_f32_e32 v57, v56, v56
	v_mul_f32_e32 v56, v59, v59
	v_fmac_f32_e32 v53, v52, v52
	v_mul_f32_e32 v52, v55, v55
	v_fmac_f32_e32 v48, v50, v50
	v_and_b32_e32 v50, 64, v191
	v_fmac_f32_e32 v60, v62, v62
	v_fmac_f32_e32 v56, v58, v58
	v_fmac_f32_e32 v52, v54, v54
	v_add_f32_e32 v48, v49, v48
	v_xor_b32_e32 v49, 16, v191
	v_add_u32_e32 v50, 64, v50
	v_add_f32_e32 v60, v61, v60
	v_add_f32_e32 v56, v57, v56
	v_add_f32_e32 v52, v53, v52
	v_cmp_lt_i32_e32 vcc, v49, v50
	v_add_f32_e32 v56, v60, v56
	v_add_f32_e32 v48, v52, v48
	v_cndmask_b32_e32 v49, v191, v49, vcc
	v_add_f32_e32 v48, v56, v48
	v_lshlrev_b32_e32 v49, 2, v49
	v_mov_b32_e32 v236, v48
	v_mov_b32_e32 v237, v48
	s_nop 1
	v_permlane16_swap_b32_e32 v236, v237
	v_cndmask_b32_e64 v49, v237, v236, s[98:99]
	s_waitcnt lgkmcnt(0)
	v_add_f32_e32 v48, v48, v49
	v_xor_b32_e32 v49, 32, v191
	v_cmp_lt_i32_e32 vcc, v49, v50
	s_nop 1
	v_cndmask_b32_e32 v49, v191, v49, vcc
	v_lshlrev_b32_e32 v49, 2, v49
	v_mov_b32_e32 v236, v48
	v_mov_b32_e32 v237, v48
	s_nop 1
	v_permlane32_swap_b32_e32 v236, v237
	v_cndmask_b32_e64 v49, v237, v236, s[100:101]
	s_and_saveexec_b64 s[2:3], s[4:5]
	s_cbranch_execz .LBB0_1056
	v_readlane_b32 s22, v235, 50
	v_lshlrev_b64 v[50:51], 6, v[100:101]
	v_readlane_b32 s23, v235, 51
	s_lshl_b32 s10, s29, 2
	s_waitcnt lgkmcnt(0)
	v_add_f32_e32 v48, v48, v49
	v_lshl_add_u64 v[50:51], s[22:23], 0, v[50:51]
	v_lshl_add_u64 v[50:51], s[20:21], 2, v[50:51]
	v_lshl_add_u64 v[50:51], v[50:51], 0, s[10:11]
	global_store_dword v[50:51], v48, off

; __device__ __forceinline__ unsigned cvt_pk_bf16(float lo, float hi) { unsigned r; asm volatile("v_cvt_pk_bf16_f32 %0, %1, %2" : "=v"(r) : "v"(lo), "v"(hi)); return r; }
; __device__ __forceinline__ float bf_lo(unsigned w) { return __uint_as_float(w << 16); }
; __device__ __forceinline__ float bf_hi(unsigned w) { return __uint_as_float(w & 0xffff0000u); }
;     __device__ __forceinline__ void operator()(const f32x4 (&acc)[2][2][4][2], const Unit& u, int wr, int wc, int fr, int fq) const {
;     ...
;             for (int mm = 0; mm < RB; ++mm) {
;                 const int m = mh + mm;
;                 const int row = row0 + ai * HALF + m * 16; const size_t off = (size_t)row * D_MODEL + col0; float s = 0.f;
; #pragma unroll
;                 for (int bj = 0; bj < 2; ++bj) {
;                     f32x4 b0, b1;
;                     if (BASE_F32) { b0 = bf[mm][bj][0]; b1 = bf[mm][bj][1]; }
;                     else { const u32x4 w = bb[mm][bj]; b0 = (f32x4){bf_lo(w.x), bf_hi(w.x), bf_lo(w.y), bf_hi(w.y)}; b1 = (f32x4){bf_lo(w.z), bf_hi(w.z), bf_lo(w.w), bf_hi(w.w)}; }
;                     const f32x4 o0 = b0 + acc[ai][bj][m][0] * alpha, o1 = b1 + acc[ai][bj][m][1] * alpha;
;                     if (OUT_F32) { *(f32x4*)(out + off + bj * HALF) = o0; *(f32x4*)(out + off + bj * HALF + 4) = o1; }
;                     else { u32x4 w; w.x = cvt_pk_bf16(o0[0], o0[1]); w.y = cvt_pk_bf16(o0[2], o0[3]); w.z = cvt_pk_bf16(o1[0], o1[1]); w.w = cvt_pk_bf16(o1[2], o1[3]); *(u32x4*)(xb + off + bj * HALF) = w; }
;                     s += ((o0[0] * o0[0] + o0[1] * o0[1]) + (o0[2] * o0[2] + o0[3] * o0[3])) + ((o1[0] * o1[0] + o1[1] * o1[1]) + (o1[2] * o1[2] + o1[3] * o1[3]));
;                 }
;                 if (ssp) { s += __shfl_xor(s, 16); s += __shfl_xor(s, 32); if (fq == 0) ssp[(size_t)row * 16 + u.pn * 4 + wc] = s; }
;             }
.LBB0_1057:
	v_readlane_b32 s2, v235, 38
	s_waitcnt vmcnt(7)
	v_lshlrev_b32_e32 v52, 16, v86
	v_and_b32_e32 v53, 0xffff0000, v86
	v_readlane_b32 s3, v235, 39
	v_lshlrev_b32_e32 v48, 16, v84
	s_waitcnt lgkmcnt(0)
	v_and_b32_e32 v49, 0xffff0000, v84
	v_lshlrev_b32_e32 v50, 16, v85
	v_and_b32_e32 v51, 0xffff0000, v85
	v_lshlrev_b32_e32 v54, 16, v87
	v_and_b32_e32 v55, 0xffff0000, v87
	v_pk_fma_f32 v[40:41], v[40:41], 0.5, v[52:53] op_sel_hi:[1,0,1]
	v_lshl_add_u64 v[52:53], s[2:3], 0, v[98:99]
	v_pk_fma_f32 v[46:47], v[46:47], 0.5, v[50:51] op_sel_hi:[1,0,1]
	v_pk_fma_f32 v[44:45], v[44:45], 0.5, v[48:49] op_sel_hi:[1,0,1]
	v_pk_fma_f32 v[42:43], v[42:43], 0.5, v[54:55] op_sel_hi:[1,0,1]
	v_cvt_pk_bf16_f32 v48, v44, v45
	v_cvt_pk_bf16_f32 v49, v46, v47
	v_cvt_pk_bf16_f32 v50, v40, v41
	v_lshl_add_u64 v[52:53], v[166:167], 1, v[52:53]
	v_cvt_pk_bf16_f32 v51, v42, v43
	global_store_dwordx4 v[52:53], v[48:51], off
	s_waitcnt vmcnt(7)
	v_lshlrev_b32_e32 v54, 16, v82
	v_and_b32_e32 v55, 0xffff0000, v82
	v_lshlrev_b32_e32 v48, 16, v80
	v_and_b32_e32 v49, 0xffff0000, v80
	v_lshlrev_b32_e32 v50, 16, v81
	v_and_b32_e32 v51, 0xffff0000, v81
	v_lshlrev_b32_e32 v56, 16, v83
	v_and_b32_e32 v57, 0xffff0000, v83
	v_pk_fma_f32 v[38:39], v[38:39], 0.5, v[50:51] op_sel_hi:[1,0,1]
	v_pk_fma_f32 v[36:37], v[36:37], 0.5, v[48:49] op_sel_hi:[1,0,1]
	v_pk_fma_f32 v[34:35], v[34:35], 0.5, v[56:57] op_sel_hi:[1,0,1]
	v_pk_fma_f32 v[32:33], v[32:33], 0.5, v[54:55] op_sel_hi:[1,0,1]
	s_and_b64 vcc, exec, s[8:9]
	v_cvt_pk_bf16_f32 v48, v36, v37
	v_cvt_pk_bf16_f32 v49, v38, v39
	v_cvt_pk_bf16_f32 v50, v32, v33
	v_cvt_pk_bf16_f32 v51, v34, v35
	global_store_dwordx4 v[52:53], v[48:51], off offset:256
	s_cbranch_vccnz .LBB0_1061
	v_mul_f32_e32 v33, v33, v33
	v_mul_f32_e32 v45, v45, v45
	v_mul_f32_e32 v41, v41, v41
	v_mul_f32_e32 v37, v37, v37
	v_fmac_f32_e32 v33, v32, v32
	v_mul_f32_e32 v32, v35, v35
	v_fmac_f32_e32 v45, v44, v44
	v_mul_f32_e32 v44, v47, v47
	v_fmac_f32_e32 v41, v40, v40
	v_mul_f32_e32 v40, v43, v43
	v_fmac_f32_e32 v37, v36, v36
	v_mul_f32_e32 v36, v39, v39
	v_fmac_f32_e32 v32, v34, v34
	v_and_b32_e32 v34, 64, v191
	v_fmac_f32_e32 v44, v46, v46
	v_fmac_f32_e32 v40, v42, v42
	v_fmac_f32_e32 v36, v38, v38
	v_add_f32_e32 v32, v33, v32
	v_xor_b32_e32 v33, 16, v191
	v_add_u32_e32 v34, 64, v34
	v_add_f32_e32 v44, v45, v44
	v_add_f32_e32 v40, v41, v40
	v_add_f32_e32 v36, v37, v36
	v_cmp_lt_i32_e32 vcc, v33, v34
	v_add_f32_e32 v40, v44, v40
	v_add_f32_e32 v32, v36, v32
	v_cndmask_b32_e32 v33, v191, v33, vcc
	v_add_f32_e32 v32, v40, v32
	v_lshlrev_b32_e32 v33, 2, v33
	v_mov_b32_e32 v236, v32
	v_mov_b32_e32 v237, v32
	s_nop 1
	v_permlane16_swap_b32_e32 v236, v237
	v_cndmask_b32_e64 v33, v237, v236, s[98:99]
	s_waitcnt lgkmcnt(0)
	v_add_f32_e32 v32, v32, v33
	v_xor_b32_e32 v33, 32, v191
	v_cmp_lt_i32_e32 vcc, v33, v34
	s_nop 1
	v_cndmask_b32_e32 v33, v191, v33, vcc
	v_lshlrev_b32_e32 v33, 2, v33
	v_mov_b32_e32 v236, v32
	v_mov_b32_e32 v237, v32
	s_nop 1
	v_permlane32_swap_b32_e32 v236, v237
	v_cndmask_b32_e64 v33, v237, v236, s[100:101]
	s_and_saveexec_b64 s[2:3], s[4:5]
	s_cbranch_execz .LBB0_1060
	v_readlane_b32 s22, v235, 50
	v_lshlrev_b64 v[34:35], 6, v[96:97]
	v_readlane_b32 s23, v235, 51
	s_lshl_b32 s10, s29, 2
	s_waitcnt lgkmcnt(0)
	v_add_f32_e32 v32, v32, v33
	v_lshl_add_u64 v[34:35], s[22:23], 0, v[34:35]
	v_lshl_add_u64 v[34:35], s[20:21], 2, v[34:35]
	v_lshl_add_u64 v[34:35], v[34:35], 0, s[10:11]
	global_store_dword v[34:35], v32, off

; __device__ __forceinline__ unsigned cvt_pk_bf16(float lo, float hi) { unsigned r; asm volatile("v_cvt_pk_bf16_f32 %0, %1, %2" : "=v"(r) : "v"(lo), "v"(hi)); return r; }
; __device__ __forceinline__ float bf_lo(unsigned w) { return __uint_as_float(w << 16); }
; __device__ __forceinline__ float bf_hi(unsigned w) { return __uint_as_float(w & 0xffff0000u); }
;     __device__ __forceinline__ void operator()(const f32x4 (&acc)[2][2][4][2], const Unit& u, int wr, int wc, int fr, int fq) const {
;     ...
;             for (int mm = 0; mm < RB; ++mm) {
;                 const int m = mh + mm;
;                 const int row = row0 + ai * HALF + m * 16; const size_t off = (size_t)row * D_MODEL + col0; float s = 0.f;
; #pragma unroll
;                 for (int bj = 0; bj < 2; ++bj) {
;                     f32x4 b0, b1;
;                     if (BASE_F32) { b0 = bf[mm][bj][0]; b1 = bf[mm][bj][1]; }
;                     else { const u32x4 w = bb[mm][bj]; b0 = (f32x4){bf_lo(w.x), bf_hi(w.x), bf_lo(w.y), bf_hi(w.y)}; b1 = (f32x4){bf_lo(w.z), bf_hi(w.z), bf_lo(w.w), bf_hi(w.w)}; }
;                     const f32x4 o0 = b0 + acc[ai][bj][m][0] * alpha, o1 = b1 + acc[ai][bj][m][1] * alpha;
;                     if (OUT_F32) { *(f32x4*)(out + off + bj * HALF) = o0; *(f32x4*)(out + off + bj * HALF + 4) = o1; }
;                     else { u32x4 w; w.x = cvt_pk_bf16(o0[0], o0[1]); w.y = cvt_pk_bf16(o0[2], o0[3]); w.z = cvt_pk_bf16(o1[0], o1[1]); w.w = cvt_pk_bf16(o1[2], o1[3]); *(u32x4*)(xb + off + bj * HALF) = w; }
;                     s += ((o0[0] * o0[0] + o0[1] * o0[1]) + (o0[2] * o0[2] + o0[3] * o0[3])) + ((o1[0] * o1[0] + o1[1] * o1[1]) + (o1[2] * o1[2] + o1[3] * o1[3]));
;                 }
;                 if (ssp) { s += __shfl_xor(s, 16); s += __shfl_xor(s, 32); if (fq == 0) ssp[(size_t)row * 16 + u.pn * 4 + wc] = s; }
;             }
.LBB0_1061:
	v_readlane_b32 s2, v235, 38
	s_waitcnt vmcnt(7)
	v_lshlrev_b32_e32 v36, 16, v78
	v_and_b32_e32 v37, 0xffff0000, v78
	v_readlane_b32 s3, v235, 39
	v_lshlrev_b32_e32 v32, 16, v76
	s_waitcnt lgkmcnt(0)
	v_and_b32_e32 v33, 0xffff0000, v76
	v_lshlrev_b32_e32 v34, 16, v77
	v_and_b32_e32 v35, 0xffff0000, v77
	v_lshlrev_b32_e32 v38, 16, v79
	v_and_b32_e32 v39, 0xffff0000, v79
	v_pk_fma_f32 v[24:25], v[24:25], 0.5, v[36:37] op_sel_hi:[1,0,1]
	v_lshl_add_u64 v[36:37], s[2:3], 0, v[94:95]
	v_pk_fma_f32 v[30:31], v[30:31], 0.5, v[34:35] op_sel_hi:[1,0,1]
	v_pk_fma_f32 v[28:29], v[28:29], 0.5, v[32:33] op_sel_hi:[1,0,1]
	v_pk_fma_f32 v[26:27], v[26:27], 0.5, v[38:39] op_sel_hi:[1,0,1]
	v_cvt_pk_bf16_f32 v32, v28, v29
	v_cvt_pk_bf16_f32 v33, v30, v31
	v_cvt_pk_bf16_f32 v34, v24, v25
	v_lshl_add_u64 v[36:37], v[166:167], 1, v[36:37]
	v_cvt_pk_bf16_f32 v35, v26, v27
	global_store_dwordx4 v[36:37], v[32:35], off
	s_waitcnt vmcnt(7)
	v_lshlrev_b32_e32 v38, 16, v74
	v_and_b32_e32 v39, 0xffff0000, v74
	v_lshlrev_b32_e32 v32, 16, v72
	v_and_b32_e32 v33, 0xffff0000, v72
	v_lshlrev_b32_e32 v34, 16, v73
	v_and_b32_e32 v35, 0xffff0000, v73
	v_lshlrev_b32_e32 v40, 16, v75
	v_and_b32_e32 v41, 0xffff0000, v75
	v_pk_fma_f32 v[22:23], v[22:23], 0.5, v[34:35] op_sel_hi:[1,0,1]
	v_pk_fma_f32 v[20:21], v[20:21], 0.5, v[32:33] op_sel_hi:[1,0,1]
	v_pk_fma_f32 v[18:19], v[18:19], 0.5, v[40:41] op_sel_hi:[1,0,1]
	v_pk_fma_f32 v[16:17], v[16:17], 0.5, v[38:39] op_sel_hi:[1,0,1]
	s_and_b64 vcc, exec, s[8:9]
	v_cvt_pk_bf16_f32 v32, v20, v21
	v_cvt_pk_bf16_f32 v33, v22, v23
	v_cvt_pk_bf16_f32 v34, v16, v17
	v_cvt_pk_bf16_f32 v35, v18, v19
	global_store_dwordx4 v[36:37], v[32:35], off offset:256
	s_cbranch_vccnz .LBB0_1065
	v_mul_f32_e32 v17, v17, v17
	v_mul_f32_e32 v29, v29, v29
	v_mul_f32_e32 v25, v25, v25
	v_mul_f32_e32 v21, v21, v21
	v_fmac_f32_e32 v17, v16, v16
	v_mul_f32_e32 v16, v19, v19
	v_fmac_f32_e32 v29, v28, v28
	v_mul_f32_e32 v28, v31, v31
	v_fmac_f32_e32 v25, v24, v24
	v_mul_f32_e32 v24, v27, v27
	v_fmac_f32_e32 v21, v20, v20
	v_mul_f32_e32 v20, v23, v23
	v_fmac_f32_e32 v16, v18, v18
	v_and_b32_e32 v18, 64, v191
	v_fmac_f32_e32 v28, v30, v30
	v_fmac_f32_e32 v24, v26, v26
	v_fmac_f32_e32 v20, v22, v22
	v_add_f32_e32 v16, v17, v16
	v_xor_b32_e32 v17, 16, v191
	v_add_u32_e32 v18, 64, v18
	v_add_f32_e32 v28, v29, v28
	v_add_f32_e32 v24, v25, v24
	v_add_f32_e32 v20, v21, v20
	v_cmp_lt_i32_e32 vcc, v17, v18
	v_add_f32_e32 v24, v28, v24
	v_add_f32_e32 v16, v20, v16
	v_cndmask_b32_e32 v17, v191, v17, vcc
	v_add_f32_e32 v16, v24, v16
	v_lshlrev_b32_e32 v17, 2, v17
	v_mov_b32_e32 v236, v16
	v_mov_b32_e32 v237, v16
	s_nop 1
	v_permlane16_swap_b32_e32 v236, v237
	v_cndmask_b32_e64 v17, v237, v236, s[98:99]
	s_waitcnt lgkmcnt(0)
	v_add_f32_e32 v16, v16, v17
	v_xor_b32_e32 v17, 32, v191
	v_cmp_lt_i32_e32 vcc, v17, v18
	s_nop 1
	v_cndmask_b32_e32 v17, v191, v17, vcc
	v_lshlrev_b32_e32 v17, 2, v17
	v_mov_b32_e32 v236, v16
	v_mov_b32_e32 v237, v16
	s_nop 1
	v_permlane32_swap_b32_e32 v236, v237
	v_cndmask_b32_e64 v17, v237, v236, s[100:101]
	s_and_saveexec_b64 s[2:3], s[4:5]
	s_cbranch_execz .LBB0_1064
	v_readlane_b32 s22, v235, 50
	v_lshlrev_b64 v[18:19], 6, v[92:93]
	v_readlane_b32 s23, v235, 51
	s_lshl_b32 s10, s29, 2
	s_waitcnt lgkmcnt(0)
	v_add_f32_e32 v16, v16, v17
	v_lshl_add_u64 v[18:19], s[22:23], 0, v[18:19]
	v_lshl_add_u64 v[18:19], s[20:21], 2, v[18:19]
	v_lshl_add_u64 v[18:19], v[18:19], 0, s[10:11]
	global_store_dword v[18:19], v16, off

; __device__ __forceinline__ unsigned cvt_pk_bf16(float lo, float hi) { unsigned r; asm volatile("v_cvt_pk_bf16_f32 %0, %1, %2" : "=v"(r) : "v"(lo), "v"(hi)); return r; }
; __device__ __forceinline__ float bf_lo(unsigned w) { return __uint_as_float(w << 16); }
; __device__ __forceinline__ float bf_hi(unsigned w) { return __uint_as_float(w & 0xffff0000u); }
;     __device__ __forceinline__ void operator()(const f32x4 (&acc)[2][2][4][2], const Unit& u, int wr, int wc, int fr, int fq) const {
;     ...
;             for (int mm = 0; mm < RB; ++mm) {
;                 const int m = mh + mm;
;                 const int row = row0 + ai * HALF + m * 16; const size_t off = (size_t)row * D_MODEL + col0; float s = 0.f;
; #pragma unroll
;                 for (int bj = 0; bj < 2; ++bj) {
;                     f32x4 b0, b1;
;                     if (BASE_F32) { b0 = bf[mm][bj][0]; b1 = bf[mm][bj][1]; }
;                     else { const u32x4 w = bb[mm][bj]; b0 = (f32x4){bf_lo(w.x), bf_hi(w.x), bf_lo(w.y), bf_hi(w.y)}; b1 = (f32x4){bf_lo(w.z), bf_hi(w.z), bf_lo(w.w), bf_hi(w.w)}; }
;                     const f32x4 o0 = b0 + acc[ai][bj][m][0] * alpha, o1 = b1 + acc[ai][bj][m][1] * alpha;
;                     if (OUT_F32) { *(f32x4*)(out + off + bj * HALF) = o0; *(f32x4*)(out + off + bj * HALF + 4) = o1; }
;                     else { u32x4 w; w.x = cvt_pk_bf16(o0[0], o0[1]); w.y = cvt_pk_bf16(o0[2], o0[3]); w.z = cvt_pk_bf16(o1[0], o1[1]); w.w = cvt_pk_bf16(o1[2], o1[3]); *(u32x4*)(xb + off + bj * HALF) = w; }
;                     s += ((o0[0] * o0[0] + o0[1] * o0[1]) + (o0[2] * o0[2] + o0[3] * o0[3])) + ((o1[0] * o1[0] + o1[1] * o1[1]) + (o1[2] * o1[2] + o1[3] * o1[3]));
;                 }
;                 if (ssp) { s += __shfl_xor(s, 16); s += __shfl_xor(s, 32); if (fq == 0) ssp[(size_t)row * 16 + u.pn * 4 + wc] = s; }
;             }
.LBB0_1065:
	v_readlane_b32 s2, v235, 38
	s_waitcnt vmcnt(7)
	v_lshlrev_b32_e32 v20, 16, v70
	v_and_b32_e32 v21, 0xffff0000, v70
	v_readlane_b32 s3, v235, 39
	v_lshlrev_b32_e32 v16, 16, v68
	s_waitcnt lgkmcnt(0)
	v_and_b32_e32 v17, 0xffff0000, v68
	v_lshlrev_b32_e32 v18, 16, v69
	v_and_b32_e32 v19, 0xffff0000, v69
	v_lshlrev_b32_e32 v22, 16, v71
	v_and_b32_e32 v23, 0xffff0000, v71
	v_pk_fma_f32 v[8:9], v[8:9], 0.5, v[20:21] op_sel_hi:[1,0,1]
	v_lshl_add_u64 v[20:21], s[2:3], 0, v[90:91]
	v_pk_fma_f32 v[14:15], v[14:15], 0.5, v[18:19] op_sel_hi:[1,0,1]
	v_pk_fma_f32 v[12:13], v[12:13], 0.5, v[16:17] op_sel_hi:[1,0,1]
	v_pk_fma_f32 v[10:11], v[10:11], 0.5, v[22:23] op_sel_hi:[1,0,1]
	v_cvt_pk_bf16_f32 v16, v12, v13
	v_cvt_pk_bf16_f32 v17, v14, v15
	v_cvt_pk_bf16_f32 v18, v8, v9
	v_lshl_add_u64 v[20:21], v[166:167], 1, v[20:21]
	v_cvt_pk_bf16_f32 v19, v10, v11
	global_store_dwordx4 v[20:21], v[16:19], off
	s_waitcnt vmcnt(7)
	v_lshlrev_b32_e32 v22, 16, v66
	v_and_b32_e32 v23, 0xffff0000, v66
	v_lshlrev_b32_e32 v16, 16, v64
	v_and_b32_e32 v17, 0xffff0000, v64
	v_lshlrev_b32_e32 v18, 16, v65
	v_and_b32_e32 v19, 0xffff0000, v65
	v_lshlrev_b32_e32 v24, 16, v67
	v_and_b32_e32 v25, 0xffff0000, v67
	v_pk_fma_f32 v[6:7], v[6:7], 0.5, v[18:19] op_sel_hi:[1,0,1]
	v_pk_fma_f32 v[4:5], v[4:5], 0.5, v[16:17] op_sel_hi:[1,0,1]
	v_pk_fma_f32 v[2:3], v[2:3], 0.5, v[24:25] op_sel_hi:[1,0,1]
	v_pk_fma_f32 v[0:1], v[0:1], 0.5, v[22:23] op_sel_hi:[1,0,1]
	s_and_b64 vcc, exec, s[8:9]
	v_cvt_pk_bf16_f32 v16, v4, v5
	v_cvt_pk_bf16_f32 v17, v6, v7
	v_cvt_pk_bf16_f32 v18, v0, v1
	v_cvt_pk_bf16_f32 v19, v2, v3
	global_store_dwordx4 v[20:21], v[16:19], off offset:256
	s_cbranch_vccnz .LBB0_1069
	v_mul_f32_e32 v1, v1, v1
	v_mul_f32_e32 v13, v13, v13
	v_mul_f32_e32 v9, v9, v9
	v_mul_f32_e32 v5, v5, v5
	v_fmac_f32_e32 v1, v0, v0
	v_mul_f32_e32 v0, v3, v3
	v_fmac_f32_e32 v13, v12, v12
	v_mul_f32_e32 v12, v15, v15
	v_fmac_f32_e32 v9, v8, v8
	v_mul_f32_e32 v8, v11, v11
	v_fmac_f32_e32 v5, v4, v4
	v_mul_f32_e32 v4, v7, v7
	v_fmac_f32_e32 v0, v2, v2
	v_and_b32_e32 v2, 64, v191
	v_fmac_f32_e32 v12, v14, v14
	v_fmac_f32_e32 v8, v10, v10
	v_fmac_f32_e32 v4, v6, v6
	v_add_f32_e32 v0, v1, v0
	v_xor_b32_e32 v1, 16, v191
	v_add_u32_e32 v2, 64, v2
	v_add_f32_e32 v12, v13, v12
	v_add_f32_e32 v8, v9, v8
	v_add_f32_e32 v4, v5, v4
	v_cmp_lt_i32_e32 vcc, v1, v2
	v_add_f32_e32 v8, v12, v8
	v_add_f32_e32 v0, v4, v0
	v_cndmask_b32_e32 v1, v191, v1, vcc
	v_add_f32_e32 v0, v8, v0
	v_lshlrev_b32_e32 v1, 2, v1
	v_mov_b32_e32 v236, v0
	v_mov_b32_e32 v237, v0
	s_nop 1
	v_permlane16_swap_b32_e32 v236, v237
	v_cndmask_b32_e64 v1, v237, v236, s[98:99]
	s_waitcnt lgkmcnt(0)
	v_add_f32_e32 v0, v0, v1
	v_xor_b32_e32 v1, 32, v191
	v_cmp_lt_i32_e32 vcc, v1, v2
	s_nop 1
	v_cndmask_b32_e32 v1, v191, v1, vcc
	v_lshlrev_b32_e32 v1, 2, v1
	v_mov_b32_e32 v236, v0
	v_mov_b32_e32 v237, v0
	s_nop 1
	v_permlane32_swap_b32_e32 v236, v237
	v_cndmask_b32_e64 v1, v237, v236, s[100:101]
	s_and_saveexec_b64 s[2:3], s[4:5]
	s_cbranch_execz .LBB0_1068
	v_readlane_b32 s8, v235, 50
	v_lshlrev_b64 v[2:3], 6, v[88:89]
	v_readlane_b32 s9, v235, 51
	s_lshl_b32 s10, s29, 2
	s_waitcnt lgkmcnt(0)
	v_add_f32_e32 v0, v0, v1
	v_lshl_add_u64 v[2:3], s[8:9], 0, v[2:3]
	v_lshl_add_u64 v[2:3], s[20:21], 2, v[2:3]
	v_lshl_add_u64 v[2:3], v[2:3], 0, s[10:11]
	global_store_dword v[2:3], v0, off

; __device__ __forceinline__ float bf_lo(unsigned w) { return __uint_as_float(w << 16); }
; __device__ __forceinline__ float bf_hi(unsigned w) { return __uint_as_float(w & 0xffff0000u); }
;     __device__ __forceinline__ void operator()(const f32x4 (&acc)[2][2][4][2], const Unit& u, int wr, int wc, int fr, int fq) const {
;     ...
;             u32x4 bb[4][2];
; #pragma unroll
;             for (int m = 0; m < 4; ++m)
; #pragma unroll
;                 for (int bj = 0; bj < 2; ++bj) bb[m][bj] = *(const u32x4*)(xb + (size_t)(row0 + ai * HALF + m * 16) * D_MODEL + col0 + bj * HALF);
; #pragma unroll
;             for (int m = 0; m < 4; ++m) { float s = 0.f;
; #pragma unroll
;                 for (int bj = 0; bj < 2; ++bj) { const u32x4 w = bb[m][bj];
;                     const f32x4 o0 = (f32x4){bf_lo(w.x), bf_hi(w.x), bf_lo(w.y), bf_hi(w.y)} + acc[ai][bj][m][0] * alpha, o1 = (f32x4){bf_lo(w.z), bf_hi(w.z), bf_lo(w.w), bf_hi(w.w)} + acc[ai][bj][m][1] * alpha;
;                     o[ai][m][bj][0] = o0; o[ai][m][bj][1] = o1;
;                     s += ((o0[0] * o0[0] + o0[1] * o0[1]) + (o0[2] * o0[2] + o0[3] * o0[3])) + ((o1[0] * o1[0] + o1[1] * o1[1]) + (o1[2] * o1[2] + o1[3] * o1[3])); }
;                 s += __shfl_xor(s, 16); s += __shfl_xor(s, 32);
;                 if (fq == 0) ssp[(size_t)(row0 + ai * HALF + m * 16) * 16 + u.pn * 4 + wc] = s; }
.LBB0_1180:
	v_lshl_add_u32 v176, s42, 8, v197
	v_lshl_or_b32 v174, s43, 8, v199
	v_readlane_b32 s2, v235, 38
	v_ashrrev_i32_e32 v175, 31, v174
	v_readlane_b32 s3, v235, 39
	v_ashrrev_i32_e32 v177, 31, v176
	v_lshlrev_b64 v[128:129], 11, v[176:177]
	v_lshl_add_u64 v[194:195], v[174:175], 1, s[2:3]
	v_lshl_add_u64 v[128:129], v[194:195], 0, v[128:129]
	global_load_dwordx4 v[178:181], v[128:129], off
	global_load_dwordx4 v[182:185], v[128:129], off offset:256
	v_or_b32_e32 v172, 16, v176
	v_or_b32_e32 v170, 32, v176
	v_or_b32_e32 v168, 48, v176
	v_ashrrev_i32_e32 v173, 31, v172
	v_ashrrev_i32_e32 v171, 31, v170
	v_ashrrev_i32_e32 v169, 31, v168
	v_lshlrev_b64 v[128:129], 11, v[172:173]
	v_lshlrev_b64 v[130:131], 11, v[170:171]
	v_lshlrev_b64 v[132:133], 11, v[168:169]
	v_lshl_add_u64 v[128:129], v[194:195], 0, v[128:129]
	v_lshl_add_u64 v[130:131], v[194:195], 0, v[130:131]
	v_lshl_add_u64 v[186:187], v[194:195], 0, v[132:133]
	global_load_dwordx4 v[148:151], v[128:129], off
	global_load_dwordx4 v[144:147], v[128:129], off offset:256
	global_load_dwordx4 v[140:143], v[130:131], off
	global_load_dwordx4 v[136:139], v[130:131], off offset:256
	global_load_dwordx4 v[132:135], v[186:187], off
	s_nop 0
	global_load_dwordx4 v[128:131], v[186:187], off offset:256
	v_and_b32_e32 v187, 64, v203
	v_xor_b32_e32 v186, 16, v203
	v_add_u32_e32 v207, 64, v187
	v_cmp_lt_i32_e32 vcc, v186, v207
	v_xor_b32_e32 v206, 32, v203
	s_lshl_b32 s2, s43, 2
	v_cndmask_b32_e32 v186, v203, v186, vcc
	v_lshlrev_b32_e32 v205, 2, v186
	v_cmp_lt_i32_e32 vcc, v206, v207
	s_ashr_i32 s3, s2, 31
	s_lshl_b64 s[2:3], s[2:3], 2
	s_add_u32 s2, s36, s2
	s_addc_u32 s3, s37, s3
	s_waitcnt vmcnt(0)
	v_lshlrev_b32_e32 v186, 16, v178
	v_and_b32_e32 v187, 0xffff0000, v178
	v_lshlrev_b32_e32 v178, 16, v179
	v_and_b32_e32 v179, 0xffff0000, v179
	v_lshlrev_b32_e32 v188, 16, v180
	v_and_b32_e32 v189, 0xffff0000, v180
	v_lshlrev_b32_e32 v180, 16, v181
	v_and_b32_e32 v181, 0xffff0000, v181
	v_lshlrev_b32_e32 v190, 16, v182
	v_and_b32_e32 v191, 0xffff0000, v182
	v_lshlrev_b32_e32 v182, 16, v183
	v_and_b32_e32 v183, 0xffff0000, v183
	v_lshlrev_b32_e32 v192, 16, v184
	v_and_b32_e32 v193, 0xffff0000, v184
	v_lshlrev_b32_e32 v184, 16, v185
	v_and_b32_e32 v185, 0xffff0000, v185
	v_pk_fma_f32 v[126:127], v[126:127], 0.5, v[178:179] op_sel_hi:[1,0,1]
	v_pk_fma_f32 v[124:125], v[124:125], 0.5, v[186:187] op_sel_hi:[1,0,1]
	v_pk_fma_f32 v[122:123], v[122:123], 0.5, v[180:181] op_sel_hi:[1,0,1]
	v_pk_fma_f32 v[120:121], v[120:121], 0.5, v[188:189] op_sel_hi:[1,0,1]
	v_pk_fma_f32 v[118:119], v[118:119], 0.5, v[182:183] op_sel_hi:[1,0,1]
	v_pk_fma_f32 v[116:117], v[116:117], 0.5, v[190:191] op_sel_hi:[1,0,1]
	v_pk_fma_f32 v[114:115], v[114:115], 0.5, v[184:185] op_sel_hi:[1,0,1]
	v_pk_fma_f32 v[112:113], v[112:113], 0.5, v[192:193] op_sel_hi:[1,0,1]
	v_mul_f32_e32 v178, v125, v125
	v_mul_f32_e32 v179, v127, v127
	v_mul_f32_e32 v180, v121, v121
	v_mul_f32_e32 v181, v123, v123
	v_mul_f32_e32 v182, v117, v117
	v_mul_f32_e32 v183, v119, v119
	v_mul_f32_e32 v184, v113, v113
	v_mul_f32_e32 v185, v115, v115
	v_fmac_f32_e32 v178, v124, v124
	v_fmac_f32_e32 v179, v126, v126
	v_fmac_f32_e32 v180, v120, v120
	v_fmac_f32_e32 v181, v122, v122
	v_fmac_f32_e32 v182, v116, v116
	v_fmac_f32_e32 v183, v118, v118
	v_fmac_f32_e32 v184, v112, v112
	v_fmac_f32_e32 v185, v114, v114
	v_add_f32_e32 v178, v178, v179
	v_add_f32_e32 v179, v180, v181
	v_add_f32_e32 v180, v182, v183
	v_add_f32_e32 v181, v184, v185
	v_add_f32_e32 v178, v178, v179
	v_add_f32_e32 v179, v180, v181
	v_add_f32_e32 v178, v178, v179
	v_mov_b32_e32 v236, v178
	v_mov_b32_e32 v237, v178
	s_nop 1
	v_permlane16_swap_b32_e32 v236, v237
	v_cndmask_b32_e64 v179, v237, v236, s[98:99]
	v_cndmask_b32_e32 v180, v203, v206, vcc
	v_lshlrev_b32_e32 v206, 2, v180
	v_lshlrev_b64 v[186:187], 6, v[176:177]
	s_waitcnt lgkmcnt(0)
	v_add_f32_e32 v178, v178, v179
	v_mov_b32_e32 v236, v178
	v_mov_b32_e32 v237, v178
	s_nop 1
	v_permlane32_swap_b32_e32 v236, v237
	v_cndmask_b32_e64 v179, v237, v236, s[100:101]
	s_and_saveexec_b64 s[20:21], s[0:1]
	s_cbranch_execz .LBB0_1182
	s_waitcnt lgkmcnt(0)
	v_add_f32_e32 v180, v178, v179
	v_lshl_add_u64 v[178:179], s[2:3], 0, v[186:187]
	global_store_dword v[178:179], v180, off
.LBB0_1182:
	s_or_b64 exec, exec, s[20:21]
	v_lshlrev_b32_e32 v178, 16, v148
	s_waitcnt lgkmcnt(0)
	v_and_b32_e32 v179, 0xffff0000, v148
	v_lshlrev_b32_e32 v148, 16, v149
	v_and_b32_e32 v149, 0xffff0000, v149
	v_pk_fma_f32 v[110:111], v[110:111], 0.5, v[148:149] op_sel_hi:[1,0,1]
	v_pk_fma_f32 v[108:109], v[108:109], 0.5, v[178:179] op_sel_hi:[1,0,1]
	v_lshlrev_b32_e32 v148, 16, v150
	v_and_b32_e32 v149, 0xffff0000, v150
	v_lshlrev_b32_e32 v150, 16, v151
	v_and_b32_e32 v151, 0xffff0000, v151
	v_pk_fma_f32 v[104:105], v[104:105], 0.5, v[148:149] op_sel_hi:[1,0,1]
	v_mul_f32_e32 v148, v109, v109
	v_mul_f32_e32 v149, v111, v111
	v_pk_fma_f32 v[106:107], v[106:107], 0.5, v[150:151] op_sel_hi:[1,0,1]
	v_fmac_f32_e32 v148, v108, v108
	v_fmac_f32_e32 v149, v110, v110
	v_add_f32_e32 v148, v148, v149
	v_mul_f32_e32 v149, v105, v105
	v_mul_f32_e32 v150, v107, v107
	v_fmac_f32_e32 v149, v104, v104
	v_fmac_f32_e32 v150, v106, v106
	v_add_f32_e32 v149, v149, v150
	v_add_f32_e32 v150, v148, v149
	v_lshlrev_b32_e32 v148, 16, v144
	v_and_b32_e32 v149, 0xffff0000, v144
	v_lshlrev_b32_e32 v144, 16, v145
	v_and_b32_e32 v145, 0xffff0000, v145
	v_pk_fma_f32 v[102:103], v[102:103], 0.5, v[144:145] op_sel_hi:[1,0,1]
	v_pk_fma_f32 v[100:101], v[100:101], 0.5, v[148:149] op_sel_hi:[1,0,1]
	v_lshlrev_b32_e32 v144, 16, v146
	v_and_b32_e32 v145, 0xffff0000, v146
	v_lshlrev_b32_e32 v146, 16, v147
	v_and_b32_e32 v147, 0xffff0000, v147
	v_pk_fma_f32 v[96:97], v[96:97], 0.5, v[144:145] op_sel_hi:[1,0,1]
	v_mul_f32_e32 v144, v101, v101
	v_mul_f32_e32 v145, v103, v103
	v_pk_fma_f32 v[98:99], v[98:99], 0.5, v[146:147] op_sel_hi:[1,0,1]
	v_fmac_f32_e32 v144, v100, v100
	v_fmac_f32_e32 v145, v102, v102
	v_add_f32_e32 v144, v144, v145
	v_mul_f32_e32 v145, v97, v97
	v_mul_f32_e32 v146, v99, v99
	v_fmac_f32_e32 v145, v96, v96
	v_fmac_f32_e32 v146, v98, v98
	v_add_f32_e32 v145, v145, v146
	v_add_f32_e32 v144, v144, v145
	v_add_f32_e32 v144, v150, v144
	v_mov_b32_e32 v236, v144
	v_mov_b32_e32 v237, v144
	s_nop 1
	v_permlane16_swap_b32_e32 v236, v237
	v_cndmask_b32_e64 v145, v237, v236, s[98:99]
	v_lshlrev_b64 v[188:189], 6, v[172:173]
	s_waitcnt lgkmcnt(0)
	v_add_f32_e32 v144, v144, v145
	v_mov_b32_e32 v236, v144
	v_mov_b32_e32 v237, v144
	s_nop 1
	v_permlane32_swap_b32_e32 v236, v237
	v_cndmask_b32_e64 v145, v237, v236, s[100:101]
	s_and_saveexec_b64 s[20:21], s[0:1]
	s_cbranch_execz .LBB0_1184
	s_waitcnt lgkmcnt(0)
	v_add_f32_e32 v146, v144, v145
	v_lshl_add_u64 v[144:145], s[2:3], 0, v[188:189]
	global_store_dword v[144:145], v146, off
; __device__ __forceinline__ float bf_lo(unsigned w) { return __uint_as_float(w << 16); }
; __device__ __forceinline__ float bf_hi(unsigned w) { return __uint_as_float(w & 0xffff0000u); }
;     __device__ __forceinline__ void operator()(const f32x4 (&acc)[2][2][4][2], const Unit& u, int wr, int wc, int fr, int fq) const {
;     ...
;             for (int m = 0; m < 4; ++m) { float s = 0.f;
; #pragma unroll
;                 for (int bj = 0; bj < 2; ++bj) { const u32x4 w = bb[m][bj];
;                     const f32x4 o0 = (f32x4){bf_lo(w.x), bf_hi(w.x), bf_lo(w.y), bf_hi(w.y)} + acc[ai][bj][m][0] * alpha, o1 = (f32x4){bf_lo(w.z), bf_hi(w.z), bf_lo(w.w), bf_hi(w.w)} + acc[ai][bj][m][1] * alpha;
;                     o[ai][m][bj][0] = o0; o[ai][m][bj][1] = o1;
;                     s += ((o0[0] * o0[0] + o0[1] * o0[1]) + (o0[2] * o0[2] + o0[3] * o0[3])) + ((o1[0] * o1[0] + o1[1] * o1[1]) + (o1[2] * o1[2] + o1[3] * o1[3])); }
;                 s += __shfl_xor(s, 16); s += __shfl_xor(s, 32);
;                 if (fq == 0) ssp[(size_t)(row0 + ai * HALF + m * 16) * 16 + u.pn * 4 + wc] = s; }
.LBB0_1184:
	s_or_b64 exec, exec, s[20:21]
	v_lshlrev_b32_e32 v144, 16, v140
	s_waitcnt lgkmcnt(0)
	v_and_b32_e32 v145, 0xffff0000, v140
	v_lshlrev_b32_e32 v140, 16, v141
	v_and_b32_e32 v141, 0xffff0000, v141
	v_pk_fma_f32 v[94:95], v[94:95], 0.5, v[140:141] op_sel_hi:[1,0,1]
	v_pk_fma_f32 v[144:145], v[92:93], 0.5, v[144:145] op_sel_hi:[1,0,1]
	v_lshlrev_b32_e32 v92, 16, v142
	v_and_b32_e32 v93, 0xffff0000, v142
	v_lshlrev_b32_e32 v140, 16, v143
	v_and_b32_e32 v141, 0xffff0000, v143
	v_pk_fma_f32 v[90:91], v[90:91], 0.5, v[140:141] op_sel_hi:[1,0,1]
	v_pk_fma_f32 v[140:141], v[88:89], 0.5, v[92:93] op_sel_hi:[1,0,1]
	v_mul_f32_e32 v88, v145, v145
	v_mul_f32_e32 v89, v95, v95
	v_fmac_f32_e32 v88, v144, v144
	v_fmac_f32_e32 v89, v94, v94
	v_add_f32_e32 v88, v88, v89
	v_mul_f32_e32 v89, v141, v141
	v_mul_f32_e32 v92, v91, v91
	v_fmac_f32_e32 v89, v140, v140
	v_fmac_f32_e32 v92, v90, v90
	v_add_f32_e32 v89, v89, v92
	v_add_f32_e32 v148, v88, v89
	v_lshlrev_b32_e32 v88, 16, v136
	v_and_b32_e32 v89, 0xffff0000, v136
	v_lshlrev_b32_e32 v92, 16, v137
	v_and_b32_e32 v93, 0xffff0000, v137
	v_pk_fma_f32 v[136:137], v[86:87], 0.5, v[92:93] op_sel_hi:[1,0,1]
	v_pk_fma_f32 v[142:143], v[84:85], 0.5, v[88:89] op_sel_hi:[1,0,1]
	v_lshlrev_b32_e32 v84, 16, v138
	v_and_b32_e32 v85, 0xffff0000, v138
	v_lshlrev_b32_e32 v86, 16, v139
	v_and_b32_e32 v87, 0xffff0000, v139
	v_pk_fma_f32 v[146:147], v[80:81], 0.5, v[84:85] op_sel_hi:[1,0,1]
	v_mul_f32_e32 v80, v143, v143
	v_mul_f32_e32 v81, v137, v137
	v_pk_fma_f32 v[138:139], v[82:83], 0.5, v[86:87] op_sel_hi:[1,0,1]
	v_fmac_f32_e32 v80, v142, v142
	v_fmac_f32_e32 v81, v136, v136
	v_add_f32_e32 v80, v80, v81
	v_mul_f32_e32 v81, v147, v147
	v_mul_f32_e32 v82, v139, v139
	v_fmac_f32_e32 v81, v146, v146
	v_fmac_f32_e32 v82, v138, v138
	v_add_f32_e32 v81, v81, v82
	v_add_f32_e32 v80, v80, v81
	v_add_f32_e32 v80, v148, v80
	v_mov_b32_e32 v236, v80
	v_mov_b32_e32 v237, v80
	s_nop 1
	v_permlane16_swap_b32_e32 v236, v237
	v_cndmask_b32_e64 v81, v237, v236, s[98:99]
	v_lshlrev_b64 v[190:191], 6, v[170:171]
	s_waitcnt lgkmcnt(0)
	v_add_f32_e32 v80, v80, v81
	v_mov_b32_e32 v236, v80
	v_mov_b32_e32 v237, v80
	s_nop 1
	v_permlane32_swap_b32_e32 v236, v237
	v_cndmask_b32_e64 v81, v237, v236, s[100:101]
	s_and_saveexec_b64 s[20:21], s[0:1]
	s_cbranch_execz .LBB0_1186
	s_waitcnt lgkmcnt(0)
	v_add_f32_e32 v82, v80, v81
	v_lshl_add_u64 v[80:81], s[2:3], 0, v[190:191]
	global_store_dword v[80:81], v82, off
.LBB0_1186:
	s_or_b64 exec, exec, s[20:21]
	v_lshlrev_b32_e32 v80, 16, v132
	s_waitcnt lgkmcnt(0)
	v_and_b32_e32 v81, 0xffff0000, v132
	v_lshlrev_b32_e32 v82, 16, v133
	v_and_b32_e32 v83, 0xffff0000, v133
	v_pk_fma_f32 v[148:149], v[78:79], 0.5, v[82:83] op_sel_hi:[1,0,1]
	v_pk_fma_f32 v[150:151], v[76:77], 0.5, v[80:81] op_sel_hi:[1,0,1]
	v_lshlrev_b32_e32 v76, 16, v134
	v_and_b32_e32 v77, 0xffff0000, v134
	v_lshlrev_b32_e32 v78, 16, v135
	v_and_b32_e32 v79, 0xffff0000, v135
	v_pk_fma_f32 v[134:135], v[72:73], 0.5, v[76:77] op_sel_hi:[1,0,1]
	v_mul_f32_e32 v72, v151, v151
	v_mul_f32_e32 v73, v149, v149
	v_pk_fma_f32 v[132:133], v[74:75], 0.5, v[78:79] op_sel_hi:[1,0,1]
	v_fmac_f32_e32 v72, v150, v150
	v_fmac_f32_e32 v73, v148, v148
	v_add_f32_e32 v72, v72, v73
	v_mul_f32_e32 v73, v135, v135
	v_mul_f32_e32 v74, v133, v133
	v_fmac_f32_e32 v73, v134, v134
	v_fmac_f32_e32 v74, v132, v132
	v_add_f32_e32 v73, v73, v74
	v_add_f32_e32 v76, v72, v73
	v_lshlrev_b32_e32 v72, 16, v128
	v_and_b32_e32 v73, 0xffff0000, v128
	v_lshlrev_b32_e32 v74, 16, v129
	v_and_b32_e32 v75, 0xffff0000, v129
	v_pk_fma_f32 v[178:179], v[70:71], 0.5, v[74:75] op_sel_hi:[1,0,1]
	v_pk_fma_f32 v[180:181], v[68:69], 0.5, v[72:73] op_sel_hi:[1,0,1]
	v_lshlrev_b32_e32 v68, 16, v130
	v_and_b32_e32 v69, 0xffff0000, v130
	v_lshlrev_b32_e32 v70, 16, v131
	v_and_b32_e32 v71, 0xffff0000, v131
	v_pk_fma_f32 v[182:183], v[64:65], 0.5, v[68:69] op_sel_hi:[1,0,1]
	v_mul_f32_e32 v64, v181, v181
	v_mul_f32_e32 v65, v179, v179
	v_pk_fma_f32 v[130:131], v[66:67], 0.5, v[70:71] op_sel_hi:[1,0,1]
	v_fmac_f32_e32 v64, v180, v180
	v_fmac_f32_e32 v65, v178, v178
	v_add_f32_e32 v64, v64, v65
	v_mul_f32_e32 v65, v183, v183
	v_mul_f32_e32 v66, v131, v131
	v_fmac_f32_e32 v65, v182, v182
	v_fmac_f32_e32 v66, v130, v130
	v_add_f32_e32 v65, v65, v66
	v_add_f32_e32 v64, v64, v65
	v_add_f32_e32 v64, v76, v64
	v_mov_b32_e32 v236, v64
	v_mov_b32_e32 v237, v64
	s_nop 1
	v_permlane16_swap_b32_e32 v236, v237
	v_cndmask_b32_e64 v65, v237, v236, s[98:99]
	v_lshlrev_b64 v[192:193], 6, v[168:169]
	s_waitcnt lgkmcnt(0)
	v_add_f32_e32 v64, v64, v65
	v_mov_b32_e32 v236, v64
	v_mov_b32_e32 v237, v64
	s_nop 1
	v_permlane32_swap_b32_e32 v236, v237
	v_cndmask_b32_e64 v65, v237, v236, s[100:101]
	s_and_saveexec_b64 s[20:21], s[0:1]
	s_cbranch_execz .LBB0_1188
	s_waitcnt lgkmcnt(0)
	v_add_f32_e32 v66, v64, v65
	v_lshl_add_u64 v[64:65], s[2:3], 0, v[192:193]
	global_store_dword v[64:65], v66, off
; __device__ __forceinline__ float bf_lo(unsigned w) { return __uint_as_float(w << 16); }
; __device__ __forceinline__ float bf_hi(unsigned w) { return __uint_as_float(w & 0xffff0000u); }
;     __device__ __forceinline__ void operator()(const f32x4 (&acc)[2][2][4][2], const Unit& u, int wr, int wc, int fr, int fq) const {
;     ...
;             u32x4 bb[4][2];
; #pragma unroll
;             for (int m = 0; m < 4; ++m)
; #pragma unroll
;                 for (int bj = 0; bj < 2; ++bj) bb[m][bj] = *(const u32x4*)(xb + (size_t)(row0 + ai * HALF + m * 16) * D_MODEL + col0 + bj * HALF);
; #pragma unroll
;             for (int m = 0; m < 4; ++m) { float s = 0.f;
; #pragma unroll
;                 for (int bj = 0; bj < 2; ++bj) { const u32x4 w = bb[m][bj];
;                     const f32x4 o0 = (f32x4){bf_lo(w.x), bf_hi(w.x), bf_lo(w.y), bf_hi(w.y)} + acc[ai][bj][m][0] * alpha, o1 = (f32x4){bf_lo(w.z), bf_hi(w.z), bf_lo(w.w), bf_hi(w.w)} + acc[ai][bj][m][1] * alpha;
;                     o[ai][m][bj][0] = o0; o[ai][m][bj][1] = o1;
;                     s += ((o0[0] * o0[0] + o0[1] * o0[1]) + (o0[2] * o0[2] + o0[3] * o0[3])) + ((o1[0] * o1[0] + o1[1] * o1[1]) + (o1[2] * o1[2] + o1[3] * o1[3])); }
;                 s += __shfl_xor(s, 16); s += __shfl_xor(s, 32);
;                 if (fq == 0) ssp[(size_t)(row0 + ai * HALF + m * 16) * 16 + u.pn * 4 + wc] = s; }
.LBB0_1188:
	s_or_b64 exec, exec, s[20:21]
	v_add_u32_e32 v184, 0x80, v176
	v_ashrrev_i32_e32 v185, 31, v184
	s_waitcnt lgkmcnt(0)
	v_lshlrev_b64 v[64:65], 11, v[184:185]
	v_lshl_add_u64 v[64:65], v[194:195], 0, v[64:65]
	global_load_dwordx4 v[208:211], v[64:65], off
	global_load_dwordx4 v[212:215], v[64:65], off offset:256
	v_add_u32_e32 v128, 0x90, v176
	v_add_u32_e32 v92, 0xa0, v176
	v_add_u32_e32 v88, 0xb0, v176
	v_ashrrev_i32_e32 v129, 31, v128
	v_ashrrev_i32_e32 v93, 31, v92
	v_ashrrev_i32_e32 v89, 31, v88
	v_lshlrev_b64 v[64:65], 11, v[128:129]
	v_lshlrev_b64 v[66:67], 11, v[92:93]
	v_lshlrev_b64 v[68:69], 11, v[88:89]
	v_lshl_add_u64 v[64:65], v[194:195], 0, v[64:65]
	v_lshl_add_u64 v[66:67], v[194:195], 0, v[66:67]
	v_lshl_add_u64 v[194:195], v[194:195], 0, v[68:69]
	global_load_dwordx4 v[84:87], v[64:65], off
	global_load_dwordx4 v[80:83], v[64:65], off offset:256
	global_load_dwordx4 v[76:79], v[66:67], off
	global_load_dwordx4 v[72:75], v[66:67], off offset:256
	global_load_dwordx4 v[68:71], v[194:195], off
	s_nop 0
	global_load_dwordx4 v[64:67], v[194:195], off offset:256
	s_waitcnt vmcnt(7)
	v_lshlrev_b32_e32 v194, 16, v208
	v_and_b32_e32 v195, 0xffff0000, v208
	v_lshlrev_b32_e32 v208, 16, v209
	v_and_b32_e32 v209, 0xffff0000, v209
	v_lshlrev_b32_e32 v216, 16, v210
	v_and_b32_e32 v217, 0xffff0000, v210
	v_lshlrev_b32_e32 v210, 16, v211
	v_and_b32_e32 v211, 0xffff0000, v211
	s_waitcnt vmcnt(6)
	v_lshlrev_b32_e32 v218, 16, v212
	v_and_b32_e32 v219, 0xffff0000, v212
	v_lshlrev_b32_e32 v212, 16, v213
	v_and_b32_e32 v213, 0xffff0000, v213
	v_lshlrev_b32_e32 v220, 16, v214
	v_and_b32_e32 v221, 0xffff0000, v214
	v_lshlrev_b32_e32 v214, 16, v215
	v_and_b32_e32 v215, 0xffff0000, v215
	v_pk_fma_f32 v[62:63], v[62:63], 0.5, v[208:209] op_sel_hi:[1,0,1]
	v_pk_fma_f32 v[60:61], v[60:61], 0.5, v[194:195] op_sel_hi:[1,0,1]
	v_pk_fma_f32 v[58:59], v[58:59], 0.5, v[210:211] op_sel_hi:[1,0,1]
	v_pk_fma_f32 v[56:57], v[56:57], 0.5, v[216:217] op_sel_hi:[1,0,1]
	v_pk_fma_f32 v[54:55], v[54:55], 0.5, v[212:213] op_sel_hi:[1,0,1]
	v_pk_fma_f32 v[52:53], v[52:53], 0.5, v[218:219] op_sel_hi:[1,0,1]
	v_pk_fma_f32 v[50:51], v[50:51], 0.5, v[214:215] op_sel_hi:[1,0,1]
	v_pk_fma_f32 v[48:49], v[48:49], 0.5, v[220:221] op_sel_hi:[1,0,1]
	v_mul_f32_e32 v194, v61, v61
	v_mul_f32_e32 v195, v63, v63
	v_mul_f32_e32 v207, v57, v57
	v_mul_f32_e32 v208, v59, v59
	v_mul_f32_e32 v209, v53, v53
	v_mul_f32_e32 v210, v55, v55
	v_mul_f32_e32 v211, v49, v49
	v_mul_f32_e32 v212, v51, v51
	v_fmac_f32_e32 v194, v60, v60
	v_fmac_f32_e32 v195, v62, v62
	v_fmac_f32_e32 v207, v56, v56
	v_fmac_f32_e32 v208, v58, v58
	v_fmac_f32_e32 v209, v52, v52
	v_fmac_f32_e32 v210, v54, v54
	v_fmac_f32_e32 v211, v48, v48
	v_fmac_f32_e32 v212, v50, v50
	v_add_f32_e32 v194, v194, v195
	v_add_f32_e32 v195, v207, v208
	v_add_f32_e32 v207, v209, v210
	v_add_f32_e32 v208, v211, v212
	v_add_f32_e32 v194, v194, v195
	v_add_f32_e32 v195, v207, v208
	v_add_f32_e32 v194, v194, v195
	v_mov_b32_e32 v236, v194
	v_mov_b32_e32 v237, v194
	s_nop 1
	v_permlane16_swap_b32_e32 v236, v237
	v_cndmask_b32_e64 v195, v237, v236, s[98:99]
	s_waitcnt lgkmcnt(0)
	v_add_f32_e32 v207, v194, v195
	v_mov_b32_e32 v236, v207
	v_mov_b32_e32 v237, v207
	s_nop 1
	v_permlane32_swap_b32_e32 v236, v237
	v_cndmask_b32_e64 v208, v237, v236, s[100:101]
	v_lshlrev_b64 v[194:195], 6, v[184:185]
	s_and_saveexec_b64 s[20:21], s[0:1]
	s_cbranch_execz .LBB0_1190
	s_waitcnt lgkmcnt(0)
	v_add_f32_e32 v207, v207, v208
	v_lshl_add_u64 v[208:209], s[2:3], 0, v[194:195]
	global_store_dword v[208:209], v207, off
.LBB0_1190:
	s_or_b64 exec, exec, s[20:21]
	s_waitcnt vmcnt(5) lgkmcnt(0)
	v_lshlrev_b32_e32 v208, 16, v84
	v_and_b32_e32 v209, 0xffff0000, v84
	v_lshlrev_b32_e32 v84, 16, v85
	v_and_b32_e32 v85, 0xffff0000, v85
	v_pk_fma_f32 v[46:47], v[46:47], 0.5, v[84:85] op_sel_hi:[1,0,1]
	v_pk_fma_f32 v[44:45], v[44:45], 0.5, v[208:209] op_sel_hi:[1,0,1]
	v_lshlrev_b32_e32 v84, 16, v86
	v_and_b32_e32 v85, 0xffff0000, v86
	v_lshlrev_b32_e32 v86, 16, v87
	v_and_b32_e32 v87, 0xffff0000, v87
	v_pk_fma_f32 v[40:41], v[40:41], 0.5, v[84:85] op_sel_hi:[1,0,1]
	v_mul_f32_e32 v84, v45, v45
	v_mul_f32_e32 v85, v47, v47
	v_pk_fma_f32 v[42:43], v[42:43], 0.5, v[86:87] op_sel_hi:[1,0,1]
	v_fmac_f32_e32 v84, v44, v44
	v_fmac_f32_e32 v85, v46, v46
	v_add_f32_e32 v84, v84, v85
	v_mul_f32_e32 v85, v41, v41
	v_mul_f32_e32 v86, v43, v43
	v_fmac_f32_e32 v85, v40, v40
	v_fmac_f32_e32 v86, v42, v42
	v_add_f32_e32 v85, v85, v86
	v_add_f32_e32 v86, v84, v85
	s_waitcnt vmcnt(4)
	v_lshlrev_b32_e32 v84, 16, v80
	v_and_b32_e32 v85, 0xffff0000, v80
	v_lshlrev_b32_e32 v80, 16, v81
	v_and_b32_e32 v81, 0xffff0000, v81
	v_pk_fma_f32 v[38:39], v[38:39], 0.5, v[80:81] op_sel_hi:[1,0,1]
	v_pk_fma_f32 v[36:37], v[36:37], 0.5, v[84:85] op_sel_hi:[1,0,1]
	v_lshlrev_b32_e32 v80, 16, v82
	v_and_b32_e32 v81, 0xffff0000, v82
	v_lshlrev_b32_e32 v82, 16, v83
	v_and_b32_e32 v83, 0xffff0000, v83
	v_pk_fma_f32 v[32:33], v[32:33], 0.5, v[80:81] op_sel_hi:[1,0,1]
	v_mul_f32_e32 v80, v37, v37
	v_mul_f32_e32 v81, v39, v39
	v_pk_fma_f32 v[34:35], v[34:35], 0.5, v[82:83] op_sel_hi:[1,0,1]
	v_fmac_f32_e32 v80, v36, v36
	v_fmac_f32_e32 v81, v38, v38
	v_add_f32_e32 v80, v80, v81
	v_mul_f32_e32 v81, v33, v33
	v_mul_f32_e32 v82, v35, v35
	v_fmac_f32_e32 v81, v32, v32
	v_fmac_f32_e32 v82, v34, v34
	v_add_f32_e32 v81, v81, v82
	v_add_f32_e32 v80, v80, v81
	v_add_f32_e32 v80, v86, v80
	v_mov_b32_e32 v236, v80
	v_mov_b32_e32 v237, v80
	s_nop 1
	v_permlane16_swap_b32_e32 v236, v237
	v_cndmask_b32_e64 v81, v237, v236, s[98:99]
	s_waitcnt lgkmcnt(0)
	v_add_f32_e32 v82, v80, v81
	v_mov_b32_e32 v236, v82
	v_mov_b32_e32 v237, v82
	s_nop 1
	v_permlane32_swap_b32_e32 v236, v237
	v_cndmask_b32_e64 v83, v237, v236, s[100:101]
	v_lshlrev_b64 v[80:81], 6, v[128:129]
	s_and_saveexec_b64 s[20:21], s[0:1]
	s_cbranch_execz .LBB0_1192
	s_waitcnt lgkmcnt(0)
	v_add_f32_e32 v84, v82, v83
	v_lshl_add_u64 v[82:83], s[2:3], 0, v[80:81]
	global_store_dword v[82:83], v84, off
; __device__ __forceinline__ float bf_lo(unsigned w) { return __uint_as_float(w << 16); }
; __device__ __forceinline__ float bf_hi(unsigned w) { return __uint_as_float(w & 0xffff0000u); }
;     __device__ __forceinline__ void operator()(const f32x4 (&acc)[2][2][4][2], const Unit& u, int wr, int wc, int fr, int fq) const {
;     ...
;             for (int m = 0; m < 4; ++m) { float s = 0.f;
; #pragma unroll
;                 for (int bj = 0; bj < 2; ++bj) { const u32x4 w = bb[m][bj];
;                     const f32x4 o0 = (f32x4){bf_lo(w.x), bf_hi(w.x), bf_lo(w.y), bf_hi(w.y)} + acc[ai][bj][m][0] * alpha, o1 = (f32x4){bf_lo(w.z), bf_hi(w.z), bf_lo(w.w), bf_hi(w.w)} + acc[ai][bj][m][1] * alpha;
;                     o[ai][m][bj][0] = o0; o[ai][m][bj][1] = o1;
;                     s += ((o0[0] * o0[0] + o0[1] * o0[1]) + (o0[2] * o0[2] + o0[3] * o0[3])) + ((o1[0] * o1[0] + o1[1] * o1[1]) + (o1[2] * o1[2] + o1[3] * o1[3])); }
;                 s += __shfl_xor(s, 16); s += __shfl_xor(s, 32);
;                 if (fq == 0) ssp[(size_t)(row0 + ai * HALF + m * 16) * 16 + u.pn * 4 + wc] = s; }
.LBB0_1192:
	s_or_b64 exec, exec, s[20:21]
	s_waitcnt vmcnt(3)
	v_lshlrev_b32_e32 v82, 16, v76
	s_waitcnt lgkmcnt(0)
	v_and_b32_e32 v83, 0xffff0000, v76
	v_lshlrev_b32_e32 v76, 16, v77
	v_and_b32_e32 v77, 0xffff0000, v77
	v_pk_fma_f32 v[30:31], v[30:31], 0.5, v[76:77] op_sel_hi:[1,0,1]
	v_pk_fma_f32 v[28:29], v[28:29], 0.5, v[82:83] op_sel_hi:[1,0,1]
	v_lshlrev_b32_e32 v76, 16, v78
	v_and_b32_e32 v77, 0xffff0000, v78
	v_lshlrev_b32_e32 v78, 16, v79
	v_and_b32_e32 v79, 0xffff0000, v79
	v_pk_fma_f32 v[24:25], v[24:25], 0.5, v[76:77] op_sel_hi:[1,0,1]
	v_mul_f32_e32 v76, v29, v29
	v_mul_f32_e32 v77, v31, v31
	v_pk_fma_f32 v[26:27], v[26:27], 0.5, v[78:79] op_sel_hi:[1,0,1]
	v_fmac_f32_e32 v76, v28, v28
	v_fmac_f32_e32 v77, v30, v30
	v_add_f32_e32 v76, v76, v77
	v_mul_f32_e32 v77, v25, v25
	v_mul_f32_e32 v78, v27, v27
	v_fmac_f32_e32 v77, v24, v24
	v_fmac_f32_e32 v78, v26, v26
	v_add_f32_e32 v77, v77, v78
	v_add_f32_e32 v78, v76, v77
	s_waitcnt vmcnt(2)
	v_lshlrev_b32_e32 v76, 16, v72
	v_and_b32_e32 v77, 0xffff0000, v72
	v_lshlrev_b32_e32 v72, 16, v73
	v_and_b32_e32 v73, 0xffff0000, v73
	v_pk_fma_f32 v[22:23], v[22:23], 0.5, v[72:73] op_sel_hi:[1,0,1]
	v_pk_fma_f32 v[20:21], v[20:21], 0.5, v[76:77] op_sel_hi:[1,0,1]
	v_lshlrev_b32_e32 v72, 16, v74
	v_and_b32_e32 v73, 0xffff0000, v74
	v_lshlrev_b32_e32 v74, 16, v75
	v_and_b32_e32 v75, 0xffff0000, v75
	v_pk_fma_f32 v[16:17], v[16:17], 0.5, v[72:73] op_sel_hi:[1,0,1]
	v_mul_f32_e32 v72, v21, v21
	v_mul_f32_e32 v73, v23, v23
	v_pk_fma_f32 v[18:19], v[18:19], 0.5, v[74:75] op_sel_hi:[1,0,1]
	v_fmac_f32_e32 v72, v20, v20
	v_fmac_f32_e32 v73, v22, v22
	v_add_f32_e32 v72, v72, v73
	v_mul_f32_e32 v73, v17, v17
	v_mul_f32_e32 v74, v19, v19
	v_fmac_f32_e32 v73, v16, v16
	v_fmac_f32_e32 v74, v18, v18
	v_add_f32_e32 v73, v73, v74
	v_add_f32_e32 v72, v72, v73
	v_add_f32_e32 v72, v78, v72
	v_mov_b32_e32 v236, v72
	v_mov_b32_e32 v237, v72
	s_nop 1
	v_permlane16_swap_b32_e32 v236, v237
	v_cndmask_b32_e64 v73, v237, v236, s[98:99]
	v_lshlrev_b64 v[82:83], 6, v[92:93]
	s_waitcnt lgkmcnt(0)
	v_add_f32_e32 v72, v72, v73
	v_mov_b32_e32 v236, v72
	v_mov_b32_e32 v237, v72
	s_nop 1
	v_permlane32_swap_b32_e32 v236, v237
	v_cndmask_b32_e64 v73, v237, v236, s[100:101]
	s_and_saveexec_b64 s[20:21], s[0:1]
	s_cbranch_execz .LBB0_1194
	s_waitcnt lgkmcnt(0)
	v_add_f32_e32 v74, v72, v73
	v_lshl_add_u64 v[72:73], s[2:3], 0, v[82:83]
	global_store_dword v[72:73], v74, off
.LBB0_1194:
	s_or_b64 exec, exec, s[20:21]
	s_waitcnt vmcnt(1)
	v_lshlrev_b32_e32 v74, 16, v68
	v_and_b32_e32 v75, 0xffff0000, v68
	v_lshlrev_b32_e32 v68, 16, v69
	v_and_b32_e32 v69, 0xffff0000, v69
	s_waitcnt lgkmcnt(0)
	v_pk_fma_f32 v[72:73], v[14:15], 0.5, v[68:69] op_sel_hi:[1,0,1]
	v_pk_fma_f32 v[74:75], v[12:13], 0.5, v[74:75] op_sel_hi:[1,0,1]
	v_lshlrev_b32_e32 v12, 16, v70
	v_and_b32_e32 v13, 0xffff0000, v70
	v_lshlrev_b32_e32 v14, 16, v71
	v_and_b32_e32 v15, 0xffff0000, v71
	v_pk_fma_f32 v[70:71], v[8:9], 0.5, v[12:13] op_sel_hi:[1,0,1]
	v_mul_f32_e32 v8, v75, v75
	v_mul_f32_e32 v9, v73, v73
	v_pk_fma_f32 v[68:69], v[10:11], 0.5, v[14:15] op_sel_hi:[1,0,1]
	v_fmac_f32_e32 v8, v74, v74
	v_fmac_f32_e32 v9, v72, v72
	v_add_f32_e32 v8, v8, v9
	v_mul_f32_e32 v9, v71, v71
	v_mul_f32_e32 v10, v69, v69
	v_fmac_f32_e32 v9, v70, v70
	v_fmac_f32_e32 v10, v68, v68
	v_add_f32_e32 v9, v9, v10
	v_add_f32_e32 v12, v8, v9
	s_waitcnt vmcnt(0)
	v_lshlrev_b32_e32 v8, 16, v64
	v_and_b32_e32 v9, 0xffff0000, v64
	v_lshlrev_b32_e32 v10, 16, v65
	v_and_b32_e32 v11, 0xffff0000, v65
	v_pk_fma_f32 v[64:65], v[6:7], 0.5, v[10:11] op_sel_hi:[1,0,1]
	v_pk_fma_f32 v[76:77], v[4:5], 0.5, v[8:9] op_sel_hi:[1,0,1]
	v_lshlrev_b32_e32 v4, 16, v66
	v_and_b32_e32 v5, 0xffff0000, v66
	v_lshlrev_b32_e32 v6, 16, v67
	v_and_b32_e32 v7, 0xffff0000, v67
	v_pk_fma_f32 v[78:79], v[0:1], 0.5, v[4:5] op_sel_hi:[1,0,1]
	v_mul_f32_e32 v0, v77, v77
	v_mul_f32_e32 v1, v65, v65
	v_pk_fma_f32 v[66:67], v[2:3], 0.5, v[6:7] op_sel_hi:[1,0,1]
	v_fmac_f32_e32 v0, v76, v76
	v_fmac_f32_e32 v1, v64, v64
	v_add_f32_e32 v0, v0, v1
	v_mul_f32_e32 v1, v79, v79
	v_mul_f32_e32 v2, v67, v67
	v_fmac_f32_e32 v1, v78, v78
	v_fmac_f32_e32 v2, v66, v66
	v_add_f32_e32 v1, v1, v2
	v_add_f32_e32 v0, v0, v1
	v_add_f32_e32 v0, v12, v0
	v_mov_b32_e32 v236, v0
	v_mov_b32_e32 v237, v0
	s_nop 1
	v_permlane16_swap_b32_e32 v236, v237
	v_cndmask_b32_e64 v1, v237, v236, s[98:99]
	v_lshlrev_b64 v[84:85], 6, v[88:89]
	s_waitcnt lgkmcnt(0)
	v_add_f32_e32 v0, v0, v1
	v_mov_b32_e32 v236, v0
	v_mov_b32_e32 v237, v0
	s_nop 1
	v_permlane32_swap_b32_e32 v236, v237
	v_cndmask_b32_e64 v1, v237, v236, s[100:101]
	s_and_saveexec_b64 s[20:21], s[0:1]
	s_cbranch_execz .LBB0_1196
	s_waitcnt lgkmcnt(0)
	v_add_f32_e32 v2, v0, v1
	v_lshl_add_u64 v[0:1], s[2:3], 0, v[84:85]
	global_store_dword v[0:1], v2, off

;     __device__ __forceinline__ void operator()(const f32x4 (&acc)[2][2][4][2], const Unit& u, int wr, int wc, int fr, int fq) const {
;     ...
;         __builtin_amdgcn_s_barrier(); asm volatile("" ::: "memory");
;         float rs[2][4];
;         { f32x4 p[2][4];
; #pragma unroll
;           for (int ai = 0; ai < 2; ++ai)
; #pragma unroll
;             for (int m = 0; m < 4; ++m) p[ai][m] = *(const volatile f32x4*)(ssp + (size_t)(row0 + ai * HALF + m * 16) * 16 + 4 * fq);
; #pragma unroll
;           for (int ai = 0; ai < 2; ++ai)
; #pragma unroll
;             for (int m = 0; m < 4; ++m) { float s = (p[ai][m][0] + p[ai][m][1]) + (p[ai][m][2] + p[ai][m][3]); s += __shfl_xor(s, 16); s += __shfl_xor(s, 32); rs[ai][m] = __builtin_amdgcn_rsqf(s * (1.0f / D_MODEL) + RMS_EPS); } }
.LBB0_1210:
	s_barrier
	v_lshl_add_u64 v[86:87], v[160:161], 0, v[186:187]
	flat_load_dwordx4 v[208:211], v[86:87] sc0 sc1
	v_lshl_add_u64 v[86:87], v[160:161], 0, v[188:189]
	flat_load_dwordx4 v[186:189], v[86:87] sc0 sc1
	v_lshl_add_u64 v[86:87], v[160:161], 0, v[190:191]
	flat_load_dwordx4 v[212:215], v[86:87] sc0 sc1
	v_lshl_add_u64 v[86:87], v[160:161], 0, v[192:193]
	flat_load_dwordx4 v[190:193], v[86:87] sc0 sc1
	v_lshl_add_u64 v[86:87], v[160:161], 0, v[194:195]
	v_lshl_add_u64 v[80:81], v[160:161], 0, v[80:81]
	flat_load_dwordx4 v[216:219], v[86:87] sc0 sc1
	flat_load_dwordx4 v[220:223], v[80:81] sc0 sc1
	v_lshl_add_u64 v[80:81], v[160:161], 0, v[82:83]
	v_lshl_add_u64 v[84:85], v[160:161], 0, v[84:85]
	flat_load_dwordx4 v[80:83], v[80:81] sc0 sc1
	s_and_b64 vcc, exec, s[4:5]
	flat_load_dwordx4 v[84:87], v[84:85] sc0 sc1
	s_waitcnt vmcnt(0)
	s_mov_b64 s[2:3], -1
	s_waitcnt lgkmcnt(0)
	v_mov_b32_e32 v194, v209
	v_mov_b32_e32 v195, v210
	v_mov_b32_e32 v209, v211
	v_mov_b32_e32 v210, v187
	v_mov_b32_e32 v211, v188
	v_mov_b32_e32 v187, v189
	v_mov_b32_e32 v188, v213
	v_mov_b32_e32 v189, v214
	v_mov_b32_e32 v213, v215
	v_mov_b32_e32 v214, v191
	v_mov_b32_e32 v215, v192
	v_mov_b32_e32 v191, v193
	v_mov_b32_e32 v192, v217
	v_mov_b32_e32 v193, v218
	v_mov_b32_e32 v217, v219
	v_mov_b32_e32 v218, v221
	v_mov_b32_e32 v219, v222
	v_mov_b32_e32 v221, v223
	v_mov_b32_e32 v222, v81
	v_mov_b32_e32 v223, v82
	v_mov_b32_e32 v81, v83
	v_mov_b32_e32 v82, v85
	v_mov_b32_e32 v83, v86
	v_mov_b32_e32 v85, v87
	v_pk_add_f32 v[86:87], v[194:195], v[208:209]
	v_pk_add_f32 v[186:187], v[210:211], v[186:187]
	v_pk_add_f32 v[188:189], v[188:189], v[212:213]
	v_pk_add_f32 v[192:193], v[192:193], v[216:217]
	v_pk_add_f32 v[80:81], v[222:223], v[80:81]
	v_pk_add_f32 v[82:83], v[82:83], v[84:85]
	v_add_f32_e32 v84, v86, v87
	v_pk_add_f32 v[190:191], v[214:215], v[190:191]
	v_add_f32_e32 v85, v186, v187
	v_add_f32_e32 v86, v188, v189
	v_add_f32_e32 v186, v192, v193
	v_add_f32_e32 v80, v80, v81
	v_add_f32_e32 v81, v82, v83
	v_mov_b32_e32 v236, v84
	v_mov_b32_e32 v237, v84
	s_nop 1
	v_permlane16_swap_b32_e32 v236, v237
	v_cndmask_b32_e64 v82, v237, v236, s[98:99]
	v_add_f32_e32 v87, v190, v191
	v_mov_b32_e32 v236, v86
	v_mov_b32_e32 v237, v86
	s_nop 1
	v_permlane16_swap_b32_e32 v236, v237
	v_cndmask_b32_e64 v188, v237, v236, s[98:99]
	v_mov_b32_e32 v236, v186
	v_mov_b32_e32 v237, v186
	s_nop 1
	v_permlane16_swap_b32_e32 v236, v237
	v_cndmask_b32_e64 v190, v237, v236, s[98:99]
	v_pk_add_f32 v[194:195], v[218:219], v[220:221]
	v_mov_b32_e32 v236, v85
	v_mov_b32_e32 v237, v85
	s_nop 1
	v_permlane16_swap_b32_e32 v236, v237
	v_cndmask_b32_e64 v83, v237, v236, s[98:99]
	v_add_f32_e32 v187, v194, v195
	v_mov_b32_e32 v236, v80
	v_mov_b32_e32 v237, v80
	s_nop 1
	v_permlane16_swap_b32_e32 v236, v237
	v_cndmask_b32_e64 v192, v237, v236, s[98:99]
	s_waitcnt lgkmcnt(4)
	v_add_f32_e32 v82, v84, v82
	v_mov_b32_e32 v236, v87
	v_mov_b32_e32 v237, v87
	s_nop 1
	v_permlane16_swap_b32_e32 v236, v237
	v_cndmask_b32_e64 v189, v237, v236, s[98:99]
	v_mov_b32_e32 v236, v187
	v_mov_b32_e32 v237, v187
	s_nop 1
	v_permlane16_swap_b32_e32 v236, v237
	v_cndmask_b32_e64 v191, v237, v236, s[98:99]
	v_mov_b32_e32 v236, v81
	v_mov_b32_e32 v237, v81
	s_nop 1
	v_permlane16_swap_b32_e32 v236, v237
	v_cndmask_b32_e64 v193, v237, v236, s[98:99]
	s_waitcnt lgkmcnt(6)
	v_add_f32_e32 v84, v86, v188
	s_waitcnt lgkmcnt(5)
	v_add_f32_e32 v86, v186, v190
	v_mov_b32_e32 v236, v82
	v_mov_b32_e32 v237, v82
	s_nop 1
	v_permlane32_swap_b32_e32 v236, v237
	v_cndmask_b32_e64 v186, v237, v236, s[100:101]
	s_waitcnt lgkmcnt(5)
	v_add_f32_e32 v83, v85, v83
	s_waitcnt lgkmcnt(4)
	v_add_f32_e32 v80, v80, v192
	s_waitcnt lgkmcnt(3)
	v_add_f32_e32 v85, v87, v189
	s_waitcnt lgkmcnt(2)
	v_add_f32_e32 v87, v187, v191
	s_waitcnt lgkmcnt(1)
	v_add_f32_e32 v81, v81, v193
	v_mov_b32_e32 v236, v83
	v_mov_b32_e32 v237, v83
	s_nop 1
	v_permlane32_swap_b32_e32 v236, v237
	v_cndmask_b32_e64 v187, v237, v236, s[100:101]
	v_mov_b32_e32 v236, v84
	v_mov_b32_e32 v237, v84
	s_nop 1
	v_permlane32_swap_b32_e32 v236, v237
	v_cndmask_b32_e64 v188, v237, v236, s[100:101]
	v_mov_b32_e32 v236, v80
	v_mov_b32_e32 v237, v80
	s_nop 1
	v_permlane32_swap_b32_e32 v236, v237
	v_cndmask_b32_e64 v193, v237, v236, s[100:101]
	s_waitcnt lgkmcnt(3)
	v_add_f32_e32 v82, v82, v186
	v_fmamk_f32 v82, v82, 0x3a800000, v204
	v_mov_b32_e32 v236, v86
	v_mov_b32_e32 v237, v86
	s_nop 1
	v_permlane32_swap_b32_e32 v236, v237
	v_cndmask_b32_e64 v190, v237, v236, s[100:101]
	v_rsq_f32_e32 v186, v82
	v_mov_b32_e32 v236, v81
	v_mov_b32_e32 v237, v81
	s_nop 1
	v_permlane32_swap_b32_e32 v236, v237
	v_cndmask_b32_e64 v82, v237, v236, s[100:101]
	s_waitcnt lgkmcnt(4)
	v_add_f32_e32 v83, v83, v187
	s_waitcnt lgkmcnt(3)
	v_add_f32_e32 v84, v84, v188
	s_waitcnt lgkmcnt(2)
	v_add_f32_e32 v80, v80, v193
	v_fmamk_f32 v83, v83, 0x3a800000, v204
	v_fmamk_f32 v84, v84, 0x3a800000, v204
	v_fmamk_f32 v80, v80, 0x3a800000, v204
	v_mov_b32_e32 v236, v85
	v_mov_b32_e32 v237, v85
	s_nop 1
	v_permlane32_swap_b32_e32 v236, v237
	v_cndmask_b32_e64 v189, v237, v236, s[100:101]
	s_waitcnt lgkmcnt(2)
	v_add_f32_e32 v86, v86, v190
	v_rsq_f32_e32 v188, v83
	v_rsq_f32_e32 v190, v84
	v_rsq_f32_e32 v84, v80
	s_waitcnt lgkmcnt(1)
;     __device__ __forceinline__ void operator()(const f32x4 (&acc)[2][2][4][2], const Unit& u, int wr, int wc, int fr, int fq) const {
;     ...
;             for (int m = 0; m < 4; ++m) { float s = (p[ai][m][0] + p[ai][m][1]) + (p[ai][m][2] + p[ai][m][3]); s += __shfl_xor(s, 16); s += __shfl_xor(s, 32); rs[ai][m] = __builtin_amdgcn_rsqf(s * (1.0f / D_MODEL) + RMS_EPS); } }
; #pragma unroll
;         for (int ai = 0; ai < 2; ++ai)
; #pragma unroll
;             for (int m = 0; m < 4; ++m) { const size_t off = (size_t)(row0 + ai * HALF + m * 16) * D_MODEL + col0; const float r = rs[ai][m];
; #pragma unroll
;                 for (int bj = 0; bj < 2; ++bj) { *(f32x4*)(out + off + bj * HALF) = o[ai][m][bj][0] * r * gv[bj][0]; *(f32x4*)(out + off + bj * HALF + 4) = o[ai][m][bj][1] * r * gv[bj][1]; } }
	v_add_f32_e32 v80, v81, v82
	v_pk_mul_f32 v[82:83], v[124:125], v[186:187] op_sel_hi:[1,0]
	v_pk_mul_f32 v[124:125], v[126:127], v[186:187] op_sel_hi:[1,0]
	v_mov_b32_e32 v236, v87
	v_mov_b32_e32 v237, v87
	s_nop 1
	v_permlane32_swap_b32_e32 v236, v237
	v_cndmask_b32_e64 v191, v237, v236, s[100:101]
	v_pk_mul_f32 v[126:127], v[14:15], v[124:125]
	v_pk_mul_f32 v[124:125], v[12:13], v[82:83]
	v_lshlrev_b64 v[82:83], 12, v[176:177]
	v_lshl_add_u64 v[176:177], s[70:71], 0, v[82:83]
	v_lshlrev_b64 v[82:83], 2, v[174:175]
	v_pk_mul_f32 v[112:113], v[112:113], v[186:187] op_sel_hi:[1,0]
	v_pk_mul_f32 v[114:115], v[114:115], v[186:187] op_sel_hi:[1,0]
	v_lshl_add_u64 v[174:175], v[176:177], 0, v[82:83]
	v_pk_mul_f32 v[114:115], v[2:3], v[114:115]
	v_pk_mul_f32 v[112:113], v[0:1], v[112:113]
	global_store_dwordx4 v[174:175], v[112:115], off offset:528
	s_waitcnt lgkmcnt(1)
	v_pk_mul_f32 v[96:97], v[96:97], v[188:189] op_sel_hi:[1,0]
	v_pk_mul_f32 v[98:99], v[98:99], v[188:189] op_sel_hi:[1,0]
	v_lshlrev_b64 v[112:113], 12, v[172:173]
	v_lshl_add_u64 v[112:113], s[70:71], 0, v[112:113]
	v_lshl_add_u64 v[112:113], v[112:113], 0, v[82:83]
	v_pk_mul_f32 v[98:99], v[2:3], v[98:99]
	v_pk_mul_f32 v[96:97], v[0:1], v[96:97]
	global_store_dwordx4 v[112:113], v[96:99], off offset:528
	s_waitcnt lgkmcnt(0)
	v_pk_mul_f32 v[94:95], v[94:95], v[190:191] op_sel_hi:[1,0]
	v_add_f32_e32 v85, v85, v189
	v_pk_mul_f32 v[98:99], v[144:145], v[190:191] op_sel_hi:[1,0]
	v_pk_mul_f32 v[96:97], v[14:15], v[94:95]
	v_pk_mul_f32 v[94:95], v[12:13], v[98:99]
	v_lshlrev_b64 v[98:99], 12, v[170:171]
	v_lshl_add_u64 v[98:99], s[70:71], 0, v[98:99]
	v_lshl_add_u64 v[98:99], v[98:99], 0, v[82:83]
	global_store_dwordx4 v[98:99], v[94:97], off
	v_pk_mul_f32 v[90:91], v[90:91], v[190:191] op_sel_hi:[1,0]
	v_fmamk_f32 v85, v85, 0x3a800000, v204
	v_pk_mul_f32 v[94:95], v[140:141], v[190:191] op_sel_hi:[1,0]
	v_pk_mul_f32 v[96:97], v[10:11], v[90:91]
	v_pk_mul_f32 v[94:95], v[8:9], v[94:95]
	v_rsq_f32_e32 v192, v85
	global_store_dwordx4 v[98:99], v[94:97], off offset:16
	v_pk_mul_f32 v[90:91], v[142:143], v[190:191] op_sel_hi:[1,0]
	v_fmamk_f32 v86, v86, 0x3a800000, v204
	v_pk_mul_f32 v[94:95], v[136:137], v[190:191] op_sel_hi:[1,0]
	v_rsq_f32_e32 v194, v86
	v_pk_mul_f32 v[96:97], v[6:7], v[94:95]
	v_pk_mul_f32 v[94:95], v[4:5], v[90:91]
	global_store_dwordx4 v[98:99], v[94:97], off offset:512
	v_pk_mul_f32 v[90:91], v[146:147], v[190:191] op_sel_hi:[1,0]
	v_add_f32_e32 v87, v87, v191
	v_pk_mul_f32 v[94:95], v[138:139], v[190:191] op_sel_hi:[1,0]
	v_fmamk_f32 v87, v87, 0x3a800000, v204
	v_pk_mul_f32 v[96:97], v[2:3], v[94:95]
	v_pk_mul_f32 v[94:95], v[0:1], v[90:91]
	global_store_dwordx4 v[98:99], v[94:97], off offset:528
	v_pk_mul_f32 v[90:91], v[150:151], v[192:193] op_sel_hi:[1,0]
	v_rsq_f32_e32 v86, v87
	v_pk_mul_f32 v[94:95], v[148:149], v[192:193] op_sel_hi:[1,0]
	v_pk_mul_f32 v[48:49], v[48:49], v[194:195] op_sel_hi:[1,0]
	v_pk_mul_f32 v[96:97], v[14:15], v[94:95]
	v_pk_mul_f32 v[94:95], v[12:13], v[90:91]
	v_lshlrev_b64 v[90:91], 12, v[168:169]
	v_lshl_add_u64 v[90:91], s[70:71], 0, v[90:91]
	v_lshl_add_u64 v[90:91], v[90:91], 0, v[82:83]
	global_store_dwordx4 v[90:91], v[94:97], off
	v_pk_mul_f32 v[50:51], v[50:51], v[194:195] op_sel_hi:[1,0]
	v_pk_mul_f32 v[48:49], v[0:1], v[48:49]
	v_pk_mul_f32 v[94:95], v[134:135], v[192:193] op_sel_hi:[1,0]
	v_pk_mul_f32 v[96:97], v[132:133], v[192:193] op_sel_hi:[1,0]
	v_pk_mul_f32 v[94:95], v[8:9], v[94:95]
	v_pk_mul_f32 v[96:97], v[10:11], v[96:97]
	global_store_dwordx4 v[90:91], v[94:97], off offset:16
	v_pk_mul_f32 v[50:51], v[2:3], v[50:51]
	v_fmamk_f32 v80, v80, 0x3a800000, v204
	v_pk_mul_f32 v[94:95], v[180:181], v[192:193] op_sel_hi:[1,0]
	v_pk_mul_f32 v[96:97], v[178:179], v[192:193] op_sel_hi:[1,0]
	v_pk_mul_f32 v[94:95], v[4:5], v[94:95]
	v_pk_mul_f32 v[96:97], v[6:7], v[96:97]
	global_store_dwordx4 v[90:91], v[94:97], off offset:512
	v_pk_mul_f32 v[32:33], v[32:33], v[86:87] op_sel_hi:[1,0]
	v_pk_mul_f32 v[34:35], v[34:35], v[86:87] op_sel_hi:[1,0]
	v_pk_mul_f32 v[94:95], v[182:183], v[192:193] op_sel_hi:[1,0]
	v_pk_mul_f32 v[96:97], v[130:131], v[192:193] op_sel_hi:[1,0]
	v_pk_mul_f32 v[94:95], v[0:1], v[94:95]
	v_pk_mul_f32 v[96:97], v[2:3], v[96:97]
	global_store_dwordx4 v[90:91], v[94:97], off offset:528
	v_lshlrev_b64 v[90:91], 12, v[184:185]
	v_lshl_add_u64 v[90:91], s[70:71], 0, v[90:91]
	v_lshl_add_u64 v[90:91], v[90:91], 0, v[82:83]
	global_store_dwordx4 v[90:91], v[48:51], off offset:528
	v_rsq_f32_e32 v80, v80
	v_pk_mul_f32 v[34:35], v[2:3], v[34:35]
	v_lshlrev_b64 v[48:49], 12, v[128:129]
	v_lshl_add_u64 v[48:49], s[70:71], 0, v[48:49]
	v_lshl_add_u64 v[48:49], v[48:49], 0, v[82:83]
	v_pk_mul_f32 v[32:33], v[0:1], v[32:33]
	global_store_dwordx4 v[48:49], v[32:35], off offset:528
	v_pk_mul_f32 v[16:17], v[16:17], v[84:85] op_sel_hi:[1,0]
	v_pk_mul_f32 v[18:19], v[18:19], v[84:85] op_sel_hi:[1,0]
	v_lshlrev_b64 v[32:33], 12, v[92:93]
	v_lshl_add_u64 v[32:33], s[70:71], 0, v[32:33]
	v_lshl_add_u64 v[32:33], v[32:33], 0, v[82:83]
	v_pk_mul_f32 v[18:19], v[2:3], v[18:19]
; #define PG8_BAR __builtin_amdgcn_s_barrier()
;     __device__ __forceinline__ void operator()(const f32x4 (&acc)[2][2][4][2], const Unit& u, int wr, int wc, int fr, int fq) const {
;     ...
;         for (int ai = 0; ai < 2; ++ai)
; #pragma unroll
;             for (int m = 0; m < 4; ++m) { const size_t off = (size_t)(row0 + ai * HALF + m * 16) * D_MODEL + col0; const float r = rs[ai][m];
; #pragma unroll
;                 for (int bj = 0; bj < 2; ++bj) { *(f32x4*)(out + off + bj * HALF) = o[ai][m][bj][0] * r * gv[bj][0]; *(f32x4*)(out + off + bj * HALF + 4) = o[ai][m][bj][1] * r * gv[bj][1]; } }
; template <class Epi>
; __device__ __forceinline__ void gemm_phase(LAS unsigned char* lds, const Gemm g, const StaticOrder& S, const Epi& E) {
;     ...
;         if (!has_next) break;
; #pragma unroll
;         for (int a = 0; a < 2; ++a)
; #pragma unroll
;             for (int b = 0; b < 2; ++b)
; #pragma unroll
;                 for (int m = 0; m < 4; ++m)
; #pragma unroll
;                     for (int n = 0; n < 2; ++n) acc[a][b][m][n] = (f32x4){0.f, 0.f, 0.f, 0.f};
;         cur = nxt; cA = nA; cB = nB; ++ui;
;         if (wr == 1) PG8_BAR;
	v_pk_mul_f32 v[16:17], v[0:1], v[16:17]
	v_pk_mul_f32 v[108:109], v[108:109], v[188:189] op_sel_hi:[1,0]
	v_pk_mul_f32 v[60:61], v[60:61], v[194:195] op_sel_hi:[1,0]
	v_pk_mul_f32 v[44:45], v[44:45], v[86:87] op_sel_hi:[1,0]
	v_pk_mul_f32 v[28:29], v[28:29], v[84:85] op_sel_hi:[1,0]
	global_store_dwordx4 v[32:33], v[16:19], off offset:528
	v_pk_mul_f32 v[108:109], v[12:13], v[108:109]
	v_pk_mul_f32 v[60:61], v[12:13], v[60:61]
	v_pk_mul_f32 v[16:17], v[74:75], v[80:81] op_sel_hi:[1,0]
	v_pk_mul_f32 v[44:45], v[12:13], v[44:45]
	v_pk_mul_f32 v[28:29], v[12:13], v[28:29]
	v_pk_mul_f32 v[12:13], v[12:13], v[16:17]
	v_lshlrev_b64 v[16:17], 12, v[88:89]
	v_pk_mul_f32 v[110:111], v[110:111], v[188:189] op_sel_hi:[1,0]
	v_pk_mul_f32 v[62:63], v[62:63], v[194:195] op_sel_hi:[1,0]
	v_pk_mul_f32 v[46:47], v[46:47], v[86:87] op_sel_hi:[1,0]
	v_pk_mul_f32 v[30:31], v[30:31], v[84:85] op_sel_hi:[1,0]
	v_pk_mul_f32 v[18:19], v[72:73], v[80:81] op_sel_hi:[1,0]
	v_lshl_add_u64 v[16:17], s[70:71], 0, v[16:17]
	v_pk_mul_f32 v[110:111], v[14:15], v[110:111]
	v_pk_mul_f32 v[62:63], v[14:15], v[62:63]
	v_pk_mul_f32 v[46:47], v[14:15], v[46:47]
	v_pk_mul_f32 v[30:31], v[14:15], v[30:31]
	v_pk_mul_f32 v[14:15], v[14:15], v[18:19]
	v_lshl_add_u64 v[16:17], v[16:17], 0, v[82:83]
	global_store_dwordx4 v[174:175], v[124:127], off
	v_pk_mul_f32 v[120:121], v[120:121], v[186:187] op_sel_hi:[1,0]
	v_pk_mul_f32 v[122:123], v[122:123], v[186:187] op_sel_hi:[1,0]
	global_store_dwordx4 v[112:113], v[108:111], off
	v_pk_mul_f32 v[104:105], v[104:105], v[188:189] op_sel_hi:[1,0]
	v_pk_mul_f32 v[106:107], v[106:107], v[188:189] op_sel_hi:[1,0]
	global_store_dwordx4 v[90:91], v[60:63], off
	v_pk_mul_f32 v[56:57], v[56:57], v[194:195] op_sel_hi:[1,0]
	v_pk_mul_f32 v[58:59], v[58:59], v[194:195] op_sel_hi:[1,0]
	global_store_dwordx4 v[48:49], v[44:47], off
	v_pk_mul_f32 v[40:41], v[40:41], v[86:87] op_sel_hi:[1,0]
	v_pk_mul_f32 v[42:43], v[42:43], v[86:87] op_sel_hi:[1,0]
	global_store_dwordx4 v[32:33], v[28:31], off
	v_pk_mul_f32 v[24:25], v[24:25], v[84:85] op_sel_hi:[1,0]
	v_pk_mul_f32 v[26:27], v[26:27], v[84:85] op_sel_hi:[1,0]
	global_store_dwordx4 v[16:17], v[12:15], off
	v_pk_mul_f32 v[122:123], v[10:11], v[122:123]
	v_pk_mul_f32 v[120:121], v[8:9], v[120:121]
	v_pk_mul_f32 v[12:13], v[70:71], v[80:81] op_sel_hi:[1,0]
	v_pk_mul_f32 v[14:15], v[68:69], v[80:81] op_sel_hi:[1,0]
	v_pk_mul_f32 v[106:107], v[10:11], v[106:107]
	v_pk_mul_f32 v[104:105], v[8:9], v[104:105]
	v_pk_mul_f32 v[58:59], v[10:11], v[58:59]
	v_pk_mul_f32 v[56:57], v[8:9], v[56:57]
	v_pk_mul_f32 v[42:43], v[10:11], v[42:43]
	v_pk_mul_f32 v[40:41], v[8:9], v[40:41]
	v_pk_mul_f32 v[26:27], v[10:11], v[26:27]
	v_pk_mul_f32 v[24:25], v[8:9], v[24:25]
	v_pk_mul_f32 v[10:11], v[10:11], v[14:15]
	v_pk_mul_f32 v[8:9], v[8:9], v[12:13]
	global_store_dwordx4 v[174:175], v[120:123], off offset:16
	v_pk_mul_f32 v[116:117], v[116:117], v[186:187] op_sel_hi:[1,0]
	v_pk_mul_f32 v[118:119], v[118:119], v[186:187] op_sel_hi:[1,0]
	global_store_dwordx4 v[112:113], v[104:107], off offset:16
	v_pk_mul_f32 v[100:101], v[100:101], v[188:189] op_sel_hi:[1,0]
	v_pk_mul_f32 v[102:103], v[102:103], v[188:189] op_sel_hi:[1,0]
	global_store_dwordx4 v[90:91], v[56:59], off offset:16
	v_pk_mul_f32 v[52:53], v[52:53], v[194:195] op_sel_hi:[1,0]
	v_pk_mul_f32 v[54:55], v[54:55], v[194:195] op_sel_hi:[1,0]
	global_store_dwordx4 v[48:49], v[40:43], off offset:16
	v_pk_mul_f32 v[36:37], v[36:37], v[86:87] op_sel_hi:[1,0]
	v_pk_mul_f32 v[38:39], v[38:39], v[86:87] op_sel_hi:[1,0]
	global_store_dwordx4 v[32:33], v[24:27], off offset:16
	v_pk_mul_f32 v[20:21], v[20:21], v[84:85] op_sel_hi:[1,0]
	v_pk_mul_f32 v[22:23], v[22:23], v[84:85] op_sel_hi:[1,0]
	global_store_dwordx4 v[16:17], v[8:11], off offset:16
	v_pk_mul_f32 v[118:119], v[6:7], v[118:119]
	v_pk_mul_f32 v[116:117], v[4:5], v[116:117]
	v_pk_mul_f32 v[8:9], v[76:77], v[80:81] op_sel_hi:[1,0]
	v_pk_mul_f32 v[10:11], v[64:65], v[80:81] op_sel_hi:[1,0]
	v_pk_mul_f32 v[102:103], v[6:7], v[102:103]
	v_pk_mul_f32 v[100:101], v[4:5], v[100:101]
	v_pk_mul_f32 v[54:55], v[6:7], v[54:55]
	v_pk_mul_f32 v[52:53], v[4:5], v[52:53]
	v_pk_mul_f32 v[38:39], v[6:7], v[38:39]
	v_pk_mul_f32 v[36:37], v[4:5], v[36:37]
	v_pk_mul_f32 v[22:23], v[6:7], v[22:23]
	v_pk_mul_f32 v[20:21], v[4:5], v[20:21]
	v_pk_mul_f32 v[6:7], v[6:7], v[10:11]
	v_pk_mul_f32 v[4:5], v[4:5], v[8:9]
	global_store_dwordx4 v[174:175], v[116:119], off offset:512
	global_store_dwordx4 v[112:113], v[100:103], off offset:512
	global_store_dwordx4 v[90:91], v[52:55], off offset:512
	global_store_dwordx4 v[48:49], v[36:39], off offset:512
	global_store_dwordx4 v[32:33], v[20:23], off offset:512
	global_store_dwordx4 v[16:17], v[4:7], off offset:512
	s_nop 1
	v_pk_mul_f32 v[4:5], v[78:79], v[80:81] op_sel_hi:[1,0]
	v_pk_mul_f32 v[6:7], v[66:67], v[80:81] op_sel_hi:[1,0]
	v_pk_mul_f32 v[0:1], v[0:1], v[4:5]
	v_pk_mul_f32 v[2:3], v[2:3], v[6:7]
	global_store_dwordx4 v[16:17], v[0:3], off offset:528
	s_cbranch_vccnz .LBB0_1165
	s_andn2_b64 vcc, exec, s[12:13]
	s_cbranch_vccnz .LBB0_1164
	s_barrier
	s_branch .LBB0_1164

; __global__ void __launch_bounds__(512, 2) mk_fwd(Args a) {
	.amdhsa_kernel _Z6mk_fwd4Args
		.amdhsa_group_segment_fixed_size 0
		.amdhsa_private_segment_fixed_size 0
		.amdhsa_kernarg_size 408
		.amdhsa_user_sgpr_count 2
		.amdhsa_user_sgpr_dispatch_ptr 0
		.amdhsa_user_sgpr_queue_ptr 0
		.amdhsa_user_sgpr_kernarg_segment_ptr 1
		.amdhsa_user_sgpr_dispatch_id 0
		.amdhsa_user_sgpr_kernarg_preload_length 0
		.amdhsa_user_sgpr_kernarg_preload_offset 0
		.amdhsa_user_sgpr_private_segment_size 0
		.amdhsa_uses_dynamic_stack 0
		.amdhsa_enable_private_segment 0
		.amdhsa_system_sgpr_workgroup_id_x 1
		.amdhsa_system_sgpr_workgroup_id_y 0
		.amdhsa_system_sgpr_workgroup_id_z 0
		.amdhsa_system_sgpr_workgroup_info 0
		.amdhsa_system_vgpr_workitem_id 2
		.amdhsa_next_free_vgpr 240
		.amdhsa_next_free_sgpr 102
		.amdhsa_accum_offset 240
		.amdhsa_reserve_vcc 1
		.amdhsa_float_round_mode_32 0
		.amdhsa_float_round_mode_16_64 0
		.amdhsa_float_denorm_mode_32 3
		.amdhsa_float_denorm_mode_16_64 3
		.amdhsa_dx10_clamp 1
		.amdhsa_ieee_mode 1
		.amdhsa_fp16_overflow 0
		.amdhsa_tg_split 0
		.amdhsa_exception_fp_ieee_invalid_op 0
		.amdhsa_exception_fp_denorm_src 0
		.amdhsa_exception_fp_ieee_div_zero 0
		.amdhsa_exception_fp_ieee_overflow 0
		.amdhsa_exception_fp_ieee_underflow 0
		.amdhsa_exception_fp_ieee_inexact 0
		.amdhsa_exception_int_div_zero 0
	.end_amdhsa_kernel

; __global__ void __launch_bounds__(512, 2) mk_fwd(Args a) {
amdhsa.kernels:
  - .agpr_count:     0
    .args:
      - .offset:         0
        .size:           152
        .value_kind:     by_value
      - .offset:         152
        .size:           4
        .value_kind:     hidden_block_count_x
      - .offset:         156
        .size:           4
        .value_kind:     hidden_block_count_y
      - .offset:         160
        .size:           4
        .value_kind:     hidden_block_count_z
      - .offset:         164
        .size:           2
        .value_kind:     hidden_group_size_x
      - .offset:         166
        .size:           2
        .value_kind:     hidden_group_size_y
      - .offset:         168
        .size:           2
        .value_kind:     hidden_group_size_z
      - .offset:         170
        .size:           2
        .value_kind:     hidden_remainder_x
      - .offset:         172
        .size:           2
        .value_kind:     hidden_remainder_y
      - .offset:         174
        .size:           2
        .value_kind:     hidden_remainder_z
      - .offset:         192
        .size:           8
        .value_kind:     hidden_global_offset_x
      - .offset:         200
        .size:           8
        .value_kind:     hidden_global_offset_y
      - .offset:         208
        .size:           8
        .value_kind:     hidden_global_offset_z
      - .offset:         216
        .size:           2
        .value_kind:     hidden_grid_dims
      - .offset:         240
        .size:           8
        .value_kind:     hidden_multigrid_sync_arg
      - .offset:         272
        .size:           4
        .value_kind:     hidden_dynamic_lds_size
    .group_segment_fixed_size: 0
    .kernarg_segment_align: 8
    .kernarg_segment_size: 408
    .language:       OpenCL C
    .language_version:
      - 2
      - 0
    .max_flat_workgroup_size: 512
    .name:           _Z6mk_fwd4Args
    .private_segment_fixed_size: 0
    .sgpr_count:     108
    .sgpr_spill_count: 94
    .symbol:         _Z6mk_fwd4Args.kd
    .uniform_work_group_size: 1
    .uses_dynamic_stack: false
    .vgpr_count:     240
    .vgpr_spill_count: 0
    .wavefront_size: 64
